# speedup vs baseline: 1.0037x; 1.0037x over previous
; #define PG8_STAGE(bufoff, gbase, voff) do { _Pragma("unroll") for (int _i = 0; _i < 2; ++_i) \
;         __builtin_amdgcn_global_load_lds((const unsigned*)((const char*)(gbase) + (voff)[_i]), (PG8_LAS unsigned*)(lds + (bufoff) + ldsw + _i * 8192), 16, 0, 0); } while (0)
; #define PG8_LDA(dst, b, h) do { _Pragma("unroll") for (int m = 0; m < 4; ++m) _Pragma("unroll") for (int k = 0; k < 2; ++k) dst[m][k] = *(const PG8_LAS bf16x8*)(lds + PG8_SA(b, h) + aoff + m * 2048 + k * 1024); } while (0)
; #define PG8_LDB(dst, b, h) do { _Pragma("unroll") for (int n = 0; n < 2; ++n) _Pragma("unroll") for (int k = 0; k < 2; ++k) dst[n][k] = *(const PG8_LAS bf16x8*)(lds + PG8_SB(b, h) + boff + n * 2048 + k * 1024); } while (0)
; #define PG8_MMA(ai, bj, At, Bt) do { __builtin_amdgcn_s_setprio(3); _Pragma("unroll") for (int m = 0; m < 4; ++m) _Pragma("unroll") for (int n = 0; n < 2; ++n) _Pragma("unroll") for (int k = 0; k < 2; ++k) \
;         acc[ai][bj][m][n] = __builtin_amdgcn_mfma_f32_16x16x32_bf16(Bt[n][k], At[m][k], acc[ai][bj][m][n], 0, 0, 0); __builtin_amdgcn_s_setprio(0); } while (0)
; #define PG8_WAIT_V(n) asm volatile("s_waitcnt vmcnt(" #n ")" ::: "memory")
; #define PG8_BAR __builtin_amdgcn_s_barrier()
; template <class Epi, class Sched, bool ALIGN_EPI = false, bool SP2 = false>
; __device__ __forceinline__ void gemm_phase(PG8_LAS unsigned char* lds, const Gemm g, const Sched& S, const Epi& E) {
;     ...
;         for (int t = 0; t < nt; t += 2) {
;             const bool last = (t == nt - 2);
;             const char* a1 = cA + (size_t)(t + 1) * kstep;
;             const char* a2 = last ? nA : cA + (size_t)(t + 2) * kstep; const char* b2 = last ? nB : cB + (size_t)(t + 2) * kstep;
;             const char* a3 = a2 + kstep; const char* b3 = b2 + kstep;
;             if (last && has_next) S.a_ready(nxt);
;             if constexpr (SP2) {
;             PG8_LDB(B0, 0, 0); PG8_LDB(B1, 0, 1); PG8_SCHED; PG8_LDA(At, 0, 0); PG8_STAGE(PG8_SA(1, 1), a1 + hstep, voffA);
;             PG8_WAIT_V(8); PG8_WAIT_L(0); PG8_BAR; PG8_MMA(0, 0, At, B0); PG8_MMA(0, 1, At, B1); PG8_BAR; PG8_SCHED;
;             PG8_LDA(At, 0, 1); PG8_STAGE(PG8_SB(0, 0), b2, voffB); PG8_STAGE(PG8_SB(0, 1), b2 + hstep, voffB); PG8_STAGE(PG8_SA(0, 0), a2, voffA);
;             PG8_WAIT_V(8); PG8_WAIT_L(0); PG8_BAR; PG8_MMA(1, 0, At, B0); PG8_MMA(1, 1, At, B1); PG8_BAR; PG8_SCHED;
.LBB0_70:
	ds_read_b128 v[148:151], v153
	ds_read_b128 v[156:159], v153 offset:1024
	ds_read_b128 v[160:163], v153 offset:2048
	ds_read_b128 v[168:171], v153 offset:3072
	ds_read_b128 v[172:175], v154
	ds_read_b128 v[176:179], v154 offset:1024
	ds_read_b128 v[180:183], v154 offset:2048
	ds_read_b128 v[184:187], v154 offset:3072
	s_add_u32 s50, s48, 0xfff80080
	s_addc_u32 s51, s49, -1
	s_cmp_eq_u32 s70, 28
	s_cselect_b32 s53, s29, s51
	s_cselect_b32 s52, s65, s50
	s_cselect_b32 s51, s27, s69
	s_cselect_b32 s50, s67, s68
	v_lshl_add_u64 v[164:165], s[48:49], 0, v[138:139]
	s_add_i32 m0, s43, 0xc000
	ds_read_b128 v[188:191], v155
	ds_read_b128 v[192:195], v155 offset:1024
	ds_read_b128 v[196:199], v155 offset:2048
	ds_read_b128 v[200:203], v155 offset:3072
	ds_read_b128 v[204:207], v155 offset:4096
	ds_read_b128 v[208:211], v155 offset:5120
	ds_read_b128 v[212:215], v155 offset:6144
	ds_read_b128 v[216:219], v155 offset:7168
	global_load_lds_dwordx4 v[164:165], off
	v_lshl_add_u64 v[164:165], s[48:49], 0, v[142:143]
	s_add_i32 m0, s43, 0xe000
	s_nop 0
	global_load_lds_dwordx4 v[164:165], off
	s_waitcnt vmcnt(8)
	s_waitcnt lgkmcnt(0)
	s_barrier
	s_waitcnt lgkmcnt(0)
	v_mfma_f32_16x16x32_bf16 v[126:129], v[148:151], v[188:191], v[126:129]
	v_mfma_f32_16x16x32_bf16 v[118:121], v[160:163], v[188:191], v[118:121]
	s_setprio 3
	v_mfma_f32_16x16x32_bf16 v[110:113], v[148:151], v[196:199], v[110:113]
	v_mfma_f32_16x16x32_bf16 v[102:105], v[160:163], v[196:199], v[102:105]
	v_mfma_f32_16x16x32_bf16 v[94:97], v[148:151], v[204:207], v[94:97]
	v_mfma_f32_16x16x32_bf16 v[86:89], v[160:163], v[204:207], v[86:89]
	v_mfma_f32_16x16x32_bf16 v[78:81], v[148:151], v[212:215], v[78:81]
	v_mfma_f32_16x16x32_bf16 v[70:73], v[160:163], v[212:215], v[70:73]
	v_mfma_f32_16x16x32_bf16 v[126:129], v[156:159], v[192:195], v[126:129]
	v_mfma_f32_16x16x32_bf16 v[118:121], v[168:171], v[192:195], v[118:121]
	v_mfma_f32_16x16x32_bf16 v[110:113], v[156:159], v[200:203], v[110:113]
	v_mfma_f32_16x16x32_bf16 v[102:105], v[168:171], v[200:203], v[102:105]
	v_mfma_f32_16x16x32_bf16 v[94:97], v[156:159], v[208:211], v[94:97]
	v_mfma_f32_16x16x32_bf16 v[86:89], v[168:171], v[208:211], v[86:89]
	v_mfma_f32_16x16x32_bf16 v[78:81], v[156:159], v[216:219], v[78:81]
	v_mfma_f32_16x16x32_bf16 v[70:73], v[168:171], v[216:219], v[70:73]
	s_setprio 0
	s_setprio 3
	v_mfma_f32_16x16x32_bf16 v[122:125], v[172:175], v[188:191], v[122:125]
	v_mfma_f32_16x16x32_bf16 v[114:117], v[180:183], v[188:191], v[114:117]
	v_mfma_f32_16x16x32_bf16 v[106:109], v[172:175], v[196:199], v[106:109]
	v_mfma_f32_16x16x32_bf16 v[98:101], v[180:183], v[196:199], v[98:101]
	v_mfma_f32_16x16x32_bf16 v[90:93], v[172:175], v[204:207], v[90:93]
	v_mfma_f32_16x16x32_bf16 v[82:85], v[180:183], v[204:207], v[82:85]
	v_mfma_f32_16x16x32_bf16 v[74:77], v[172:175], v[212:215], v[74:77]
	v_mfma_f32_16x16x32_bf16 v[66:69], v[180:183], v[212:215], v[66:69]
	v_mfma_f32_16x16x32_bf16 v[122:125], v[176:179], v[192:195], v[122:125]
	v_mfma_f32_16x16x32_bf16 v[114:117], v[184:187], v[192:195], v[114:117]
	v_mfma_f32_16x16x32_bf16 v[106:109], v[176:179], v[200:203], v[106:109]
	v_mfma_f32_16x16x32_bf16 v[98:101], v[184:187], v[200:203], v[98:101]
	v_mfma_f32_16x16x32_bf16 v[90:93], v[176:179], v[208:211], v[90:93]
	v_mfma_f32_16x16x32_bf16 v[82:85], v[184:187], v[208:211], v[82:85]
	s_barrier
	v_mfma_f32_16x16x32_bf16 v[74:77], v[176:179], v[216:219], v[74:77]
	v_mfma_f32_16x16x32_bf16 v[66:69], v[184:187], v[216:219], v[66:69]
	s_setprio 0
	s_add_i32 s71, s61, s37
	v_lshl_add_u64 v[164:165], s[50:51], 0, v[132:133]
	s_mov_b32 m0, s71
	ds_read_b128 v[188:191], v155 offset:16384
	ds_read_b128 v[192:195], v155 offset:17408
	ds_read_b128 v[196:199], v155 offset:18432
	ds_read_b128 v[200:203], v155 offset:19456
	ds_read_b128 v[204:207], v155 offset:20480
	ds_read_b128 v[208:211], v155 offset:21504
	ds_read_b128 v[212:215], v155 offset:22528
	ds_read_b128 v[216:219], v155 offset:23552
	global_load_lds_dwordx4 v[164:165], off
	s_add_i32 m0, s71, 0x2000
	s_add_u32 s72, s50, 0x80000
	v_lshl_add_u64 v[220:221], s[50:51], 0, v[136:137]
	s_addc_u32 s73, s51, 0
	s_add_i32 s71, s62, s37
	global_load_lds_dwordx4 v[220:221], off
	v_lshl_add_u64 v[222:223], s[72:73], 0, v[132:133]
	s_mov_b32 m0, s71
	v_lshl_add_u64 v[224:225], s[52:53], 0, v[134:135]
	global_load_lds_dwordx4 v[222:223], off
	v_lshl_add_u64 v[222:223], s[72:73], 0, v[136:137]
	s_add_i32 m0, s71, 0x2000
	s_nop 0
	global_load_lds_dwordx4 v[222:223], off
	v_lshl_add_u64 v[222:223], s[52:53], 0, v[130:131]
	s_mov_b32 m0, s43
	s_nop 0
	global_load_lds_dwordx4 v[222:223], off
	s_mov_b32 m0, s47
	s_nop 0
	global_load_lds_dwordx4 v[224:225], off
	s_waitcnt vmcnt(8)
	s_waitcnt lgkmcnt(0)
	s_barrier
; #define PG8_STAGE(bufoff, gbase, voff) do { _Pragma("unroll") for (int _i = 0; _i < 2; ++_i) \
;         __builtin_amdgcn_global_load_lds((const unsigned*)((const char*)(gbase) + (voff)[_i]), (PG8_LAS unsigned*)(lds + (bufoff) + ldsw + _i * 8192), 16, 0, 0); } while (0)
; #define PG8_LDA(dst, b, h) do { _Pragma("unroll") for (int m = 0; m < 4; ++m) _Pragma("unroll") for (int k = 0; k < 2; ++k) dst[m][k] = *(const PG8_LAS bf16x8*)(lds + PG8_SA(b, h) + aoff + m * 2048 + k * 1024); } while (0)
; #define PG8_LDB(dst, b, h) do { _Pragma("unroll") for (int n = 0; n < 2; ++n) _Pragma("unroll") for (int k = 0; k < 2; ++k) dst[n][k] = *(const PG8_LAS bf16x8*)(lds + PG8_SB(b, h) + boff + n * 2048 + k * 1024); } while (0)
; #define PG8_MMA(ai, bj, At, Bt) do { __builtin_amdgcn_s_setprio(3); _Pragma("unroll") for (int m = 0; m < 4; ++m) _Pragma("unroll") for (int n = 0; n < 2; ++n) _Pragma("unroll") for (int k = 0; k < 2; ++k) \
;         acc[ai][bj][m][n] = __builtin_amdgcn_mfma_f32_16x16x32_bf16(Bt[n][k], At[m][k], acc[ai][bj][m][n], 0, 0, 0); __builtin_amdgcn_s_setprio(0); } while (0)
; #define PG8_WAIT_V(n) asm volatile("s_waitcnt vmcnt(" #n ")" ::: "memory")
; #define PG8_WAIT_L(n) asm volatile("s_waitcnt lgkmcnt(" #n ")" ::: "memory")
; #define PG8_BAR __builtin_amdgcn_s_barrier()
; #define PG8_SCHED __builtin_amdgcn_sched_barrier(0)
; template <class Epi, class Sched, bool ALIGN_EPI = false, bool SP2 = false>
; __device__ __forceinline__ void gemm_phase(PG8_LAS unsigned char* lds, const Gemm g, const Sched& S, const Epi& E) {
;     ...
;             PG8_WAIT_V(8); PG8_WAIT_L(0); PG8_BAR; PG8_MMA(1, 0, At, B0); PG8_MMA(1, 1, At, B1); PG8_BAR; PG8_SCHED;
;             PG8_LDB(B0, 1, 0); PG8_LDB(B1, 1, 1); PG8_SCHED; PG8_LDA(At, 1, 0); PG8_STAGE(PG8_SA(0, 1), a2 + hstep, voffA);
;             PG8_WAIT_V(8); PG8_WAIT_L(0); PG8_BAR; PG8_MMA(0, 0, At, B0); PG8_MMA(0, 1, At, B1); PG8_BAR; PG8_SCHED;
	s_waitcnt lgkmcnt(0)
	v_mfma_f32_16x16x32_bf16 v[62:65], v[148:151], v[188:191], v[62:65]
	v_mfma_f32_16x16x32_bf16 v[54:57], v[160:163], v[188:191], v[54:57]
	s_setprio 3
	v_mfma_f32_16x16x32_bf16 v[46:49], v[148:151], v[196:199], v[46:49]
	v_mfma_f32_16x16x32_bf16 v[38:41], v[160:163], v[196:199], v[38:41]
	v_mfma_f32_16x16x32_bf16 v[30:33], v[148:151], v[204:207], v[30:33]
	v_mfma_f32_16x16x32_bf16 v[22:25], v[160:163], v[204:207], v[22:25]
	v_mfma_f32_16x16x32_bf16 v[14:17], v[148:151], v[212:215], v[14:17]
	v_mfma_f32_16x16x32_bf16 v[6:9], v[160:163], v[212:215], v[6:9]
	v_mfma_f32_16x16x32_bf16 v[62:65], v[156:159], v[192:195], v[62:65]
	v_mfma_f32_16x16x32_bf16 v[54:57], v[168:171], v[192:195], v[54:57]
	v_mfma_f32_16x16x32_bf16 v[46:49], v[156:159], v[200:203], v[46:49]
	v_mfma_f32_16x16x32_bf16 v[38:41], v[168:171], v[200:203], v[38:41]
	v_mfma_f32_16x16x32_bf16 v[30:33], v[156:159], v[208:211], v[30:33]
	v_mfma_f32_16x16x32_bf16 v[22:25], v[168:171], v[208:211], v[22:25]
	v_mfma_f32_16x16x32_bf16 v[14:17], v[156:159], v[216:219], v[14:17]
	v_mfma_f32_16x16x32_bf16 v[6:9], v[168:171], v[216:219], v[6:9]
	s_setprio 0
	s_setprio 3
	v_mfma_f32_16x16x32_bf16 v[58:61], v[172:175], v[188:191], v[58:61]
	v_mfma_f32_16x16x32_bf16 v[50:53], v[180:183], v[188:191], v[50:53]
	v_mfma_f32_16x16x32_bf16 v[42:45], v[172:175], v[196:199], v[42:45]
	v_mfma_f32_16x16x32_bf16 v[34:37], v[180:183], v[196:199], v[34:37]
	v_mfma_f32_16x16x32_bf16 v[26:29], v[172:175], v[204:207], v[26:29]
	v_mfma_f32_16x16x32_bf16 v[18:21], v[180:183], v[204:207], v[18:21]
	v_mfma_f32_16x16x32_bf16 v[10:13], v[172:175], v[212:215], v[10:13]
	v_mfma_f32_16x16x32_bf16 v[2:5], v[180:183], v[212:215], v[2:5]
	v_mfma_f32_16x16x32_bf16 v[58:61], v[176:179], v[192:195], v[58:61]
	v_mfma_f32_16x16x32_bf16 v[50:53], v[184:187], v[192:195], v[50:53]
	v_mfma_f32_16x16x32_bf16 v[42:45], v[176:179], v[200:203], v[42:45]
	v_mfma_f32_16x16x32_bf16 v[34:37], v[184:187], v[200:203], v[34:37]
	v_mfma_f32_16x16x32_bf16 v[26:29], v[176:179], v[208:211], v[26:29]
	v_mfma_f32_16x16x32_bf16 v[18:21], v[184:187], v[208:211], v[18:21]
	s_barrier
	v_mfma_f32_16x16x32_bf16 v[10:13], v[176:179], v[216:219], v[10:13]
	v_mfma_f32_16x16x32_bf16 v[2:5], v[184:187], v[216:219], v[2:5]
	s_setprio 0
	s_add_i32 s71, 0, 0x18000
	v_add_u32_e32 v167, s71, v141
	s_add_i32 s72, 0, 0x1c000
	ds_read_b128 v[148:151], v167
	ds_read_b128 v[156:159], v167 offset:1024
	ds_read_b128 v[160:163], v167 offset:2048
	ds_read_b128 v[168:171], v167 offset:3072
	v_add_u32_e32 v167, s72, v141
	ds_read_b128 v[172:175], v167
	ds_read_b128 v[176:179], v167 offset:1024
	ds_read_b128 v[180:183], v167 offset:2048
	ds_read_b128 v[184:187], v167 offset:3072
	s_add_u32 s52, s52, 0x80000
	s_addc_u32 s53, s53, 0
	s_mov_b32 m0, s54
	v_lshl_add_u64 v[226:227], s[52:53], 0, v[130:131]
	ds_read_b128 v[188:191], v155 offset:32768
	ds_read_b128 v[192:195], v155 offset:33792
	ds_read_b128 v[196:199], v155 offset:34816
	ds_read_b128 v[200:203], v155 offset:35840
	ds_read_b128 v[204:207], v155 offset:36864
	ds_read_b128 v[208:211], v155 offset:37888
	ds_read_b128 v[212:215], v155 offset:38912
	ds_read_b128 v[216:219], v155 offset:39936
	global_load_lds_dwordx4 v[226:227], off
	v_lshl_add_u64 v[226:227], s[52:53], 0, v[134:135]
	s_mov_b32 m0, s55
	s_nop 0
	global_load_lds_dwordx4 v[226:227], off
	s_waitcnt vmcnt(8)
	s_waitcnt lgkmcnt(0)
	s_barrier
	s_waitcnt lgkmcnt(0)
	v_mfma_f32_16x16x32_bf16 v[126:129], v[148:151], v[188:191], v[126:129]
	v_mfma_f32_16x16x32_bf16 v[118:121], v[160:163], v[188:191], v[118:121]
	s_setprio 3
	v_mfma_f32_16x16x32_bf16 v[110:113], v[148:151], v[196:199], v[110:113]
	v_mfma_f32_16x16x32_bf16 v[102:105], v[160:163], v[196:199], v[102:105]
	v_mfma_f32_16x16x32_bf16 v[94:97], v[148:151], v[204:207], v[94:97]
	v_mfma_f32_16x16x32_bf16 v[86:89], v[160:163], v[204:207], v[86:89]
	v_mfma_f32_16x16x32_bf16 v[78:81], v[148:151], v[212:215], v[78:81]
	v_mfma_f32_16x16x32_bf16 v[70:73], v[160:163], v[212:215], v[70:73]
	v_mfma_f32_16x16x32_bf16 v[126:129], v[156:159], v[192:195], v[126:129]
	v_mfma_f32_16x16x32_bf16 v[118:121], v[168:171], v[192:195], v[118:121]
	v_mfma_f32_16x16x32_bf16 v[110:113], v[156:159], v[200:203], v[110:113]
	v_mfma_f32_16x16x32_bf16 v[102:105], v[168:171], v[200:203], v[102:105]
	v_mfma_f32_16x16x32_bf16 v[94:97], v[156:159], v[208:211], v[94:97]
	v_mfma_f32_16x16x32_bf16 v[86:89], v[168:171], v[208:211], v[86:89]
	v_mfma_f32_16x16x32_bf16 v[78:81], v[156:159], v[216:219], v[78:81]
	v_mfma_f32_16x16x32_bf16 v[70:73], v[168:171], v[216:219], v[70:73]
	s_setprio 0
	s_setprio 3
	v_mfma_f32_16x16x32_bf16 v[122:125], v[172:175], v[188:191], v[122:125]
	v_mfma_f32_16x16x32_bf16 v[114:117], v[180:183], v[188:191], v[114:117]
	v_mfma_f32_16x16x32_bf16 v[106:109], v[172:175], v[196:199], v[106:109]
	v_mfma_f32_16x16x32_bf16 v[98:101], v[180:183], v[196:199], v[98:101]
	v_mfma_f32_16x16x32_bf16 v[90:93], v[172:175], v[204:207], v[90:93]
	v_mfma_f32_16x16x32_bf16 v[82:85], v[180:183], v[204:207], v[82:85]
	v_mfma_f32_16x16x32_bf16 v[74:77], v[172:175], v[212:215], v[74:77]
	v_mfma_f32_16x16x32_bf16 v[66:69], v[180:183], v[212:215], v[66:69]
	v_mfma_f32_16x16x32_bf16 v[122:125], v[176:179], v[192:195], v[122:125]
	v_mfma_f32_16x16x32_bf16 v[114:117], v[184:187], v[192:195], v[114:117]
	v_mfma_f32_16x16x32_bf16 v[106:109], v[176:179], v[200:203], v[106:109]
	v_mfma_f32_16x16x32_bf16 v[98:101], v[184:187], v[200:203], v[98:101]
	v_mfma_f32_16x16x32_bf16 v[90:93], v[176:179], v[208:211], v[90:93]
	v_mfma_f32_16x16x32_bf16 v[82:85], v[184:187], v[208:211], v[82:85]
	s_barrier
; #define PG8_STAGE(bufoff, gbase, voff) do { _Pragma("unroll") for (int _i = 0; _i < 2; ++_i) \
;         __builtin_amdgcn_global_load_lds((const unsigned*)((const char*)(gbase) + (voff)[_i]), (PG8_LAS unsigned*)(lds + (bufoff) + ldsw + _i * 8192), 16, 0, 0); } while (0)
; #define PG8_LDA(dst, b, h) do { _Pragma("unroll") for (int m = 0; m < 4; ++m) _Pragma("unroll") for (int k = 0; k < 2; ++k) dst[m][k] = *(const PG8_LAS bf16x8*)(lds + PG8_SA(b, h) + aoff + m * 2048 + k * 1024); } while (0)
; #define PG8_MMA(ai, bj, At, Bt) do { __builtin_amdgcn_s_setprio(3); _Pragma("unroll") for (int m = 0; m < 4; ++m) _Pragma("unroll") for (int n = 0; n < 2; ++n) _Pragma("unroll") for (int k = 0; k < 2; ++k) \
;         acc[ai][bj][m][n] = __builtin_amdgcn_mfma_f32_16x16x32_bf16(Bt[n][k], At[m][k], acc[ai][bj][m][n], 0, 0, 0); __builtin_amdgcn_s_setprio(0); } while (0)
; #define PG8_WAIT_V(n) asm volatile("s_waitcnt vmcnt(" #n ")" ::: "memory")
; #define PG8_WAIT_L(n) asm volatile("s_waitcnt lgkmcnt(" #n ")" ::: "memory")
; #define PG8_BAR __builtin_amdgcn_s_barrier()
; #define PG8_SCHED __builtin_amdgcn_sched_barrier(0)
; template <class Epi, class Sched, bool ALIGN_EPI = false, bool SP2 = false>
; __device__ __forceinline__ void gemm_phase(PG8_LAS unsigned char* lds, const Gemm g, const Sched& S, const Epi& E) {
;     ...
;             PG8_LDA(At, 1, 1); PG8_STAGE(PG8_SB(1, 0), b3, voffB); PG8_STAGE(PG8_SB(1, 1), b3 + hstep, voffB); PG8_STAGE(PG8_SA(1, 0), a3, voffA);
;             PG8_WAIT_V(8); PG8_WAIT_L(0); PG8_BAR; PG8_MMA(1, 0, At, B0); PG8_MMA(1, 1, At, B1); PG8_BAR; PG8_SCHED;
;     ...
;         }
;         if constexpr (ALIGN_EPI) { if (wr == 0) PG8_BAR; }
	v_mfma_f32_16x16x32_bf16 v[74:77], v[176:179], v[216:219], v[74:77]
	v_mfma_f32_16x16x32_bf16 v[66:69], v[184:187], v[216:219], v[66:69]
	s_setprio 0
	s_add_i32 s52, s71, s37
	v_lshl_add_u64 v[164:165], v[164:165], 0, s[18:19]
	s_mov_b32 m0, s52
	ds_read_b128 v[188:191], v155 offset:49152
	ds_read_b128 v[192:195], v155 offset:50176
	ds_read_b128 v[196:199], v155 offset:51200
	ds_read_b128 v[200:203], v155 offset:52224
	ds_read_b128 v[204:207], v155 offset:53248
	ds_read_b128 v[208:211], v155 offset:54272
	ds_read_b128 v[212:215], v155 offset:55296
	ds_read_b128 v[216:219], v155 offset:56320
	global_load_lds_dwordx4 v[164:165], off
	s_add_i32 m0, s52, 0x2000
	s_add_u32 s50, s50, 0x80080
	v_lshl_add_u64 v[164:165], v[220:221], 0, s[18:19]
	s_addc_u32 s51, s51, 0
	s_add_i32 s52, s72, s37
	global_load_lds_dwordx4 v[164:165], off
	v_lshl_add_u64 v[164:165], s[50:51], 0, v[132:133]
	s_mov_b32 m0, s52
	s_nop 0
	global_load_lds_dwordx4 v[164:165], off
	v_lshl_add_u64 v[164:165], s[50:51], 0, v[136:137]
	s_add_i32 m0, s52, 0x2000
	s_nop 0
	global_load_lds_dwordx4 v[164:165], off
	v_lshl_add_u64 v[164:165], v[222:223], 0, s[18:19]
	s_mov_b32 m0, s58
	s_nop 0
	global_load_lds_dwordx4 v[164:165], off
	v_lshl_add_u64 v[164:165], v[224:225], 0, s[18:19]
	s_mov_b32 m0, s59
	s_nop 0
	global_load_lds_dwordx4 v[164:165], off
	s_waitcnt vmcnt(8)
	s_waitcnt lgkmcnt(0)
	s_barrier
	s_waitcnt lgkmcnt(0)
	v_mfma_f32_16x16x32_bf16 v[62:65], v[148:151], v[188:191], v[62:65]
	v_mfma_f32_16x16x32_bf16 v[54:57], v[160:163], v[188:191], v[54:57]
	s_setprio 3
	v_mfma_f32_16x16x32_bf16 v[46:49], v[148:151], v[196:199], v[46:49]
	v_mfma_f32_16x16x32_bf16 v[38:41], v[160:163], v[196:199], v[38:41]
	v_mfma_f32_16x16x32_bf16 v[30:33], v[148:151], v[204:207], v[30:33]
	v_mfma_f32_16x16x32_bf16 v[22:25], v[160:163], v[204:207], v[22:25]
	v_mfma_f32_16x16x32_bf16 v[14:17], v[148:151], v[212:215], v[14:17]
	v_mfma_f32_16x16x32_bf16 v[6:9], v[160:163], v[212:215], v[6:9]
	v_mfma_f32_16x16x32_bf16 v[62:65], v[156:159], v[192:195], v[62:65]
	v_mfma_f32_16x16x32_bf16 v[54:57], v[168:171], v[192:195], v[54:57]
	v_mfma_f32_16x16x32_bf16 v[46:49], v[156:159], v[200:203], v[46:49]
	v_mfma_f32_16x16x32_bf16 v[38:41], v[168:171], v[200:203], v[38:41]
	v_mfma_f32_16x16x32_bf16 v[30:33], v[156:159], v[208:211], v[30:33]
	v_mfma_f32_16x16x32_bf16 v[22:25], v[168:171], v[208:211], v[22:25]
	v_mfma_f32_16x16x32_bf16 v[14:17], v[156:159], v[216:219], v[14:17]
	v_mfma_f32_16x16x32_bf16 v[6:9], v[168:171], v[216:219], v[6:9]
	s_setprio 0
	s_setprio 3
	v_mfma_f32_16x16x32_bf16 v[58:61], v[172:175], v[188:191], v[58:61]
	v_mfma_f32_16x16x32_bf16 v[50:53], v[180:183], v[188:191], v[50:53]
	v_mfma_f32_16x16x32_bf16 v[42:45], v[172:175], v[196:199], v[42:45]
	v_mfma_f32_16x16x32_bf16 v[34:37], v[180:183], v[196:199], v[34:37]
	v_mfma_f32_16x16x32_bf16 v[26:29], v[172:175], v[204:207], v[26:29]
	v_mfma_f32_16x16x32_bf16 v[18:21], v[180:183], v[204:207], v[18:21]
	v_mfma_f32_16x16x32_bf16 v[10:13], v[172:175], v[212:215], v[10:13]
	v_mfma_f32_16x16x32_bf16 v[2:5], v[180:183], v[212:215], v[2:5]
	v_mfma_f32_16x16x32_bf16 v[58:61], v[176:179], v[192:195], v[58:61]
	v_mfma_f32_16x16x32_bf16 v[50:53], v[184:187], v[192:195], v[50:53]
	v_mfma_f32_16x16x32_bf16 v[42:45], v[176:179], v[200:203], v[42:45]
	v_mfma_f32_16x16x32_bf16 v[34:37], v[184:187], v[200:203], v[34:37]
	v_mfma_f32_16x16x32_bf16 v[26:29], v[176:179], v[208:211], v[26:29]
	v_mfma_f32_16x16x32_bf16 v[18:21], v[184:187], v[208:211], v[18:21]
	s_barrier
	v_mfma_f32_16x16x32_bf16 v[10:13], v[176:179], v[216:219], v[10:13]
	v_mfma_f32_16x16x32_bf16 v[2:5], v[184:187], v[216:219], v[2:5]
	s_setprio 0
	s_add_i32 s70, s70, 2
	s_add_u32 s48, s48, 0x100
	s_addc_u32 s49, s49, 0
	s_add_u32 s68, s68, 0x100
	s_addc_u32 s69, s69, 0
	s_cmp_gt_u32 s70, 29
	s_cbranch_scc0 .LBB0_70
	s_and_b64 vcc, exec, s[24:25]
	s_cbranch_vccz .LBB0_73
	s_barrier

; #define PG8_STAGE(bufoff, gbase, voff) do { _Pragma("unroll") for (int _i = 0; _i < 2; ++_i) \
;         __builtin_amdgcn_global_load_lds((const unsigned*)((const char*)(gbase) + (voff)[_i]), (PG8_LAS unsigned*)(lds + (bufoff) + ldsw + _i * 8192), 16, 0, 0); } while (0)
; #define PG8_LDA(dst, b, h) do { _Pragma("unroll") for (int m = 0; m < 4; ++m) _Pragma("unroll") for (int k = 0; k < 2; ++k) dst[m][k] = *(const PG8_LAS bf16x8*)(lds + PG8_SA(b, h) + aoff + m * 2048 + k * 1024); } while (0)
; #define PG8_LDB(dst, b, h) do { _Pragma("unroll") for (int n = 0; n < 2; ++n) _Pragma("unroll") for (int k = 0; k < 2; ++k) dst[n][k] = *(const PG8_LAS bf16x8*)(lds + PG8_SB(b, h) + boff + n * 2048 + k * 1024); } while (0)
; #define PG8_MMA(ai, bj, At, Bt) do { __builtin_amdgcn_s_setprio(3); _Pragma("unroll") for (int m = 0; m < 4; ++m) _Pragma("unroll") for (int n = 0; n < 2; ++n) _Pragma("unroll") for (int k = 0; k < 2; ++k) \
;         acc[ai][bj][m][n] = __builtin_amdgcn_mfma_f32_16x16x32_bf16(Bt[n][k], At[m][k], acc[ai][bj][m][n], 0, 0, 0); __builtin_amdgcn_s_setprio(0); } while (0)
; #define PG8_WAIT_V(n) asm volatile("s_waitcnt vmcnt(" #n ")" ::: "memory")
; #define PG8_BAR __builtin_amdgcn_s_barrier()
; template <class Epi, class Sched, bool ALIGN_EPI = false, bool SP2 = false>
; __device__ __forceinline__ void gemm_phase(PG8_LAS unsigned char* lds, const Gemm g, const Sched& S, const Epi& E) {
;     ...
;         for (int t = 0; t < nt; t += 2) {
;             const bool last = (t == nt - 2);
;             const char* a1 = cA + (size_t)(t + 1) * kstep;
;             const char* a2 = last ? nA : cA + (size_t)(t + 2) * kstep; const char* b2 = last ? nB : cB + (size_t)(t + 2) * kstep;
;             const char* a3 = a2 + kstep; const char* b3 = b2 + kstep;
;             if (last && has_next) S.a_ready(nxt);
;             if constexpr (SP2) {
;             PG8_LDB(B0, 0, 0); PG8_LDB(B1, 0, 1); PG8_SCHED; PG8_LDA(At, 0, 0); PG8_STAGE(PG8_SA(1, 1), a1 + hstep, voffA);
;             PG8_WAIT_V(8); PG8_WAIT_L(0); PG8_BAR; PG8_MMA(0, 0, At, B0); PG8_MMA(0, 1, At, B1); PG8_BAR; PG8_SCHED;
;             PG8_LDA(At, 0, 1); PG8_STAGE(PG8_SB(0, 0), b2, voffB); PG8_STAGE(PG8_SB(0, 1), b2 + hstep, voffB); PG8_STAGE(PG8_SA(0, 0), a2, voffA);
;             PG8_WAIT_V(8); PG8_WAIT_L(0); PG8_BAR; PG8_MMA(1, 0, At, B0); PG8_MMA(1, 1, At, B1); PG8_BAR; PG8_SCHED;
.LBB0_179:
	ds_read_b128 v[148:151], v157
	ds_read_b128 v[152:155], v157 offset:1024
	ds_read_b128 v[160:163], v157 offset:2048
	ds_read_b128 v[168:171], v157 offset:3072
	ds_read_b128 v[172:175], v158
	ds_read_b128 v[176:179], v158 offset:1024
	ds_read_b128 v[180:183], v158 offset:2048
	ds_read_b128 v[184:187], v158 offset:3072
	s_add_i32 s79, s50, 2
	s_add_u32 s51, s8, 0xffea8080
	s_addc_u32 s52, s9, -1
	s_cmp_eq_u32 s76, s50
	s_cselect_b32 s50, s48, s77
	s_cselect_b32 s53, s47, s52
	s_cselect_b32 s52, s46, s51
	s_cselect_b32 s51, s49, s78
	v_lshl_add_u64 v[164:165], s[8:9], 0, v[138:139]
	s_add_i32 m0, s54, 0xc000
	ds_read_b128 v[188:191], v159
	ds_read_b128 v[192:195], v159 offset:1024
	ds_read_b128 v[196:199], v159 offset:2048
	ds_read_b128 v[200:203], v159 offset:3072
	ds_read_b128 v[204:207], v159 offset:4096
	ds_read_b128 v[208:211], v159 offset:5120
	ds_read_b128 v[212:215], v159 offset:6144
	ds_read_b128 v[216:219], v159 offset:7168
	global_load_lds_dwordx4 v[164:165], off
	v_lshl_add_u64 v[164:165], s[8:9], 0, v[142:143]
	s_add_i32 m0, s54, 0xe000
	s_nop 0
	global_load_lds_dwordx4 v[164:165], off
	s_waitcnt vmcnt(8)
	s_waitcnt lgkmcnt(0)
	s_barrier
	s_waitcnt lgkmcnt(0)
	v_mfma_f32_16x16x32_bf16 v[126:129], v[148:151], v[188:191], v[126:129]
	v_mfma_f32_16x16x32_bf16 v[122:125], v[160:163], v[188:191], v[122:125]
	s_setprio 3
	v_mfma_f32_16x16x32_bf16 v[114:117], v[148:151], v[196:199], v[114:117]
	v_mfma_f32_16x16x32_bf16 v[106:109], v[160:163], v[196:199], v[106:109]
	v_mfma_f32_16x16x32_bf16 v[98:101], v[148:151], v[204:207], v[98:101]
	v_mfma_f32_16x16x32_bf16 v[90:93], v[160:163], v[204:207], v[90:93]
	v_mfma_f32_16x16x32_bf16 v[82:85], v[148:151], v[212:215], v[82:85]
	v_mfma_f32_16x16x32_bf16 v[74:77], v[160:163], v[212:215], v[74:77]
	v_mfma_f32_16x16x32_bf16 v[126:129], v[152:155], v[192:195], v[126:129]
	v_mfma_f32_16x16x32_bf16 v[122:125], v[168:171], v[192:195], v[122:125]
	v_mfma_f32_16x16x32_bf16 v[114:117], v[152:155], v[200:203], v[114:117]
	v_mfma_f32_16x16x32_bf16 v[106:109], v[168:171], v[200:203], v[106:109]
	v_mfma_f32_16x16x32_bf16 v[98:101], v[152:155], v[208:211], v[98:101]
	v_mfma_f32_16x16x32_bf16 v[90:93], v[168:171], v[208:211], v[90:93]
	v_mfma_f32_16x16x32_bf16 v[82:85], v[152:155], v[216:219], v[82:85]
	v_mfma_f32_16x16x32_bf16 v[74:77], v[168:171], v[216:219], v[74:77]
	s_setprio 0
	s_setprio 3
	v_mfma_f32_16x16x32_bf16 v[118:121], v[172:175], v[188:191], v[118:121]
	v_mfma_f32_16x16x32_bf16 v[110:113], v[180:183], v[188:191], v[110:113]
	v_mfma_f32_16x16x32_bf16 v[102:105], v[172:175], v[196:199], v[102:105]
	v_mfma_f32_16x16x32_bf16 v[94:97], v[180:183], v[196:199], v[94:97]
	v_mfma_f32_16x16x32_bf16 v[86:89], v[172:175], v[204:207], v[86:89]
	v_mfma_f32_16x16x32_bf16 v[78:81], v[180:183], v[204:207], v[78:81]
	v_mfma_f32_16x16x32_bf16 v[70:73], v[172:175], v[212:215], v[70:73]
	v_mfma_f32_16x16x32_bf16 v[66:69], v[180:183], v[212:215], v[66:69]
	v_mfma_f32_16x16x32_bf16 v[118:121], v[176:179], v[192:195], v[118:121]
	v_mfma_f32_16x16x32_bf16 v[110:113], v[184:187], v[192:195], v[110:113]
	v_mfma_f32_16x16x32_bf16 v[102:105], v[176:179], v[200:203], v[102:105]
	v_mfma_f32_16x16x32_bf16 v[94:97], v[184:187], v[200:203], v[94:97]
	v_mfma_f32_16x16x32_bf16 v[86:89], v[176:179], v[208:211], v[86:89]
	v_mfma_f32_16x16x32_bf16 v[78:81], v[184:187], v[208:211], v[78:81]
	s_barrier
	v_mfma_f32_16x16x32_bf16 v[70:73], v[176:179], v[216:219], v[70:73]
	v_mfma_f32_16x16x32_bf16 v[66:69], v[184:187], v[216:219], v[66:69]
	s_setprio 0
	s_add_i32 s81, s65, s43
	v_lshl_add_u64 v[164:165], s[50:51], 0, v[132:133]
	s_mov_b32 m0, s81
	ds_read_b128 v[188:191], v159 offset:16384
	ds_read_b128 v[192:195], v159 offset:17408
	ds_read_b128 v[196:199], v159 offset:18432
	ds_read_b128 v[200:203], v159 offset:19456
	ds_read_b128 v[204:207], v159 offset:20480
	ds_read_b128 v[208:211], v159 offset:21504
	ds_read_b128 v[212:215], v159 offset:22528
	ds_read_b128 v[216:219], v159 offset:23552
	global_load_lds_dwordx4 v[164:165], off
	s_add_i32 m0, s81, 0x2000
	s_add_u32 s82, s50, 0x158000
	v_lshl_add_u64 v[220:221], s[50:51], 0, v[136:137]
	s_addc_u32 s83, s51, 0
	s_add_i32 s81, s67, s43
	global_load_lds_dwordx4 v[220:221], off
	v_lshl_add_u64 v[222:223], s[82:83], 0, v[132:133]
	s_mov_b32 m0, s81
	v_lshl_add_u64 v[224:225], s[52:53], 0, v[134:135]
	global_load_lds_dwordx4 v[222:223], off
	v_lshl_add_u64 v[222:223], s[82:83], 0, v[136:137]
	s_add_i32 m0, s81, 0x2000
	s_nop 0
	global_load_lds_dwordx4 v[222:223], off
	v_lshl_add_u64 v[222:223], s[52:53], 0, v[130:131]
	s_mov_b32 m0, s54
	s_nop 0
	global_load_lds_dwordx4 v[222:223], off
	s_mov_b32 m0, s55
	s_nop 0
	global_load_lds_dwordx4 v[224:225], off
	s_waitcnt vmcnt(8)
	s_waitcnt lgkmcnt(0)
	s_barrier
; #define PG8_STAGE(bufoff, gbase, voff) do { _Pragma("unroll") for (int _i = 0; _i < 2; ++_i) \
;         __builtin_amdgcn_global_load_lds((const unsigned*)((const char*)(gbase) + (voff)[_i]), (PG8_LAS unsigned*)(lds + (bufoff) + ldsw + _i * 8192), 16, 0, 0); } while (0)
; #define PG8_LDA(dst, b, h) do { _Pragma("unroll") for (int m = 0; m < 4; ++m) _Pragma("unroll") for (int k = 0; k < 2; ++k) dst[m][k] = *(const PG8_LAS bf16x8*)(lds + PG8_SA(b, h) + aoff + m * 2048 + k * 1024); } while (0)
; #define PG8_LDB(dst, b, h) do { _Pragma("unroll") for (int n = 0; n < 2; ++n) _Pragma("unroll") for (int k = 0; k < 2; ++k) dst[n][k] = *(const PG8_LAS bf16x8*)(lds + PG8_SB(b, h) + boff + n * 2048 + k * 1024); } while (0)
; #define PG8_MMA(ai, bj, At, Bt) do { __builtin_amdgcn_s_setprio(3); _Pragma("unroll") for (int m = 0; m < 4; ++m) _Pragma("unroll") for (int n = 0; n < 2; ++n) _Pragma("unroll") for (int k = 0; k < 2; ++k) \
;         acc[ai][bj][m][n] = __builtin_amdgcn_mfma_f32_16x16x32_bf16(Bt[n][k], At[m][k], acc[ai][bj][m][n], 0, 0, 0); __builtin_amdgcn_s_setprio(0); } while (0)
; #define PG8_WAIT_V(n) asm volatile("s_waitcnt vmcnt(" #n ")" ::: "memory")
; #define PG8_WAIT_L(n) asm volatile("s_waitcnt lgkmcnt(" #n ")" ::: "memory")
; #define PG8_BAR __builtin_amdgcn_s_barrier()
; #define PG8_SCHED __builtin_amdgcn_sched_barrier(0)
; template <class Epi, class Sched, bool ALIGN_EPI = false, bool SP2 = false>
; __device__ __forceinline__ void gemm_phase(PG8_LAS unsigned char* lds, const Gemm g, const Sched& S, const Epi& E) {
;     ...
;             PG8_WAIT_V(8); PG8_WAIT_L(0); PG8_BAR; PG8_MMA(1, 0, At, B0); PG8_MMA(1, 1, At, B1); PG8_BAR; PG8_SCHED;
;             PG8_LDB(B0, 1, 0); PG8_LDB(B1, 1, 1); PG8_SCHED; PG8_LDA(At, 1, 0); PG8_STAGE(PG8_SA(0, 1), a2 + hstep, voffA);
;             PG8_WAIT_V(8); PG8_WAIT_L(0); PG8_BAR; PG8_MMA(0, 0, At, B0); PG8_MMA(0, 1, At, B1); PG8_BAR; PG8_SCHED;
	s_waitcnt lgkmcnt(0)
	v_mfma_f32_16x16x32_bf16 v[62:65], v[148:151], v[188:191], v[62:65]
	v_mfma_f32_16x16x32_bf16 v[58:61], v[160:163], v[188:191], v[58:61]
	s_setprio 3
	v_mfma_f32_16x16x32_bf16 v[50:53], v[148:151], v[196:199], v[50:53]
	v_mfma_f32_16x16x32_bf16 v[42:45], v[160:163], v[196:199], v[42:45]
	v_mfma_f32_16x16x32_bf16 v[34:37], v[148:151], v[204:207], v[34:37]
	v_mfma_f32_16x16x32_bf16 v[26:29], v[160:163], v[204:207], v[26:29]
	v_mfma_f32_16x16x32_bf16 v[18:21], v[148:151], v[212:215], v[18:21]
	v_mfma_f32_16x16x32_bf16 v[10:13], v[160:163], v[212:215], v[10:13]
	v_mfma_f32_16x16x32_bf16 v[62:65], v[152:155], v[192:195], v[62:65]
	v_mfma_f32_16x16x32_bf16 v[58:61], v[168:171], v[192:195], v[58:61]
	v_mfma_f32_16x16x32_bf16 v[50:53], v[152:155], v[200:203], v[50:53]
	v_mfma_f32_16x16x32_bf16 v[42:45], v[168:171], v[200:203], v[42:45]
	v_mfma_f32_16x16x32_bf16 v[34:37], v[152:155], v[208:211], v[34:37]
	v_mfma_f32_16x16x32_bf16 v[26:29], v[168:171], v[208:211], v[26:29]
	v_mfma_f32_16x16x32_bf16 v[18:21], v[152:155], v[216:219], v[18:21]
	v_mfma_f32_16x16x32_bf16 v[10:13], v[168:171], v[216:219], v[10:13]
	s_setprio 0
	s_setprio 3
	v_mfma_f32_16x16x32_bf16 v[54:57], v[172:175], v[188:191], v[54:57]
	v_mfma_f32_16x16x32_bf16 v[46:49], v[180:183], v[188:191], v[46:49]
	v_mfma_f32_16x16x32_bf16 v[38:41], v[172:175], v[196:199], v[38:41]
	v_mfma_f32_16x16x32_bf16 v[30:33], v[180:183], v[196:199], v[30:33]
	v_mfma_f32_16x16x32_bf16 v[22:25], v[172:175], v[204:207], v[22:25]
	v_mfma_f32_16x16x32_bf16 v[14:17], v[180:183], v[204:207], v[14:17]
	v_mfma_f32_16x16x32_bf16 v[6:9], v[172:175], v[212:215], v[6:9]
	v_mfma_f32_16x16x32_bf16 v[2:5], v[180:183], v[212:215], v[2:5]
	v_mfma_f32_16x16x32_bf16 v[54:57], v[176:179], v[192:195], v[54:57]
	v_mfma_f32_16x16x32_bf16 v[46:49], v[184:187], v[192:195], v[46:49]
	v_mfma_f32_16x16x32_bf16 v[38:41], v[176:179], v[200:203], v[38:41]
	v_mfma_f32_16x16x32_bf16 v[30:33], v[184:187], v[200:203], v[30:33]
	v_mfma_f32_16x16x32_bf16 v[22:25], v[176:179], v[208:211], v[22:25]
	v_mfma_f32_16x16x32_bf16 v[14:17], v[184:187], v[208:211], v[14:17]
	s_barrier
	v_mfma_f32_16x16x32_bf16 v[6:9], v[176:179], v[216:219], v[6:9]
	v_mfma_f32_16x16x32_bf16 v[2:5], v[184:187], v[216:219], v[2:5]
	s_setprio 0
	s_add_i32 s81, 0, 0x18000
	v_add_u32_e32 v167, s81, v141
	s_add_i32 s82, 0, 0x1c000
	ds_read_b128 v[148:151], v167
	ds_read_b128 v[152:155], v167 offset:1024
	ds_read_b128 v[160:163], v167 offset:2048
	ds_read_b128 v[168:171], v167 offset:3072
	v_add_u32_e32 v167, s82, v141
	ds_read_b128 v[172:175], v167
	ds_read_b128 v[176:179], v167 offset:1024
	ds_read_b128 v[180:183], v167 offset:2048
	ds_read_b128 v[184:187], v167 offset:3072
	s_add_u32 s52, s52, 0x158000
	s_addc_u32 s53, s53, 0
	s_mov_b32 m0, s56
	v_lshl_add_u64 v[226:227], s[52:53], 0, v[130:131]
	ds_read_b128 v[188:191], v159 offset:32768
	ds_read_b128 v[192:195], v159 offset:33792
	ds_read_b128 v[196:199], v159 offset:34816
	ds_read_b128 v[200:203], v159 offset:35840
	ds_read_b128 v[204:207], v159 offset:36864
	ds_read_b128 v[208:211], v159 offset:37888
	ds_read_b128 v[212:215], v159 offset:38912
	ds_read_b128 v[216:219], v159 offset:39936
	global_load_lds_dwordx4 v[226:227], off
	v_lshl_add_u64 v[226:227], s[52:53], 0, v[134:135]
	s_mov_b32 m0, s57
	s_nop 0
	global_load_lds_dwordx4 v[226:227], off
	s_waitcnt vmcnt(8)
	s_waitcnt lgkmcnt(0)
	s_barrier
	s_waitcnt lgkmcnt(0)
	v_mfma_f32_16x16x32_bf16 v[126:129], v[148:151], v[188:191], v[126:129]
	v_mfma_f32_16x16x32_bf16 v[122:125], v[160:163], v[188:191], v[122:125]
	s_setprio 3
	v_mfma_f32_16x16x32_bf16 v[114:117], v[148:151], v[196:199], v[114:117]
	v_mfma_f32_16x16x32_bf16 v[106:109], v[160:163], v[196:199], v[106:109]
	v_mfma_f32_16x16x32_bf16 v[98:101], v[148:151], v[204:207], v[98:101]
	v_mfma_f32_16x16x32_bf16 v[90:93], v[160:163], v[204:207], v[90:93]
	v_mfma_f32_16x16x32_bf16 v[82:85], v[148:151], v[212:215], v[82:85]
	v_mfma_f32_16x16x32_bf16 v[74:77], v[160:163], v[212:215], v[74:77]
	v_mfma_f32_16x16x32_bf16 v[126:129], v[152:155], v[192:195], v[126:129]
	v_mfma_f32_16x16x32_bf16 v[122:125], v[168:171], v[192:195], v[122:125]
	v_mfma_f32_16x16x32_bf16 v[114:117], v[152:155], v[200:203], v[114:117]
	v_mfma_f32_16x16x32_bf16 v[106:109], v[168:171], v[200:203], v[106:109]
	v_mfma_f32_16x16x32_bf16 v[98:101], v[152:155], v[208:211], v[98:101]
	v_mfma_f32_16x16x32_bf16 v[90:93], v[168:171], v[208:211], v[90:93]
	v_mfma_f32_16x16x32_bf16 v[82:85], v[152:155], v[216:219], v[82:85]
	v_mfma_f32_16x16x32_bf16 v[74:77], v[168:171], v[216:219], v[74:77]
	s_setprio 0
	s_setprio 3
	v_mfma_f32_16x16x32_bf16 v[118:121], v[172:175], v[188:191], v[118:121]
	v_mfma_f32_16x16x32_bf16 v[110:113], v[180:183], v[188:191], v[110:113]
	v_mfma_f32_16x16x32_bf16 v[102:105], v[172:175], v[196:199], v[102:105]
	v_mfma_f32_16x16x32_bf16 v[94:97], v[180:183], v[196:199], v[94:97]
	v_mfma_f32_16x16x32_bf16 v[86:89], v[172:175], v[204:207], v[86:89]
	v_mfma_f32_16x16x32_bf16 v[78:81], v[180:183], v[204:207], v[78:81]
	v_mfma_f32_16x16x32_bf16 v[70:73], v[172:175], v[212:215], v[70:73]
	v_mfma_f32_16x16x32_bf16 v[66:69], v[180:183], v[212:215], v[66:69]
	v_mfma_f32_16x16x32_bf16 v[118:121], v[176:179], v[192:195], v[118:121]
	v_mfma_f32_16x16x32_bf16 v[110:113], v[184:187], v[192:195], v[110:113]
	v_mfma_f32_16x16x32_bf16 v[102:105], v[176:179], v[200:203], v[102:105]
	v_mfma_f32_16x16x32_bf16 v[94:97], v[184:187], v[200:203], v[94:97]
	v_mfma_f32_16x16x32_bf16 v[86:89], v[176:179], v[208:211], v[86:89]
	v_mfma_f32_16x16x32_bf16 v[78:81], v[184:187], v[208:211], v[78:81]
	s_barrier
; #define PG8_STAGE(bufoff, gbase, voff) do { _Pragma("unroll") for (int _i = 0; _i < 2; ++_i) \
;         __builtin_amdgcn_global_load_lds((const unsigned*)((const char*)(gbase) + (voff)[_i]), (PG8_LAS unsigned*)(lds + (bufoff) + ldsw + _i * 8192), 16, 0, 0); } while (0)
; #define PG8_LDA(dst, b, h) do { _Pragma("unroll") for (int m = 0; m < 4; ++m) _Pragma("unroll") for (int k = 0; k < 2; ++k) dst[m][k] = *(const PG8_LAS bf16x8*)(lds + PG8_SA(b, h) + aoff + m * 2048 + k * 1024); } while (0)
; #define PG8_MMA(ai, bj, At, Bt) do { __builtin_amdgcn_s_setprio(3); _Pragma("unroll") for (int m = 0; m < 4; ++m) _Pragma("unroll") for (int n = 0; n < 2; ++n) _Pragma("unroll") for (int k = 0; k < 2; ++k) \
;         acc[ai][bj][m][n] = __builtin_amdgcn_mfma_f32_16x16x32_bf16(Bt[n][k], At[m][k], acc[ai][bj][m][n], 0, 0, 0); __builtin_amdgcn_s_setprio(0); } while (0)
; #define PG8_WAIT_V(n) asm volatile("s_waitcnt vmcnt(" #n ")" ::: "memory")
; #define PG8_WAIT_L(n) asm volatile("s_waitcnt lgkmcnt(" #n ")" ::: "memory")
; #define PG8_BAR __builtin_amdgcn_s_barrier()
; #define PG8_SCHED __builtin_amdgcn_sched_barrier(0)
; template <class Epi, class Sched, bool ALIGN_EPI = false, bool SP2 = false>
; __device__ __forceinline__ void gemm_phase(PG8_LAS unsigned char* lds, const Gemm g, const Sched& S, const Epi& E) {
;     ...
;             PG8_LDA(At, 1, 1); PG8_STAGE(PG8_SB(1, 0), b3, voffB); PG8_STAGE(PG8_SB(1, 1), b3 + hstep, voffB); PG8_STAGE(PG8_SA(1, 0), a3, voffA);
;             PG8_WAIT_V(8); PG8_WAIT_L(0); PG8_BAR; PG8_MMA(1, 0, At, B0); PG8_MMA(1, 1, At, B1); PG8_BAR; PG8_SCHED;
;     ...
;         }
;         if constexpr (ALIGN_EPI) { if (wr == 0) PG8_BAR; }
	v_mfma_f32_16x16x32_bf16 v[70:73], v[176:179], v[216:219], v[70:73]
	v_mfma_f32_16x16x32_bf16 v[66:69], v[184:187], v[216:219], v[66:69]
	s_setprio 0
	s_add_i32 s52, s81, s43
	v_lshl_add_u64 v[164:165], v[164:165], 0, s[18:19]
	s_mov_b32 m0, s52
	ds_read_b128 v[188:191], v159 offset:49152
	ds_read_b128 v[192:195], v159 offset:50176
	ds_read_b128 v[196:199], v159 offset:51200
	ds_read_b128 v[200:203], v159 offset:52224
	ds_read_b128 v[204:207], v159 offset:53248
	ds_read_b128 v[208:211], v159 offset:54272
	ds_read_b128 v[212:215], v159 offset:55296
	ds_read_b128 v[216:219], v159 offset:56320
	global_load_lds_dwordx4 v[164:165], off
	s_add_i32 m0, s52, 0x2000
	s_add_u32 s50, s50, 0x158080
	v_lshl_add_u64 v[164:165], v[220:221], 0, s[18:19]
	s_addc_u32 s51, s51, 0
	s_add_i32 s52, s82, s43
	global_load_lds_dwordx4 v[164:165], off
	v_lshl_add_u64 v[164:165], s[50:51], 0, v[132:133]
	s_mov_b32 m0, s52
	s_nop 0
	global_load_lds_dwordx4 v[164:165], off
	v_lshl_add_u64 v[164:165], s[50:51], 0, v[136:137]
	s_add_i32 m0, s52, 0x2000
	s_nop 0
	global_load_lds_dwordx4 v[164:165], off
	v_lshl_add_u64 v[164:165], v[222:223], 0, s[18:19]
	s_mov_b32 m0, s62
	s_nop 0
	global_load_lds_dwordx4 v[164:165], off
	v_lshl_add_u64 v[164:165], v[224:225], 0, s[18:19]
	s_mov_b32 m0, s63
	s_nop 0
	global_load_lds_dwordx4 v[164:165], off
	s_waitcnt vmcnt(8)
	s_waitcnt lgkmcnt(0)
	s_barrier
	s_waitcnt lgkmcnt(0)
	v_mfma_f32_16x16x32_bf16 v[62:65], v[148:151], v[188:191], v[62:65]
	v_mfma_f32_16x16x32_bf16 v[58:61], v[160:163], v[188:191], v[58:61]
	s_setprio 3
	v_mfma_f32_16x16x32_bf16 v[50:53], v[148:151], v[196:199], v[50:53]
	v_mfma_f32_16x16x32_bf16 v[42:45], v[160:163], v[196:199], v[42:45]
	v_mfma_f32_16x16x32_bf16 v[34:37], v[148:151], v[204:207], v[34:37]
	v_mfma_f32_16x16x32_bf16 v[26:29], v[160:163], v[204:207], v[26:29]
	v_mfma_f32_16x16x32_bf16 v[18:21], v[148:151], v[212:215], v[18:21]
	v_mfma_f32_16x16x32_bf16 v[10:13], v[160:163], v[212:215], v[10:13]
	v_mfma_f32_16x16x32_bf16 v[62:65], v[152:155], v[192:195], v[62:65]
	v_mfma_f32_16x16x32_bf16 v[58:61], v[168:171], v[192:195], v[58:61]
	v_mfma_f32_16x16x32_bf16 v[50:53], v[152:155], v[200:203], v[50:53]
	v_mfma_f32_16x16x32_bf16 v[42:45], v[168:171], v[200:203], v[42:45]
	v_mfma_f32_16x16x32_bf16 v[34:37], v[152:155], v[208:211], v[34:37]
	v_mfma_f32_16x16x32_bf16 v[26:29], v[168:171], v[208:211], v[26:29]
	v_mfma_f32_16x16x32_bf16 v[18:21], v[152:155], v[216:219], v[18:21]
	v_mfma_f32_16x16x32_bf16 v[10:13], v[168:171], v[216:219], v[10:13]
	s_setprio 0
	s_setprio 3
	v_mfma_f32_16x16x32_bf16 v[54:57], v[172:175], v[188:191], v[54:57]
	v_mfma_f32_16x16x32_bf16 v[46:49], v[180:183], v[188:191], v[46:49]
	v_mfma_f32_16x16x32_bf16 v[38:41], v[172:175], v[196:199], v[38:41]
	v_mfma_f32_16x16x32_bf16 v[30:33], v[180:183], v[196:199], v[30:33]
	v_mfma_f32_16x16x32_bf16 v[22:25], v[172:175], v[204:207], v[22:25]
	v_mfma_f32_16x16x32_bf16 v[14:17], v[180:183], v[204:207], v[14:17]
	v_mfma_f32_16x16x32_bf16 v[6:9], v[172:175], v[212:215], v[6:9]
	v_mfma_f32_16x16x32_bf16 v[2:5], v[180:183], v[212:215], v[2:5]
	v_mfma_f32_16x16x32_bf16 v[54:57], v[176:179], v[192:195], v[54:57]
	v_mfma_f32_16x16x32_bf16 v[46:49], v[184:187], v[192:195], v[46:49]
	v_mfma_f32_16x16x32_bf16 v[38:41], v[176:179], v[200:203], v[38:41]
	v_mfma_f32_16x16x32_bf16 v[30:33], v[184:187], v[200:203], v[30:33]
	v_mfma_f32_16x16x32_bf16 v[22:25], v[176:179], v[208:211], v[22:25]
	v_mfma_f32_16x16x32_bf16 v[14:17], v[184:187], v[208:211], v[14:17]
	s_barrier
	v_mfma_f32_16x16x32_bf16 v[6:9], v[176:179], v[216:219], v[6:9]
	v_mfma_f32_16x16x32_bf16 v[2:5], v[184:187], v[216:219], v[2:5]
	s_setprio 0
	s_add_u32 s8, s8, 0x100
	s_addc_u32 s9, s9, 0
	s_add_u32 s77, s77, 0x100
	s_addc_u32 s78, s78, 0
	s_cmp_ge_u32 s79, s75
	s_mov_b32 s50, s79
	s_cbranch_scc0 .LBB0_179
	s_and_b64 vcc, exec, s[24:25]
	s_cbranch_vccz .LBB0_182
	s_barrier

; #define PG8_STAGE(bufoff, gbase, voff) do { _Pragma("unroll") for (int _i = 0; _i < 2; ++_i) \
;         __builtin_amdgcn_global_load_lds((const unsigned*)((const char*)(gbase) + (voff)[_i]), (PG8_LAS unsigned*)(lds + (bufoff) + ldsw + _i * 8192), 16, 0, 0); } while (0)
; #define PG8_LDA(dst, b, h) do { _Pragma("unroll") for (int m = 0; m < 4; ++m) _Pragma("unroll") for (int k = 0; k < 2; ++k) dst[m][k] = *(const PG8_LAS bf16x8*)(lds + PG8_SA(b, h) + aoff + m * 2048 + k * 1024); } while (0)
; #define PG8_LDB(dst, b, h) do { _Pragma("unroll") for (int n = 0; n < 2; ++n) _Pragma("unroll") for (int k = 0; k < 2; ++k) dst[n][k] = *(const PG8_LAS bf16x8*)(lds + PG8_SB(b, h) + boff + n * 2048 + k * 1024); } while (0)
; #define PG8_MMA(ai, bj, At, Bt) do { __builtin_amdgcn_s_setprio(3); _Pragma("unroll") for (int m = 0; m < 4; ++m) _Pragma("unroll") for (int n = 0; n < 2; ++n) _Pragma("unroll") for (int k = 0; k < 2; ++k) \
;         acc[ai][bj][m][n] = __builtin_amdgcn_mfma_f32_16x16x32_bf16(Bt[n][k], At[m][k], acc[ai][bj][m][n], 0, 0, 0); __builtin_amdgcn_s_setprio(0); } while (0)
; #define PG8_WAIT_V(n) asm volatile("s_waitcnt vmcnt(" #n ")" ::: "memory")
; #define PG8_BAR __builtin_amdgcn_s_barrier()
; template <class Epi, class Sched, bool ALIGN_EPI = false, bool SP2 = false>
; __device__ __forceinline__ void gemm_phase(PG8_LAS unsigned char* lds, const Gemm g, const Sched& S, const Epi& E) {
;     ...
;         for (int t = 0; t < nt; t += 2) {
;             const bool last = (t == nt - 2);
;             const char* a1 = cA + (size_t)(t + 1) * kstep;
;             const char* a2 = last ? nA : cA + (size_t)(t + 2) * kstep; const char* b2 = last ? nB : cB + (size_t)(t + 2) * kstep;
;             const char* a3 = a2 + kstep; const char* b3 = b2 + kstep;
;             if (last && has_next) S.a_ready(nxt);
;             if constexpr (SP2) {
;             PG8_LDB(B0, 0, 0); PG8_LDB(B1, 0, 1); PG8_SCHED; PG8_LDA(At, 0, 0); PG8_STAGE(PG8_SA(1, 1), a1 + hstep, voffA);
;             PG8_WAIT_V(8); PG8_WAIT_L(0); PG8_BAR; PG8_MMA(0, 0, At, B0); PG8_MMA(0, 1, At, B1); PG8_BAR; PG8_SCHED;
;             PG8_LDA(At, 0, 1); PG8_STAGE(PG8_SB(0, 0), b2, voffB); PG8_STAGE(PG8_SB(0, 1), b2 + hstep, voffB); PG8_STAGE(PG8_SA(0, 0), a2, voffA);
;             PG8_WAIT_V(8); PG8_WAIT_L(0); PG8_BAR; PG8_MMA(1, 0, At, B0); PG8_MMA(1, 1, At, B1); PG8_BAR; PG8_SCHED;
.LBB0_394:
	ds_read_b128 v[148:151], v155
	ds_read_b128 v[158:161], v155 offset:1024
	ds_read_b128 v[162:165], v155 offset:2048
	ds_read_b128 v[168:171], v155 offset:3072
	ds_read_b128 v[172:175], v156
	ds_read_b128 v[176:179], v156 offset:1024
	ds_read_b128 v[180:183], v156 offset:2048
	ds_read_b128 v[184:187], v156 offset:3072
	s_add_u32 s48, s46, 0xfff80080
	s_addc_u32 s49, s47, -1
	s_cmp_eq_u32 s70, 28
	s_cselect_b32 s51, s7, s49
	s_cselect_b32 s50, s27, s48
	s_cselect_b32 s49, s25, s69
	s_cselect_b32 s48, s45, s68
	v_lshl_add_u64 v[152:153], s[46:47], 0, v[138:139]
	s_add_i32 m0, s52, 0xc000
	ds_read_b128 v[188:191], v157
	ds_read_b128 v[192:195], v157 offset:1024
	ds_read_b128 v[196:199], v157 offset:2048
	ds_read_b128 v[200:203], v157 offset:3072
	ds_read_b128 v[204:207], v157 offset:4096
	ds_read_b128 v[208:211], v157 offset:5120
	ds_read_b128 v[212:215], v157 offset:6144
	ds_read_b128 v[216:219], v157 offset:7168
	global_load_lds_dwordx4 v[152:153], off
	v_lshl_add_u64 v[152:153], s[46:47], 0, v[142:143]
	s_add_i32 m0, s52, 0xe000
	s_nop 0
	global_load_lds_dwordx4 v[152:153], off
	s_waitcnt vmcnt(8)
	s_waitcnt lgkmcnt(0)
	s_barrier
	s_waitcnt lgkmcnt(0)
	v_mfma_f32_16x16x32_bf16 v[126:129], v[148:151], v[188:191], v[126:129]
	v_mfma_f32_16x16x32_bf16 v[122:125], v[162:165], v[188:191], v[122:125]
	s_setprio 3
	v_mfma_f32_16x16x32_bf16 v[114:117], v[148:151], v[196:199], v[114:117]
	v_mfma_f32_16x16x32_bf16 v[106:109], v[162:165], v[196:199], v[106:109]
	v_mfma_f32_16x16x32_bf16 v[98:101], v[148:151], v[204:207], v[98:101]
	v_mfma_f32_16x16x32_bf16 v[90:93], v[162:165], v[204:207], v[90:93]
	v_mfma_f32_16x16x32_bf16 v[82:85], v[148:151], v[212:215], v[82:85]
	v_mfma_f32_16x16x32_bf16 v[74:77], v[162:165], v[212:215], v[74:77]
	v_mfma_f32_16x16x32_bf16 v[126:129], v[158:161], v[192:195], v[126:129]
	v_mfma_f32_16x16x32_bf16 v[122:125], v[168:171], v[192:195], v[122:125]
	v_mfma_f32_16x16x32_bf16 v[114:117], v[158:161], v[200:203], v[114:117]
	v_mfma_f32_16x16x32_bf16 v[106:109], v[168:171], v[200:203], v[106:109]
	v_mfma_f32_16x16x32_bf16 v[98:101], v[158:161], v[208:211], v[98:101]
	v_mfma_f32_16x16x32_bf16 v[90:93], v[168:171], v[208:211], v[90:93]
	v_mfma_f32_16x16x32_bf16 v[82:85], v[158:161], v[216:219], v[82:85]
	v_mfma_f32_16x16x32_bf16 v[74:77], v[168:171], v[216:219], v[74:77]
	s_setprio 0
	s_setprio 3
	v_mfma_f32_16x16x32_bf16 v[118:121], v[172:175], v[188:191], v[118:121]
	v_mfma_f32_16x16x32_bf16 v[110:113], v[180:183], v[188:191], v[110:113]
	v_mfma_f32_16x16x32_bf16 v[102:105], v[172:175], v[196:199], v[102:105]
	v_mfma_f32_16x16x32_bf16 v[94:97], v[180:183], v[196:199], v[94:97]
	v_mfma_f32_16x16x32_bf16 v[86:89], v[172:175], v[204:207], v[86:89]
	v_mfma_f32_16x16x32_bf16 v[78:81], v[180:183], v[204:207], v[78:81]
	v_mfma_f32_16x16x32_bf16 v[70:73], v[172:175], v[212:215], v[70:73]
	v_mfma_f32_16x16x32_bf16 v[66:69], v[180:183], v[212:215], v[66:69]
	v_mfma_f32_16x16x32_bf16 v[118:121], v[176:179], v[192:195], v[118:121]
	v_mfma_f32_16x16x32_bf16 v[110:113], v[184:187], v[192:195], v[110:113]
	v_mfma_f32_16x16x32_bf16 v[102:105], v[176:179], v[200:203], v[102:105]
	v_mfma_f32_16x16x32_bf16 v[94:97], v[184:187], v[200:203], v[94:97]
	v_mfma_f32_16x16x32_bf16 v[86:89], v[176:179], v[208:211], v[86:89]
	v_mfma_f32_16x16x32_bf16 v[78:81], v[184:187], v[208:211], v[78:81]
	s_barrier
	v_mfma_f32_16x16x32_bf16 v[70:73], v[176:179], v[216:219], v[70:73]
	v_mfma_f32_16x16x32_bf16 v[66:69], v[184:187], v[216:219], v[66:69]
	s_setprio 0
	s_add_i32 s71, s63, s43
	v_lshl_add_u64 v[152:153], s[48:49], 0, v[132:133]
	s_mov_b32 m0, s71
	ds_read_b128 v[188:191], v157 offset:16384
	ds_read_b128 v[192:195], v157 offset:17408
	ds_read_b128 v[196:199], v157 offset:18432
	ds_read_b128 v[200:203], v157 offset:19456
	ds_read_b128 v[204:207], v157 offset:20480
	ds_read_b128 v[208:211], v157 offset:21504
	ds_read_b128 v[212:215], v157 offset:22528
	ds_read_b128 v[216:219], v157 offset:23552
	global_load_lds_dwordx4 v[152:153], off
	s_add_i32 m0, s71, 0x2000
	s_add_u32 s72, s48, 0x80000
	v_lshl_add_u64 v[220:221], s[48:49], 0, v[136:137]
	s_addc_u32 s73, s49, 0
	s_add_i32 s71, s64, s43
	global_load_lds_dwordx4 v[220:221], off
	v_lshl_add_u64 v[222:223], s[72:73], 0, v[132:133]
	s_mov_b32 m0, s71
	v_lshl_add_u64 v[224:225], s[50:51], 0, v[134:135]
	global_load_lds_dwordx4 v[222:223], off
	v_lshl_add_u64 v[222:223], s[72:73], 0, v[136:137]
	s_add_i32 m0, s71, 0x2000
	s_nop 0
	global_load_lds_dwordx4 v[222:223], off
	v_lshl_add_u64 v[222:223], s[50:51], 0, v[130:131]
	s_mov_b32 m0, s52
	s_nop 0
	global_load_lds_dwordx4 v[222:223], off
	s_mov_b32 m0, s53
	s_nop 0
	global_load_lds_dwordx4 v[224:225], off
	s_waitcnt vmcnt(8)
	s_waitcnt lgkmcnt(0)
	s_barrier
; #define PG8_STAGE(bufoff, gbase, voff) do { _Pragma("unroll") for (int _i = 0; _i < 2; ++_i) \
;         __builtin_amdgcn_global_load_lds((const unsigned*)((const char*)(gbase) + (voff)[_i]), (PG8_LAS unsigned*)(lds + (bufoff) + ldsw + _i * 8192), 16, 0, 0); } while (0)
; #define PG8_LDA(dst, b, h) do { _Pragma("unroll") for (int m = 0; m < 4; ++m) _Pragma("unroll") for (int k = 0; k < 2; ++k) dst[m][k] = *(const PG8_LAS bf16x8*)(lds + PG8_SA(b, h) + aoff + m * 2048 + k * 1024); } while (0)
; #define PG8_LDB(dst, b, h) do { _Pragma("unroll") for (int n = 0; n < 2; ++n) _Pragma("unroll") for (int k = 0; k < 2; ++k) dst[n][k] = *(const PG8_LAS bf16x8*)(lds + PG8_SB(b, h) + boff + n * 2048 + k * 1024); } while (0)
; #define PG8_MMA(ai, bj, At, Bt) do { __builtin_amdgcn_s_setprio(3); _Pragma("unroll") for (int m = 0; m < 4; ++m) _Pragma("unroll") for (int n = 0; n < 2; ++n) _Pragma("unroll") for (int k = 0; k < 2; ++k) \
;         acc[ai][bj][m][n] = __builtin_amdgcn_mfma_f32_16x16x32_bf16(Bt[n][k], At[m][k], acc[ai][bj][m][n], 0, 0, 0); __builtin_amdgcn_s_setprio(0); } while (0)
; #define PG8_WAIT_V(n) asm volatile("s_waitcnt vmcnt(" #n ")" ::: "memory")
; #define PG8_WAIT_L(n) asm volatile("s_waitcnt lgkmcnt(" #n ")" ::: "memory")
; #define PG8_BAR __builtin_amdgcn_s_barrier()
; #define PG8_SCHED __builtin_amdgcn_sched_barrier(0)
; template <class Epi, class Sched, bool ALIGN_EPI = false, bool SP2 = false>
; __device__ __forceinline__ void gemm_phase(PG8_LAS unsigned char* lds, const Gemm g, const Sched& S, const Epi& E) {
;     ...
;             PG8_WAIT_V(8); PG8_WAIT_L(0); PG8_BAR; PG8_MMA(1, 0, At, B0); PG8_MMA(1, 1, At, B1); PG8_BAR; PG8_SCHED;
;             PG8_LDB(B0, 1, 0); PG8_LDB(B1, 1, 1); PG8_SCHED; PG8_LDA(At, 1, 0); PG8_STAGE(PG8_SA(0, 1), a2 + hstep, voffA);
;             PG8_WAIT_V(8); PG8_WAIT_L(0); PG8_BAR; PG8_MMA(0, 0, At, B0); PG8_MMA(0, 1, At, B1); PG8_BAR; PG8_SCHED;
	s_waitcnt lgkmcnt(0)
	v_mfma_f32_16x16x32_bf16 v[62:65], v[148:151], v[188:191], v[62:65]
	v_mfma_f32_16x16x32_bf16 v[58:61], v[162:165], v[188:191], v[58:61]
	s_setprio 3
	v_mfma_f32_16x16x32_bf16 v[50:53], v[148:151], v[196:199], v[50:53]
	v_mfma_f32_16x16x32_bf16 v[42:45], v[162:165], v[196:199], v[42:45]
	v_mfma_f32_16x16x32_bf16 v[34:37], v[148:151], v[204:207], v[34:37]
	v_mfma_f32_16x16x32_bf16 v[26:29], v[162:165], v[204:207], v[26:29]
	v_mfma_f32_16x16x32_bf16 v[18:21], v[148:151], v[212:215], v[18:21]
	v_mfma_f32_16x16x32_bf16 v[10:13], v[162:165], v[212:215], v[10:13]
	v_mfma_f32_16x16x32_bf16 v[62:65], v[158:161], v[192:195], v[62:65]
	v_mfma_f32_16x16x32_bf16 v[58:61], v[168:171], v[192:195], v[58:61]
	v_mfma_f32_16x16x32_bf16 v[50:53], v[158:161], v[200:203], v[50:53]
	v_mfma_f32_16x16x32_bf16 v[42:45], v[168:171], v[200:203], v[42:45]
	v_mfma_f32_16x16x32_bf16 v[34:37], v[158:161], v[208:211], v[34:37]
	v_mfma_f32_16x16x32_bf16 v[26:29], v[168:171], v[208:211], v[26:29]
	v_mfma_f32_16x16x32_bf16 v[18:21], v[158:161], v[216:219], v[18:21]
	v_mfma_f32_16x16x32_bf16 v[10:13], v[168:171], v[216:219], v[10:13]
	s_setprio 0
	s_setprio 3
	v_mfma_f32_16x16x32_bf16 v[54:57], v[172:175], v[188:191], v[54:57]
	v_mfma_f32_16x16x32_bf16 v[46:49], v[180:183], v[188:191], v[46:49]
	v_mfma_f32_16x16x32_bf16 v[38:41], v[172:175], v[196:199], v[38:41]
	v_mfma_f32_16x16x32_bf16 v[30:33], v[180:183], v[196:199], v[30:33]
	v_mfma_f32_16x16x32_bf16 v[22:25], v[172:175], v[204:207], v[22:25]
	v_mfma_f32_16x16x32_bf16 v[14:17], v[180:183], v[204:207], v[14:17]
	v_mfma_f32_16x16x32_bf16 v[6:9], v[172:175], v[212:215], v[6:9]
	v_mfma_f32_16x16x32_bf16 v[2:5], v[180:183], v[212:215], v[2:5]
	v_mfma_f32_16x16x32_bf16 v[54:57], v[176:179], v[192:195], v[54:57]
	v_mfma_f32_16x16x32_bf16 v[46:49], v[184:187], v[192:195], v[46:49]
	v_mfma_f32_16x16x32_bf16 v[38:41], v[176:179], v[200:203], v[38:41]
	v_mfma_f32_16x16x32_bf16 v[30:33], v[184:187], v[200:203], v[30:33]
	v_mfma_f32_16x16x32_bf16 v[22:25], v[176:179], v[208:211], v[22:25]
	v_mfma_f32_16x16x32_bf16 v[14:17], v[184:187], v[208:211], v[14:17]
	s_barrier
	v_mfma_f32_16x16x32_bf16 v[6:9], v[176:179], v[216:219], v[6:9]
	v_mfma_f32_16x16x32_bf16 v[2:5], v[184:187], v[216:219], v[2:5]
	s_setprio 0
	s_add_i32 s71, 0, 0x18000
	v_add_u32_e32 v167, s71, v141
	s_add_i32 s72, 0, 0x1c000
	ds_read_b128 v[148:151], v167
	ds_read_b128 v[158:161], v167 offset:1024
	ds_read_b128 v[162:165], v167 offset:2048
	ds_read_b128 v[168:171], v167 offset:3072
	v_add_u32_e32 v167, s72, v141
	ds_read_b128 v[172:175], v167
	ds_read_b128 v[176:179], v167 offset:1024
	ds_read_b128 v[180:183], v167 offset:2048
	ds_read_b128 v[184:187], v167 offset:3072
	s_add_u32 s50, s50, 0x80000
	s_addc_u32 s51, s51, 0
	s_mov_b32 m0, s54
	v_lshl_add_u64 v[226:227], s[50:51], 0, v[130:131]
	ds_read_b128 v[188:191], v157 offset:32768
	ds_read_b128 v[192:195], v157 offset:33792
	ds_read_b128 v[196:199], v157 offset:34816
	ds_read_b128 v[200:203], v157 offset:35840
	ds_read_b128 v[204:207], v157 offset:36864
	ds_read_b128 v[208:211], v157 offset:37888
	ds_read_b128 v[212:215], v157 offset:38912
	ds_read_b128 v[216:219], v157 offset:39936
	global_load_lds_dwordx4 v[226:227], off
	v_lshl_add_u64 v[226:227], s[50:51], 0, v[134:135]
	s_mov_b32 m0, s55
	s_nop 0
	global_load_lds_dwordx4 v[226:227], off
	s_waitcnt vmcnt(8)
	s_waitcnt lgkmcnt(0)
	s_barrier
	s_waitcnt lgkmcnt(0)
	v_mfma_f32_16x16x32_bf16 v[126:129], v[148:151], v[188:191], v[126:129]
	v_mfma_f32_16x16x32_bf16 v[122:125], v[162:165], v[188:191], v[122:125]
	s_setprio 3
	v_mfma_f32_16x16x32_bf16 v[114:117], v[148:151], v[196:199], v[114:117]
	v_mfma_f32_16x16x32_bf16 v[106:109], v[162:165], v[196:199], v[106:109]
	v_mfma_f32_16x16x32_bf16 v[98:101], v[148:151], v[204:207], v[98:101]
	v_mfma_f32_16x16x32_bf16 v[90:93], v[162:165], v[204:207], v[90:93]
	v_mfma_f32_16x16x32_bf16 v[82:85], v[148:151], v[212:215], v[82:85]
	v_mfma_f32_16x16x32_bf16 v[74:77], v[162:165], v[212:215], v[74:77]
	v_mfma_f32_16x16x32_bf16 v[126:129], v[158:161], v[192:195], v[126:129]
	v_mfma_f32_16x16x32_bf16 v[122:125], v[168:171], v[192:195], v[122:125]
	v_mfma_f32_16x16x32_bf16 v[114:117], v[158:161], v[200:203], v[114:117]
	v_mfma_f32_16x16x32_bf16 v[106:109], v[168:171], v[200:203], v[106:109]
	v_mfma_f32_16x16x32_bf16 v[98:101], v[158:161], v[208:211], v[98:101]
	v_mfma_f32_16x16x32_bf16 v[90:93], v[168:171], v[208:211], v[90:93]
	v_mfma_f32_16x16x32_bf16 v[82:85], v[158:161], v[216:219], v[82:85]
	v_mfma_f32_16x16x32_bf16 v[74:77], v[168:171], v[216:219], v[74:77]
	s_setprio 0
	s_setprio 3
	v_mfma_f32_16x16x32_bf16 v[118:121], v[172:175], v[188:191], v[118:121]
	v_mfma_f32_16x16x32_bf16 v[110:113], v[180:183], v[188:191], v[110:113]
	v_mfma_f32_16x16x32_bf16 v[102:105], v[172:175], v[196:199], v[102:105]
	v_mfma_f32_16x16x32_bf16 v[94:97], v[180:183], v[196:199], v[94:97]
	v_mfma_f32_16x16x32_bf16 v[86:89], v[172:175], v[204:207], v[86:89]
	v_mfma_f32_16x16x32_bf16 v[78:81], v[180:183], v[204:207], v[78:81]
	v_mfma_f32_16x16x32_bf16 v[70:73], v[172:175], v[212:215], v[70:73]
	v_mfma_f32_16x16x32_bf16 v[66:69], v[180:183], v[212:215], v[66:69]
	v_mfma_f32_16x16x32_bf16 v[118:121], v[176:179], v[192:195], v[118:121]
	v_mfma_f32_16x16x32_bf16 v[110:113], v[184:187], v[192:195], v[110:113]
	v_mfma_f32_16x16x32_bf16 v[102:105], v[176:179], v[200:203], v[102:105]
	v_mfma_f32_16x16x32_bf16 v[94:97], v[184:187], v[200:203], v[94:97]
	v_mfma_f32_16x16x32_bf16 v[86:89], v[176:179], v[208:211], v[86:89]
	v_mfma_f32_16x16x32_bf16 v[78:81], v[184:187], v[208:211], v[78:81]
	s_barrier
; #define PG8_STAGE(bufoff, gbase, voff) do { _Pragma("unroll") for (int _i = 0; _i < 2; ++_i) \
;         __builtin_amdgcn_global_load_lds((const unsigned*)((const char*)(gbase) + (voff)[_i]), (PG8_LAS unsigned*)(lds + (bufoff) + ldsw + _i * 8192), 16, 0, 0); } while (0)
; #define PG8_LDA(dst, b, h) do { _Pragma("unroll") for (int m = 0; m < 4; ++m) _Pragma("unroll") for (int k = 0; k < 2; ++k) dst[m][k] = *(const PG8_LAS bf16x8*)(lds + PG8_SA(b, h) + aoff + m * 2048 + k * 1024); } while (0)
; #define PG8_MMA(ai, bj, At, Bt) do { __builtin_amdgcn_s_setprio(3); _Pragma("unroll") for (int m = 0; m < 4; ++m) _Pragma("unroll") for (int n = 0; n < 2; ++n) _Pragma("unroll") for (int k = 0; k < 2; ++k) \
;         acc[ai][bj][m][n] = __builtin_amdgcn_mfma_f32_16x16x32_bf16(Bt[n][k], At[m][k], acc[ai][bj][m][n], 0, 0, 0); __builtin_amdgcn_s_setprio(0); } while (0)
; #define PG8_WAIT_V(n) asm volatile("s_waitcnt vmcnt(" #n ")" ::: "memory")
; #define PG8_WAIT_L(n) asm volatile("s_waitcnt lgkmcnt(" #n ")" ::: "memory")
; #define PG8_BAR __builtin_amdgcn_s_barrier()
; #define PG8_SCHED __builtin_amdgcn_sched_barrier(0)
; template <class Epi, class Sched, bool ALIGN_EPI = false, bool SP2 = false>
; __device__ __forceinline__ void gemm_phase(PG8_LAS unsigned char* lds, const Gemm g, const Sched& S, const Epi& E) {
;     ...
;             PG8_LDA(At, 1, 1); PG8_STAGE(PG8_SB(1, 0), b3, voffB); PG8_STAGE(PG8_SB(1, 1), b3 + hstep, voffB); PG8_STAGE(PG8_SA(1, 0), a3, voffA);
;             PG8_WAIT_V(8); PG8_WAIT_L(0); PG8_BAR; PG8_MMA(1, 0, At, B0); PG8_MMA(1, 1, At, B1); PG8_BAR; PG8_SCHED;
;     ...
;         }
;         if constexpr (ALIGN_EPI) { if (wr == 0) PG8_BAR; }
	v_mfma_f32_16x16x32_bf16 v[70:73], v[176:179], v[216:219], v[70:73]
	v_mfma_f32_16x16x32_bf16 v[66:69], v[184:187], v[216:219], v[66:69]
	s_setprio 0
	s_add_i32 s50, s71, s43
	v_lshl_add_u64 v[152:153], v[152:153], 0, s[16:17]
	s_mov_b32 m0, s50
	ds_read_b128 v[188:191], v157 offset:49152
	ds_read_b128 v[192:195], v157 offset:50176
	ds_read_b128 v[196:199], v157 offset:51200
	ds_read_b128 v[200:203], v157 offset:52224
	ds_read_b128 v[204:207], v157 offset:53248
	ds_read_b128 v[208:211], v157 offset:54272
	ds_read_b128 v[212:215], v157 offset:55296
	ds_read_b128 v[216:219], v157 offset:56320
	global_load_lds_dwordx4 v[152:153], off
	s_add_i32 m0, s50, 0x2000
	s_add_u32 s48, s48, 0x80080
	v_lshl_add_u64 v[152:153], v[220:221], 0, s[16:17]
	s_addc_u32 s49, s49, 0
	s_add_i32 s50, s72, s43
	global_load_lds_dwordx4 v[152:153], off
	v_lshl_add_u64 v[152:153], s[48:49], 0, v[132:133]
	s_mov_b32 m0, s50
	s_nop 0
	global_load_lds_dwordx4 v[152:153], off
	v_lshl_add_u64 v[152:153], s[48:49], 0, v[136:137]
	s_add_i32 m0, s50, 0x2000
	s_nop 0
	global_load_lds_dwordx4 v[152:153], off
	v_lshl_add_u64 v[152:153], v[222:223], 0, s[16:17]
	s_mov_b32 m0, s59
	s_nop 0
	global_load_lds_dwordx4 v[152:153], off
	v_lshl_add_u64 v[152:153], v[224:225], 0, s[16:17]
	s_mov_b32 m0, s60
	s_nop 0
	global_load_lds_dwordx4 v[152:153], off
	s_waitcnt vmcnt(8)
	s_waitcnt lgkmcnt(0)
	s_barrier
	s_waitcnt lgkmcnt(0)
	v_mfma_f32_16x16x32_bf16 v[62:65], v[148:151], v[188:191], v[62:65]
	v_mfma_f32_16x16x32_bf16 v[58:61], v[162:165], v[188:191], v[58:61]
	s_setprio 3
	v_mfma_f32_16x16x32_bf16 v[50:53], v[148:151], v[196:199], v[50:53]
	v_mfma_f32_16x16x32_bf16 v[42:45], v[162:165], v[196:199], v[42:45]
	v_mfma_f32_16x16x32_bf16 v[34:37], v[148:151], v[204:207], v[34:37]
	v_mfma_f32_16x16x32_bf16 v[26:29], v[162:165], v[204:207], v[26:29]
	v_mfma_f32_16x16x32_bf16 v[18:21], v[148:151], v[212:215], v[18:21]
	v_mfma_f32_16x16x32_bf16 v[10:13], v[162:165], v[212:215], v[10:13]
	v_mfma_f32_16x16x32_bf16 v[62:65], v[158:161], v[192:195], v[62:65]
	v_mfma_f32_16x16x32_bf16 v[58:61], v[168:171], v[192:195], v[58:61]
	v_mfma_f32_16x16x32_bf16 v[50:53], v[158:161], v[200:203], v[50:53]
	v_mfma_f32_16x16x32_bf16 v[42:45], v[168:171], v[200:203], v[42:45]
	v_mfma_f32_16x16x32_bf16 v[34:37], v[158:161], v[208:211], v[34:37]
	v_mfma_f32_16x16x32_bf16 v[26:29], v[168:171], v[208:211], v[26:29]
	v_mfma_f32_16x16x32_bf16 v[18:21], v[158:161], v[216:219], v[18:21]
	v_mfma_f32_16x16x32_bf16 v[10:13], v[168:171], v[216:219], v[10:13]
	s_setprio 0
	s_setprio 3
	v_mfma_f32_16x16x32_bf16 v[54:57], v[172:175], v[188:191], v[54:57]
	v_mfma_f32_16x16x32_bf16 v[46:49], v[180:183], v[188:191], v[46:49]
	v_mfma_f32_16x16x32_bf16 v[38:41], v[172:175], v[196:199], v[38:41]
	v_mfma_f32_16x16x32_bf16 v[30:33], v[180:183], v[196:199], v[30:33]
	v_mfma_f32_16x16x32_bf16 v[22:25], v[172:175], v[204:207], v[22:25]
	v_mfma_f32_16x16x32_bf16 v[14:17], v[180:183], v[204:207], v[14:17]
	v_mfma_f32_16x16x32_bf16 v[6:9], v[172:175], v[212:215], v[6:9]
	v_mfma_f32_16x16x32_bf16 v[2:5], v[180:183], v[212:215], v[2:5]
	v_mfma_f32_16x16x32_bf16 v[54:57], v[176:179], v[192:195], v[54:57]
	v_mfma_f32_16x16x32_bf16 v[46:49], v[184:187], v[192:195], v[46:49]
	v_mfma_f32_16x16x32_bf16 v[38:41], v[176:179], v[200:203], v[38:41]
	v_mfma_f32_16x16x32_bf16 v[30:33], v[184:187], v[200:203], v[30:33]
	v_mfma_f32_16x16x32_bf16 v[22:25], v[176:179], v[208:211], v[22:25]
	v_mfma_f32_16x16x32_bf16 v[14:17], v[184:187], v[208:211], v[14:17]
	s_barrier
	v_mfma_f32_16x16x32_bf16 v[6:9], v[176:179], v[216:219], v[6:9]
	v_mfma_f32_16x16x32_bf16 v[2:5], v[184:187], v[216:219], v[2:5]
	s_setprio 0
	s_add_i32 s70, s70, 2
	s_add_u32 s46, s46, 0x100
	s_addc_u32 s47, s47, 0
	s_add_u32 s68, s68, 0x100
	s_addc_u32 s69, s69, 0
	s_cmp_gt_u32 s70, 29
	s_cbranch_scc0 .LBB0_394
	s_and_b64 vcc, exec, s[18:19]
	s_cbranch_vccz .LBB0_397
	s_barrier

; #define PG8_STAGE(bufoff, gbase, voff) do { _Pragma("unroll") for (int _i = 0; _i < 2; ++_i) \
;         __builtin_amdgcn_global_load_lds((const unsigned*)((const char*)(gbase) + (voff)[_i]), (PG8_LAS unsigned*)(lds + (bufoff) + ldsw + _i * 8192), 16, 0, 0); } while (0)
; #define PG8_LDA(dst, b, h) do { _Pragma("unroll") for (int m = 0; m < 4; ++m) _Pragma("unroll") for (int k = 0; k < 2; ++k) dst[m][k] = *(const PG8_LAS bf16x8*)(lds + PG8_SA(b, h) + aoff + m * 2048 + k * 1024); } while (0)
; #define PG8_LDB(dst, b, h) do { _Pragma("unroll") for (int n = 0; n < 2; ++n) _Pragma("unroll") for (int k = 0; k < 2; ++k) dst[n][k] = *(const PG8_LAS bf16x8*)(lds + PG8_SB(b, h) + boff + n * 2048 + k * 1024); } while (0)
; #define PG8_MMA(ai, bj, At, Bt) do { __builtin_amdgcn_s_setprio(3); _Pragma("unroll") for (int m = 0; m < 4; ++m) _Pragma("unroll") for (int n = 0; n < 2; ++n) _Pragma("unroll") for (int k = 0; k < 2; ++k) \
;         acc[ai][bj][m][n] = __builtin_amdgcn_mfma_f32_16x16x32_bf16(Bt[n][k], At[m][k], acc[ai][bj][m][n], 0, 0, 0); __builtin_amdgcn_s_setprio(0); } while (0)
; #define PG8_WAIT_V(n) asm volatile("s_waitcnt vmcnt(" #n ")" ::: "memory")
; #define PG8_BAR __builtin_amdgcn_s_barrier()
; template <class Epi, class Sched, bool ALIGN_EPI = false, bool SP2 = false>
; __device__ __forceinline__ void gemm_phase(PG8_LAS unsigned char* lds, const Gemm g, const Sched& S, const Epi& E) {
;     ...
;         for (int t = 0; t < nt; t += 2) {
;             const bool last = (t == nt - 2);
;             const char* a1 = cA + (size_t)(t + 1) * kstep;
;             const char* a2 = last ? nA : cA + (size_t)(t + 2) * kstep; const char* b2 = last ? nB : cB + (size_t)(t + 2) * kstep;
;             const char* a3 = a2 + kstep; const char* b3 = b2 + kstep;
;             if (last && has_next) S.a_ready(nxt);
;             if constexpr (SP2) {
;             PG8_LDB(B0, 0, 0); PG8_LDB(B1, 0, 1); PG8_SCHED; PG8_LDA(At, 0, 0); PG8_STAGE(PG8_SA(1, 1), a1 + hstep, voffA);
;             PG8_WAIT_V(8); PG8_WAIT_L(0); PG8_BAR; PG8_MMA(0, 0, At, B0); PG8_MMA(0, 1, At, B1); PG8_BAR; PG8_SCHED;
;             PG8_LDA(At, 0, 1); PG8_STAGE(PG8_SB(0, 0), b2, voffB); PG8_STAGE(PG8_SB(0, 1), b2 + hstep, voffB); PG8_STAGE(PG8_SA(0, 0), a2, voffA);
;             PG8_WAIT_V(8); PG8_WAIT_L(0); PG8_BAR; PG8_MMA(1, 0, At, B0); PG8_MMA(1, 1, At, B1); PG8_BAR; PG8_SCHED;
.LBB0_677:
	ds_read_b128 v[132:135], v168
	ds_read_b128 v[136:139], v168 offset:1024
	ds_read_b128 v[158:161], v168 offset:2048
	ds_read_b128 v[162:165], v168 offset:3072
	ds_read_b128 v[172:175], v169
	ds_read_b128 v[176:179], v169 offset:1024
	ds_read_b128 v[180:183], v169 offset:2048
	ds_read_b128 v[184:187], v169 offset:3072
	s_add_i32 s74, s48, 2
	s_add_u32 s75, s6, 0x80
	s_addc_u32 s49, s7, 0
	s_cmp_eq_u32 s73, s48
	s_cselect_b32 s48, s44, s75
	s_cselect_b32 s49, s45, s49
	s_cselect_b32 s77, s47, s51
	s_cselect_b32 s76, s46, s50
	v_lshl_add_u64 v[74:75], s[6:7], 0, v[150:151]
	s_add_i32 m0, s54, 0xc000
	ds_read_b128 v[188:191], v170
	ds_read_b128 v[192:195], v170 offset:1024
	ds_read_b128 v[196:199], v170 offset:2048
	ds_read_b128 v[200:203], v170 offset:3072
	ds_read_b128 v[204:207], v170 offset:4096
	ds_read_b128 v[208:211], v170 offset:5120
	ds_read_b128 v[212:215], v170 offset:6144
	ds_read_b128 v[216:219], v170 offset:7168
	global_load_lds_dwordx4 v[74:75], off
	v_lshl_add_u64 v[74:75], s[6:7], 0, v[152:153]
	s_add_i32 m0, s54, 0xe000
	s_nop 0
	global_load_lds_dwordx4 v[74:75], off
	s_waitcnt vmcnt(8)
	s_waitcnt lgkmcnt(0)
	s_barrier
	s_waitcnt lgkmcnt(0)
	v_mfma_f32_16x16x32_bf16 v[128:131], v[132:135], v[188:191], v[128:131]
	v_mfma_f32_16x16x32_bf16 v[124:127], v[158:161], v[188:191], v[124:127]
	s_setprio 3
	v_mfma_f32_16x16x32_bf16 v[120:123], v[132:135], v[196:199], v[120:123]
	v_mfma_f32_16x16x32_bf16 v[116:119], v[158:161], v[196:199], v[116:119]
	v_mfma_f32_16x16x32_bf16 v[112:115], v[132:135], v[204:207], v[112:115]
	v_mfma_f32_16x16x32_bf16 v[108:111], v[158:161], v[204:207], v[108:111]
	v_mfma_f32_16x16x32_bf16 v[104:107], v[132:135], v[212:215], v[104:107]
	v_mfma_f32_16x16x32_bf16 v[100:103], v[158:161], v[212:215], v[100:103]
	v_mfma_f32_16x16x32_bf16 v[128:131], v[136:139], v[192:195], v[128:131]
	v_mfma_f32_16x16x32_bf16 v[124:127], v[162:165], v[192:195], v[124:127]
	v_mfma_f32_16x16x32_bf16 v[120:123], v[136:139], v[200:203], v[120:123]
	v_mfma_f32_16x16x32_bf16 v[116:119], v[162:165], v[200:203], v[116:119]
	v_mfma_f32_16x16x32_bf16 v[112:115], v[136:139], v[208:211], v[112:115]
	v_mfma_f32_16x16x32_bf16 v[108:111], v[162:165], v[208:211], v[108:111]
	v_mfma_f32_16x16x32_bf16 v[104:107], v[136:139], v[216:219], v[104:107]
	v_mfma_f32_16x16x32_bf16 v[100:103], v[162:165], v[216:219], v[100:103]
	s_setprio 0
	s_setprio 3
	v_mfma_f32_16x16x32_bf16 v[62:65], v[172:175], v[188:191], v[62:65]
	v_mfma_f32_16x16x32_bf16 v[58:61], v[180:183], v[188:191], v[58:61]
	v_mfma_f32_16x16x32_bf16 v[54:57], v[172:175], v[196:199], v[54:57]
	v_mfma_f32_16x16x32_bf16 v[50:53], v[180:183], v[196:199], v[50:53]
	v_mfma_f32_16x16x32_bf16 v[46:49], v[172:175], v[204:207], v[46:49]
	v_mfma_f32_16x16x32_bf16 v[42:45], v[180:183], v[204:207], v[42:45]
	v_mfma_f32_16x16x32_bf16 v[38:41], v[172:175], v[212:215], v[38:41]
	v_mfma_f32_16x16x32_bf16 v[34:37], v[180:183], v[212:215], v[34:37]
	v_mfma_f32_16x16x32_bf16 v[62:65], v[176:179], v[192:195], v[62:65]
	v_mfma_f32_16x16x32_bf16 v[58:61], v[184:187], v[192:195], v[58:61]
	v_mfma_f32_16x16x32_bf16 v[54:57], v[176:179], v[200:203], v[54:57]
	v_mfma_f32_16x16x32_bf16 v[50:53], v[184:187], v[200:203], v[50:53]
	v_mfma_f32_16x16x32_bf16 v[46:49], v[176:179], v[208:211], v[46:49]
	v_mfma_f32_16x16x32_bf16 v[42:45], v[184:187], v[208:211], v[42:45]
	s_barrier
	v_mfma_f32_16x16x32_bf16 v[38:41], v[176:179], v[216:219], v[38:41]
	v_mfma_f32_16x16x32_bf16 v[34:37], v[184:187], v[216:219], v[34:37]
	s_setprio 0
	s_add_i32 s75, s63, s43
	v_lshl_add_u64 v[220:221], s[76:77], 0, v[146:147]
	s_mov_b32 m0, s75
	ds_read_b128 v[188:191], v170 offset:16384
	ds_read_b128 v[192:195], v170 offset:17408
	ds_read_b128 v[196:199], v170 offset:18432
	ds_read_b128 v[200:203], v170 offset:19456
	ds_read_b128 v[204:207], v170 offset:20480
	ds_read_b128 v[208:211], v170 offset:21504
	ds_read_b128 v[212:215], v170 offset:22528
	ds_read_b128 v[216:219], v170 offset:23552
	global_load_lds_dwordx4 v[220:221], off
	s_add_i32 m0, s75, 0x2000
	v_lshl_add_u64 v[222:223], s[76:77], 0, v[142:143]
	s_add_u32 s76, s76, s14
	s_addc_u32 s77, s77, s15
	s_add_i32 s75, s64, s43
	global_load_lds_dwordx4 v[222:223], off
	v_lshl_add_u64 v[224:225], s[76:77], 0, v[146:147]
	s_mov_b32 m0, s75
	v_lshl_add_u64 v[226:227], s[76:77], 0, v[142:143]
	global_load_lds_dwordx4 v[224:225], off
	s_add_i32 m0, s75, 0x2000
	v_lshl_add_u64 v[228:229], s[48:49], 0, v[148:149]
	global_load_lds_dwordx4 v[226:227], off
	s_mov_b32 m0, s54
	v_lshl_add_u64 v[230:231], s[48:49], 0, v[144:145]
	global_load_lds_dwordx4 v[228:229], off
	s_mov_b32 m0, s55
	s_nop 0
	global_load_lds_dwordx4 v[230:231], off
	s_waitcnt vmcnt(8)
	s_waitcnt lgkmcnt(0)
	s_barrier
; #define PG8_STAGE(bufoff, gbase, voff) do { _Pragma("unroll") for (int _i = 0; _i < 2; ++_i) \
;         __builtin_amdgcn_global_load_lds((const unsigned*)((const char*)(gbase) + (voff)[_i]), (PG8_LAS unsigned*)(lds + (bufoff) + ldsw + _i * 8192), 16, 0, 0); } while (0)
; #define PG8_LDA(dst, b, h) do { _Pragma("unroll") for (int m = 0; m < 4; ++m) _Pragma("unroll") for (int k = 0; k < 2; ++k) dst[m][k] = *(const PG8_LAS bf16x8*)(lds + PG8_SA(b, h) + aoff + m * 2048 + k * 1024); } while (0)
; #define PG8_LDB(dst, b, h) do { _Pragma("unroll") for (int n = 0; n < 2; ++n) _Pragma("unroll") for (int k = 0; k < 2; ++k) dst[n][k] = *(const PG8_LAS bf16x8*)(lds + PG8_SB(b, h) + boff + n * 2048 + k * 1024); } while (0)
; #define PG8_MMA(ai, bj, At, Bt) do { __builtin_amdgcn_s_setprio(3); _Pragma("unroll") for (int m = 0; m < 4; ++m) _Pragma("unroll") for (int n = 0; n < 2; ++n) _Pragma("unroll") for (int k = 0; k < 2; ++k) \
;         acc[ai][bj][m][n] = __builtin_amdgcn_mfma_f32_16x16x32_bf16(Bt[n][k], At[m][k], acc[ai][bj][m][n], 0, 0, 0); __builtin_amdgcn_s_setprio(0); } while (0)
; #define PG8_WAIT_V(n) asm volatile("s_waitcnt vmcnt(" #n ")" ::: "memory")
; #define PG8_WAIT_L(n) asm volatile("s_waitcnt lgkmcnt(" #n ")" ::: "memory")
; #define PG8_BAR __builtin_amdgcn_s_barrier()
; #define PG8_SCHED __builtin_amdgcn_sched_barrier(0)
; template <class Epi, class Sched, bool ALIGN_EPI = false, bool SP2 = false>
; __device__ __forceinline__ void gemm_phase(PG8_LAS unsigned char* lds, const Gemm g, const Sched& S, const Epi& E) {
;     ...
;             PG8_WAIT_V(8); PG8_WAIT_L(0); PG8_BAR; PG8_MMA(1, 0, At, B0); PG8_MMA(1, 1, At, B1); PG8_BAR; PG8_SCHED;
;             PG8_LDB(B0, 1, 0); PG8_LDB(B1, 1, 1); PG8_SCHED; PG8_LDA(At, 1, 0); PG8_STAGE(PG8_SA(0, 1), a2 + hstep, voffA);
;             PG8_WAIT_V(8); PG8_WAIT_L(0); PG8_BAR; PG8_MMA(0, 0, At, B0); PG8_MMA(0, 1, At, B1); PG8_BAR; PG8_SCHED;
	s_waitcnt lgkmcnt(0)
	v_mfma_f32_16x16x32_bf16 v[96:99], v[132:135], v[188:191], v[96:99]
	v_mfma_f32_16x16x32_bf16 v[92:95], v[158:161], v[188:191], v[92:95]
	s_setprio 3
	v_mfma_f32_16x16x32_bf16 v[88:91], v[132:135], v[196:199], v[88:91]
	v_mfma_f32_16x16x32_bf16 v[84:87], v[158:161], v[196:199], v[84:87]
	v_mfma_f32_16x16x32_bf16 v[80:83], v[132:135], v[204:207], v[80:83]
	v_mfma_f32_16x16x32_bf16 v[74:77], v[158:161], v[204:207], v[76:79]
	v_mfma_f32_16x16x32_bf16 v[70:73], v[132:135], v[212:215], v[70:73]
	v_mfma_f32_16x16x32_bf16 v[66:69], v[158:161], v[212:215], v[66:69]
	v_mfma_f32_16x16x32_bf16 v[96:99], v[136:139], v[192:195], v[96:99]
	v_mfma_f32_16x16x32_bf16 v[92:95], v[162:165], v[192:195], v[92:95]
	v_mfma_f32_16x16x32_bf16 v[88:91], v[136:139], v[200:203], v[88:91]
	v_mfma_f32_16x16x32_bf16 v[84:87], v[162:165], v[200:203], v[84:87]
	v_mfma_f32_16x16x32_bf16 v[80:83], v[136:139], v[208:211], v[80:83]
	v_mfma_f32_16x16x32_bf16 v[74:77], v[162:165], v[208:211], v[74:77]
	v_mfma_f32_16x16x32_bf16 v[70:73], v[136:139], v[216:219], v[70:73]
	v_mfma_f32_16x16x32_bf16 v[66:69], v[162:165], v[216:219], v[66:69]
	s_setprio 0
	s_setprio 3
	v_mfma_f32_16x16x32_bf16 v[30:33], v[172:175], v[188:191], v[30:33]
	v_mfma_f32_16x16x32_bf16 v[26:29], v[180:183], v[188:191], v[26:29]
	v_mfma_f32_16x16x32_bf16 v[22:25], v[172:175], v[196:199], v[22:25]
	v_mfma_f32_16x16x32_bf16 v[18:21], v[180:183], v[196:199], v[18:21]
	v_mfma_f32_16x16x32_bf16 v[14:17], v[172:175], v[204:207], v[14:17]
	v_mfma_f32_16x16x32_bf16 v[10:13], v[180:183], v[204:207], v[10:13]
	v_mfma_f32_16x16x32_bf16 v[6:9], v[172:175], v[212:215], v[6:9]
	v_mfma_f32_16x16x32_bf16 v[2:5], v[180:183], v[212:215], v[2:5]
	v_mfma_f32_16x16x32_bf16 v[30:33], v[176:179], v[192:195], v[30:33]
	v_mfma_f32_16x16x32_bf16 v[26:29], v[184:187], v[192:195], v[26:29]
	v_mfma_f32_16x16x32_bf16 v[22:25], v[176:179], v[200:203], v[22:25]
	v_mfma_f32_16x16x32_bf16 v[18:21], v[184:187], v[200:203], v[18:21]
	v_mfma_f32_16x16x32_bf16 v[14:17], v[176:179], v[208:211], v[14:17]
	v_mfma_f32_16x16x32_bf16 v[10:13], v[184:187], v[208:211], v[10:13]
	s_barrier
	v_mfma_f32_16x16x32_bf16 v[6:9], v[176:179], v[216:219], v[6:9]
	v_mfma_f32_16x16x32_bf16 v[2:5], v[184:187], v[216:219], v[2:5]
	s_setprio 0
	s_add_i32 s75, 0, 0x18000
	v_add_u32_e32 v78, s75, v141
	s_add_i32 s76, 0, 0x1c000
	ds_read_b128 v[132:135], v78
	ds_read_b128 v[136:139], v78 offset:1024
	ds_read_b128 v[158:161], v78 offset:2048
	ds_read_b128 v[162:165], v78 offset:3072
	v_add_u32_e32 v78, s76, v141
	ds_read_b128 v[172:175], v78
	ds_read_b128 v[176:179], v78 offset:1024
	ds_read_b128 v[180:183], v78 offset:2048
	ds_read_b128 v[184:187], v78 offset:3072
	s_add_u32 s48, s48, s14
	s_addc_u32 s49, s49, s15
	s_mov_b32 m0, s56
	v_lshl_add_u64 v[78:79], s[48:49], 0, v[148:149]
	ds_read_b128 v[188:191], v170 offset:32768
	ds_read_b128 v[192:195], v170 offset:33792
	ds_read_b128 v[196:199], v170 offset:34816
	ds_read_b128 v[200:203], v170 offset:35840
	ds_read_b128 v[204:207], v170 offset:36864
	ds_read_b128 v[208:211], v170 offset:37888
	ds_read_b128 v[212:215], v170 offset:38912
	ds_read_b128 v[216:219], v170 offset:39936
	global_load_lds_dwordx4 v[78:79], off
	v_lshl_add_u64 v[78:79], s[48:49], 0, v[144:145]
	s_mov_b32 m0, s57
	s_nop 0
	global_load_lds_dwordx4 v[78:79], off
	s_waitcnt vmcnt(8)
	s_waitcnt lgkmcnt(0)
	s_barrier
	s_waitcnt lgkmcnt(0)
	v_mfma_f32_16x16x32_bf16 v[128:131], v[132:135], v[188:191], v[128:131]
	v_mfma_f32_16x16x32_bf16 v[124:127], v[158:161], v[188:191], v[124:127]
	s_setprio 3
	v_mfma_f32_16x16x32_bf16 v[120:123], v[132:135], v[196:199], v[120:123]
	v_mfma_f32_16x16x32_bf16 v[116:119], v[158:161], v[196:199], v[116:119]
	v_mfma_f32_16x16x32_bf16 v[112:115], v[132:135], v[204:207], v[112:115]
	v_mfma_f32_16x16x32_bf16 v[108:111], v[158:161], v[204:207], v[108:111]
	v_mfma_f32_16x16x32_bf16 v[104:107], v[132:135], v[212:215], v[104:107]
	v_mfma_f32_16x16x32_bf16 v[100:103], v[158:161], v[212:215], v[100:103]
	v_mfma_f32_16x16x32_bf16 v[128:131], v[136:139], v[192:195], v[128:131]
	v_mfma_f32_16x16x32_bf16 v[124:127], v[162:165], v[192:195], v[124:127]
	v_mfma_f32_16x16x32_bf16 v[120:123], v[136:139], v[200:203], v[120:123]
	v_mfma_f32_16x16x32_bf16 v[116:119], v[162:165], v[200:203], v[116:119]
	v_mfma_f32_16x16x32_bf16 v[112:115], v[136:139], v[208:211], v[112:115]
	v_mfma_f32_16x16x32_bf16 v[108:111], v[162:165], v[208:211], v[108:111]
	v_mfma_f32_16x16x32_bf16 v[104:107], v[136:139], v[216:219], v[104:107]
	v_mfma_f32_16x16x32_bf16 v[100:103], v[162:165], v[216:219], v[100:103]
	s_setprio 0
	s_setprio 3
	v_mfma_f32_16x16x32_bf16 v[62:65], v[172:175], v[188:191], v[62:65]
	v_mfma_f32_16x16x32_bf16 v[58:61], v[180:183], v[188:191], v[58:61]
	v_mfma_f32_16x16x32_bf16 v[54:57], v[172:175], v[196:199], v[54:57]
	v_mfma_f32_16x16x32_bf16 v[50:53], v[180:183], v[196:199], v[50:53]
	v_mfma_f32_16x16x32_bf16 v[46:49], v[172:175], v[204:207], v[46:49]
	v_mfma_f32_16x16x32_bf16 v[42:45], v[180:183], v[204:207], v[42:45]
	v_mfma_f32_16x16x32_bf16 v[38:41], v[172:175], v[212:215], v[38:41]
	v_mfma_f32_16x16x32_bf16 v[34:37], v[180:183], v[212:215], v[34:37]
	v_mfma_f32_16x16x32_bf16 v[62:65], v[176:179], v[192:195], v[62:65]
	v_mfma_f32_16x16x32_bf16 v[58:61], v[184:187], v[192:195], v[58:61]
	v_mfma_f32_16x16x32_bf16 v[54:57], v[176:179], v[200:203], v[54:57]
	v_mfma_f32_16x16x32_bf16 v[50:53], v[184:187], v[200:203], v[50:53]
	v_mfma_f32_16x16x32_bf16 v[46:49], v[176:179], v[208:211], v[46:49]
	v_mfma_f32_16x16x32_bf16 v[42:45], v[184:187], v[208:211], v[42:45]
	s_barrier
; #define PG8_STAGE(bufoff, gbase, voff) do { _Pragma("unroll") for (int _i = 0; _i < 2; ++_i) \
;         __builtin_amdgcn_global_load_lds((const unsigned*)((const char*)(gbase) + (voff)[_i]), (PG8_LAS unsigned*)(lds + (bufoff) + ldsw + _i * 8192), 16, 0, 0); } while (0)
; #define PG8_LDA(dst, b, h) do { _Pragma("unroll") for (int m = 0; m < 4; ++m) _Pragma("unroll") for (int k = 0; k < 2; ++k) dst[m][k] = *(const PG8_LAS bf16x8*)(lds + PG8_SA(b, h) + aoff + m * 2048 + k * 1024); } while (0)
; #define PG8_MMA(ai, bj, At, Bt) do { __builtin_amdgcn_s_setprio(3); _Pragma("unroll") for (int m = 0; m < 4; ++m) _Pragma("unroll") for (int n = 0; n < 2; ++n) _Pragma("unroll") for (int k = 0; k < 2; ++k) \
;         acc[ai][bj][m][n] = __builtin_amdgcn_mfma_f32_16x16x32_bf16(Bt[n][k], At[m][k], acc[ai][bj][m][n], 0, 0, 0); __builtin_amdgcn_s_setprio(0); } while (0)
; #define PG8_WAIT_V(n) asm volatile("s_waitcnt vmcnt(" #n ")" ::: "memory")
; #define PG8_WAIT_L(n) asm volatile("s_waitcnt lgkmcnt(" #n ")" ::: "memory")
; #define PG8_BAR __builtin_amdgcn_s_barrier()
; #define PG8_SCHED __builtin_amdgcn_sched_barrier(0)
; template <class Epi, class Sched, bool ALIGN_EPI = false, bool SP2 = false>
; __device__ __forceinline__ void gemm_phase(PG8_LAS unsigned char* lds, const Gemm g, const Sched& S, const Epi& E) {
;     ...
;             PG8_LDA(At, 1, 1); PG8_STAGE(PG8_SB(1, 0), b3, voffB); PG8_STAGE(PG8_SB(1, 1), b3 + hstep, voffB); PG8_STAGE(PG8_SA(1, 0), a3, voffA);
;             PG8_WAIT_V(8); PG8_WAIT_L(0); PG8_BAR; PG8_MMA(1, 0, At, B0); PG8_MMA(1, 1, At, B1); PG8_BAR; PG8_SCHED;
;     ...
;         }
;         if constexpr (ALIGN_EPI) { if (wr == 0) PG8_BAR; }
	v_mfma_f32_16x16x32_bf16 v[38:41], v[176:179], v[216:219], v[38:41]
	v_mfma_f32_16x16x32_bf16 v[34:37], v[184:187], v[216:219], v[34:37]
	s_setprio 0
	s_add_i32 s48, s75, s43
	v_lshl_add_u64 v[78:79], v[220:221], 0, s[28:29]
	s_mov_b32 m0, s48
	ds_read_b128 v[188:191], v170 offset:49152
	ds_read_b128 v[192:195], v170 offset:50176
	ds_read_b128 v[196:199], v170 offset:51200
	ds_read_b128 v[200:203], v170 offset:52224
	ds_read_b128 v[204:207], v170 offset:53248
	ds_read_b128 v[208:211], v170 offset:54272
	ds_read_b128 v[212:215], v170 offset:55296
	ds_read_b128 v[216:219], v170 offset:56320
	global_load_lds_dwordx4 v[78:79], off
	v_lshl_add_u64 v[78:79], v[222:223], 0, s[28:29]
	s_add_i32 m0, s48, 0x2000
	s_add_i32 s48, s76, s43
	global_load_lds_dwordx4 v[78:79], off
	v_lshl_add_u64 v[78:79], v[224:225], 0, s[28:29]
	s_mov_b32 m0, s48
	s_nop 0
	global_load_lds_dwordx4 v[78:79], off
	v_lshl_add_u64 v[78:79], v[226:227], 0, s[28:29]
	s_add_i32 m0, s48, 0x2000
	s_nop 0
	global_load_lds_dwordx4 v[78:79], off
	v_lshl_add_u64 v[78:79], v[228:229], 0, s[28:29]
	s_mov_b32 m0, s60
	s_nop 0
	global_load_lds_dwordx4 v[78:79], off
	v_lshl_add_u64 v[78:79], v[230:231], 0, s[28:29]
	s_mov_b32 m0, s61
	s_nop 0
	global_load_lds_dwordx4 v[78:79], off
	s_waitcnt vmcnt(8)
	s_waitcnt lgkmcnt(0)
	s_barrier
	s_waitcnt lgkmcnt(0)
	v_mfma_f32_16x16x32_bf16 v[96:99], v[132:135], v[188:191], v[96:99]
	v_mfma_f32_16x16x32_bf16 v[92:95], v[158:161], v[188:191], v[92:95]
	s_setprio 3
	v_mfma_f32_16x16x32_bf16 v[88:91], v[132:135], v[196:199], v[88:91]
	v_mfma_f32_16x16x32_bf16 v[84:87], v[158:161], v[196:199], v[84:87]
	v_mfma_f32_16x16x32_bf16 v[78:81], v[132:135], v[204:207], v[80:83]
	v_mfma_f32_16x16x32_bf16 v[74:77], v[158:161], v[204:207], v[74:77]
	v_mfma_f32_16x16x32_bf16 v[70:73], v[132:135], v[212:215], v[70:73]
	v_mfma_f32_16x16x32_bf16 v[66:69], v[158:161], v[212:215], v[66:69]
	v_mfma_f32_16x16x32_bf16 v[96:99], v[136:139], v[192:195], v[96:99]
	v_mfma_f32_16x16x32_bf16 v[92:95], v[162:165], v[192:195], v[92:95]
	v_mfma_f32_16x16x32_bf16 v[88:91], v[136:139], v[200:203], v[88:91]
	v_mfma_f32_16x16x32_bf16 v[84:87], v[162:165], v[200:203], v[84:87]
	v_mfma_f32_16x16x32_bf16 v[80:83], v[136:139], v[208:211], v[78:81]
	v_mfma_f32_16x16x32_bf16 v[76:79], v[162:165], v[208:211], v[74:77]
	v_mfma_f32_16x16x32_bf16 v[70:73], v[136:139], v[216:219], v[70:73]
	v_mfma_f32_16x16x32_bf16 v[66:69], v[162:165], v[216:219], v[66:69]
	s_setprio 0
	s_setprio 3
	v_mfma_f32_16x16x32_bf16 v[30:33], v[172:175], v[188:191], v[30:33]
	v_mfma_f32_16x16x32_bf16 v[26:29], v[180:183], v[188:191], v[26:29]
	v_mfma_f32_16x16x32_bf16 v[22:25], v[172:175], v[196:199], v[22:25]
	v_mfma_f32_16x16x32_bf16 v[18:21], v[180:183], v[196:199], v[18:21]
	v_mfma_f32_16x16x32_bf16 v[14:17], v[172:175], v[204:207], v[14:17]
	v_mfma_f32_16x16x32_bf16 v[10:13], v[180:183], v[204:207], v[10:13]
	v_mfma_f32_16x16x32_bf16 v[6:9], v[172:175], v[212:215], v[6:9]
	v_mfma_f32_16x16x32_bf16 v[2:5], v[180:183], v[212:215], v[2:5]
	v_mfma_f32_16x16x32_bf16 v[30:33], v[176:179], v[192:195], v[30:33]
	v_mfma_f32_16x16x32_bf16 v[26:29], v[184:187], v[192:195], v[26:29]
	v_mfma_f32_16x16x32_bf16 v[22:25], v[176:179], v[200:203], v[22:25]
	v_mfma_f32_16x16x32_bf16 v[18:21], v[184:187], v[200:203], v[18:21]
	v_mfma_f32_16x16x32_bf16 v[14:17], v[176:179], v[208:211], v[14:17]
	v_mfma_f32_16x16x32_bf16 v[10:13], v[184:187], v[208:211], v[10:13]
	s_barrier
	v_mfma_f32_16x16x32_bf16 v[6:9], v[176:179], v[216:219], v[6:9]
	v_mfma_f32_16x16x32_bf16 v[2:5], v[184:187], v[216:219], v[2:5]
	s_setprio 0
	s_add_u32 s6, s6, 0x100
	s_addc_u32 s7, s7, 0
	s_add_u32 s50, s50, 0x100
	s_addc_u32 s51, s51, 0
	s_cmp_ge_u32 s74, s72
	s_mov_b32 s48, s74
	s_cbranch_scc0 .LBB0_677
	s_and_b64 vcc, exec, s[30:31]
	s_cbranch_vccz .LBB0_680
	s_barrier

; #define PG8_STAGE(bufoff, gbase, voff) do { _Pragma("unroll") for (int _i = 0; _i < 2; ++_i) \
;         __builtin_amdgcn_global_load_lds((const unsigned*)((const char*)(gbase) + (voff)[_i]), (PG8_LAS unsigned*)(lds + (bufoff) + ldsw + _i * 8192), 16, 0, 0); } while (0)
; #define PG8_LDA(dst, b, h) do { _Pragma("unroll") for (int m = 0; m < 4; ++m) _Pragma("unroll") for (int k = 0; k < 2; ++k) dst[m][k] = *(const PG8_LAS bf16x8*)(lds + PG8_SA(b, h) + aoff + m * 2048 + k * 1024); } while (0)
; #define PG8_LDB(dst, b, h) do { _Pragma("unroll") for (int n = 0; n < 2; ++n) _Pragma("unroll") for (int k = 0; k < 2; ++k) dst[n][k] = *(const PG8_LAS bf16x8*)(lds + PG8_SB(b, h) + boff + n * 2048 + k * 1024); } while (0)
; #define PG8_MMA(ai, bj, At, Bt) do { __builtin_amdgcn_s_setprio(3); _Pragma("unroll") for (int m = 0; m < 4; ++m) _Pragma("unroll") for (int n = 0; n < 2; ++n) _Pragma("unroll") for (int k = 0; k < 2; ++k) \
;         acc[ai][bj][m][n] = __builtin_amdgcn_mfma_f32_16x16x32_bf16(Bt[n][k], At[m][k], acc[ai][bj][m][n], 0, 0, 0); __builtin_amdgcn_s_setprio(0); } while (0)
; #define PG8_WAIT_V(n) asm volatile("s_waitcnt vmcnt(" #n ")" ::: "memory")
; #define PG8_BAR __builtin_amdgcn_s_barrier()
; template <class Epi, class Sched, bool ALIGN_EPI = false, bool SP2 = false>
; __device__ __forceinline__ void gemm_phase(PG8_LAS unsigned char* lds, const Gemm g, const Sched& S, const Epi& E) {
;     ...
;         for (int t = 0; t < nt; t += 2) {
;             const bool last = (t == nt - 2);
;             const char* a1 = cA + (size_t)(t + 1) * kstep;
;             const char* a2 = last ? nA : cA + (size_t)(t + 2) * kstep; const char* b2 = last ? nB : cB + (size_t)(t + 2) * kstep;
;             const char* a3 = a2 + kstep; const char* b3 = b2 + kstep;
;             if (last && has_next) S.a_ready(nxt);
;             if constexpr (SP2) {
;             PG8_LDB(B0, 0, 0); PG8_LDB(B1, 0, 1); PG8_SCHED; PG8_LDA(At, 0, 0); PG8_STAGE(PG8_SA(1, 1), a1 + hstep, voffA);
;             PG8_WAIT_V(8); PG8_WAIT_L(0); PG8_BAR; PG8_MMA(0, 0, At, B0); PG8_MMA(0, 1, At, B1); PG8_BAR; PG8_SCHED;
;             PG8_LDA(At, 0, 1); PG8_STAGE(PG8_SB(0, 0), b2, voffB); PG8_STAGE(PG8_SB(0, 1), b2 + hstep, voffB); PG8_STAGE(PG8_SA(0, 0), a2, voffA);
;             PG8_WAIT_V(8); PG8_WAIT_L(0); PG8_BAR; PG8_MMA(1, 0, At, B0); PG8_MMA(1, 1, At, B1); PG8_BAR; PG8_SCHED;
.LBB0_1013:
	ds_read_b128 v[148:151], v157
	ds_read_b128 v[152:155], v157 offset:1024
	ds_read_b128 v[160:163], v157 offset:2048
	ds_read_b128 v[168:171], v157 offset:3072
	ds_read_b128 v[172:175], v158
	ds_read_b128 v[176:179], v158 offset:1024
	ds_read_b128 v[180:183], v158 offset:2048
	ds_read_b128 v[184:187], v158 offset:3072
	s_add_i32 s79, s55, 2
	s_add_u32 s10, s56, 0xfff80080
	s_addc_u32 s11, s57, -1
	s_cmp_eq_u32 s9, s55
	s_cselect_b32 s61, s49, s11
	s_cselect_b32 s60, s48, s10
	s_cselect_b32 s59, s53, s51
	s_cselect_b32 s58, s52, s47
	v_lshl_add_u64 v[164:165], s[56:57], 0, v[138:139]
	s_add_i32 m0, s43, 0xc000
	ds_read_b128 v[188:191], v159
	ds_read_b128 v[192:195], v159 offset:1024
	ds_read_b128 v[196:199], v159 offset:2048
	ds_read_b128 v[200:203], v159 offset:3072
	ds_read_b128 v[204:207], v159 offset:4096
	ds_read_b128 v[208:211], v159 offset:5120
	ds_read_b128 v[212:215], v159 offset:6144
	ds_read_b128 v[216:219], v159 offset:7168
	global_load_lds_dwordx4 v[164:165], off
	v_lshl_add_u64 v[164:165], s[56:57], 0, v[142:143]
	s_add_i32 m0, s43, 0xe000
	s_nop 0
	global_load_lds_dwordx4 v[164:165], off
	s_waitcnt vmcnt(8)
	s_waitcnt lgkmcnt(0)
	s_barrier
	s_waitcnt lgkmcnt(0)
	v_mfma_f32_16x16x32_bf16 v[126:129], v[148:151], v[188:191], v[126:129]
	v_mfma_f32_16x16x32_bf16 v[122:125], v[160:163], v[188:191], v[122:125]
	s_setprio 3
	v_mfma_f32_16x16x32_bf16 v[114:117], v[148:151], v[196:199], v[114:117]
	v_mfma_f32_16x16x32_bf16 v[106:109], v[160:163], v[196:199], v[106:109]
	v_mfma_f32_16x16x32_bf16 v[98:101], v[148:151], v[204:207], v[98:101]
	v_mfma_f32_16x16x32_bf16 v[90:93], v[160:163], v[204:207], v[90:93]
	v_mfma_f32_16x16x32_bf16 v[82:85], v[148:151], v[212:215], v[82:85]
	v_mfma_f32_16x16x32_bf16 v[74:77], v[160:163], v[212:215], v[74:77]
	v_mfma_f32_16x16x32_bf16 v[126:129], v[152:155], v[192:195], v[126:129]
	v_mfma_f32_16x16x32_bf16 v[122:125], v[168:171], v[192:195], v[122:125]
	v_mfma_f32_16x16x32_bf16 v[114:117], v[152:155], v[200:203], v[114:117]
	v_mfma_f32_16x16x32_bf16 v[106:109], v[168:171], v[200:203], v[106:109]
	v_mfma_f32_16x16x32_bf16 v[98:101], v[152:155], v[208:211], v[98:101]
	v_mfma_f32_16x16x32_bf16 v[90:93], v[168:171], v[208:211], v[90:93]
	v_mfma_f32_16x16x32_bf16 v[82:85], v[152:155], v[216:219], v[82:85]
	v_mfma_f32_16x16x32_bf16 v[74:77], v[168:171], v[216:219], v[74:77]
	s_setprio 0
	s_setprio 3
	v_mfma_f32_16x16x32_bf16 v[118:121], v[172:175], v[188:191], v[118:121]
	v_mfma_f32_16x16x32_bf16 v[110:113], v[180:183], v[188:191], v[110:113]
	v_mfma_f32_16x16x32_bf16 v[102:105], v[172:175], v[196:199], v[102:105]
	v_mfma_f32_16x16x32_bf16 v[94:97], v[180:183], v[196:199], v[94:97]
	v_mfma_f32_16x16x32_bf16 v[86:89], v[172:175], v[204:207], v[86:89]
	v_mfma_f32_16x16x32_bf16 v[78:81], v[180:183], v[204:207], v[78:81]
	v_mfma_f32_16x16x32_bf16 v[70:73], v[172:175], v[212:215], v[70:73]
	v_mfma_f32_16x16x32_bf16 v[66:69], v[180:183], v[212:215], v[66:69]
	v_mfma_f32_16x16x32_bf16 v[118:121], v[176:179], v[192:195], v[118:121]
	v_mfma_f32_16x16x32_bf16 v[110:113], v[184:187], v[192:195], v[110:113]
	v_mfma_f32_16x16x32_bf16 v[102:105], v[176:179], v[200:203], v[102:105]
	v_mfma_f32_16x16x32_bf16 v[94:97], v[184:187], v[200:203], v[94:97]
	v_mfma_f32_16x16x32_bf16 v[86:89], v[176:179], v[208:211], v[86:89]
	v_mfma_f32_16x16x32_bf16 v[78:81], v[184:187], v[208:211], v[78:81]
	s_barrier
	v_mfma_f32_16x16x32_bf16 v[70:73], v[176:179], v[216:219], v[70:73]
	v_mfma_f32_16x16x32_bf16 v[66:69], v[184:187], v[216:219], v[66:69]
	s_setprio 0
	s_add_i32 s10, s72, s42
	v_lshl_add_u64 v[164:165], s[58:59], 0, v[132:133]
	s_mov_b32 m0, s10
	ds_read_b128 v[188:191], v159 offset:16384
	ds_read_b128 v[192:195], v159 offset:17408
	ds_read_b128 v[196:199], v159 offset:18432
	ds_read_b128 v[200:203], v159 offset:19456
	ds_read_b128 v[204:207], v159 offset:20480
	ds_read_b128 v[208:211], v159 offset:21504
	ds_read_b128 v[212:215], v159 offset:22528
	ds_read_b128 v[216:219], v159 offset:23552
	global_load_lds_dwordx4 v[164:165], off
	s_add_i32 m0, s10, 0x2000
	s_add_u32 s82, s58, 0x80000
	v_lshl_add_u64 v[220:221], s[58:59], 0, v[136:137]
	s_addc_u32 s83, s59, 0
	s_add_i32 s10, s73, s42
	global_load_lds_dwordx4 v[220:221], off
	v_lshl_add_u64 v[222:223], s[82:83], 0, v[132:133]
	s_mov_b32 m0, s10
	v_lshl_add_u64 v[224:225], s[60:61], 0, v[134:135]
	global_load_lds_dwordx4 v[222:223], off
	v_lshl_add_u64 v[222:223], s[82:83], 0, v[136:137]
	s_add_i32 m0, s10, 0x2000
	s_nop 0
	global_load_lds_dwordx4 v[222:223], off
	v_lshl_add_u64 v[222:223], s[60:61], 0, v[130:131]
	s_mov_b32 m0, s43
	s_nop 0
	global_load_lds_dwordx4 v[222:223], off
	s_mov_b32 m0, s62
	s_nop 0
	global_load_lds_dwordx4 v[224:225], off
	s_waitcnt vmcnt(8)
	s_waitcnt lgkmcnt(0)
	s_barrier
; #define PG8_STAGE(bufoff, gbase, voff) do { _Pragma("unroll") for (int _i = 0; _i < 2; ++_i) \
;         __builtin_amdgcn_global_load_lds((const unsigned*)((const char*)(gbase) + (voff)[_i]), (PG8_LAS unsigned*)(lds + (bufoff) + ldsw + _i * 8192), 16, 0, 0); } while (0)
; #define PG8_LDA(dst, b, h) do { _Pragma("unroll") for (int m = 0; m < 4; ++m) _Pragma("unroll") for (int k = 0; k < 2; ++k) dst[m][k] = *(const PG8_LAS bf16x8*)(lds + PG8_SA(b, h) + aoff + m * 2048 + k * 1024); } while (0)
; #define PG8_LDB(dst, b, h) do { _Pragma("unroll") for (int n = 0; n < 2; ++n) _Pragma("unroll") for (int k = 0; k < 2; ++k) dst[n][k] = *(const PG8_LAS bf16x8*)(lds + PG8_SB(b, h) + boff + n * 2048 + k * 1024); } while (0)
; #define PG8_MMA(ai, bj, At, Bt) do { __builtin_amdgcn_s_setprio(3); _Pragma("unroll") for (int m = 0; m < 4; ++m) _Pragma("unroll") for (int n = 0; n < 2; ++n) _Pragma("unroll") for (int k = 0; k < 2; ++k) \
;         acc[ai][bj][m][n] = __builtin_amdgcn_mfma_f32_16x16x32_bf16(Bt[n][k], At[m][k], acc[ai][bj][m][n], 0, 0, 0); __builtin_amdgcn_s_setprio(0); } while (0)
; #define PG8_WAIT_V(n) asm volatile("s_waitcnt vmcnt(" #n ")" ::: "memory")
; #define PG8_WAIT_L(n) asm volatile("s_waitcnt lgkmcnt(" #n ")" ::: "memory")
; #define PG8_BAR __builtin_amdgcn_s_barrier()
; #define PG8_SCHED __builtin_amdgcn_sched_barrier(0)
; template <class Epi, class Sched, bool ALIGN_EPI = false, bool SP2 = false>
; __device__ __forceinline__ void gemm_phase(PG8_LAS unsigned char* lds, const Gemm g, const Sched& S, const Epi& E) {
;     ...
;             PG8_WAIT_V(8); PG8_WAIT_L(0); PG8_BAR; PG8_MMA(1, 0, At, B0); PG8_MMA(1, 1, At, B1); PG8_BAR; PG8_SCHED;
;             PG8_LDB(B0, 1, 0); PG8_LDB(B1, 1, 1); PG8_SCHED; PG8_LDA(At, 1, 0); PG8_STAGE(PG8_SA(0, 1), a2 + hstep, voffA);
;             PG8_WAIT_V(8); PG8_WAIT_L(0); PG8_BAR; PG8_MMA(0, 0, At, B0); PG8_MMA(0, 1, At, B1); PG8_BAR; PG8_SCHED;
	s_waitcnt lgkmcnt(0)
	v_mfma_f32_16x16x32_bf16 v[62:65], v[148:151], v[188:191], v[62:65]
	v_mfma_f32_16x16x32_bf16 v[58:61], v[160:163], v[188:191], v[58:61]
	s_setprio 3
	v_mfma_f32_16x16x32_bf16 v[50:53], v[148:151], v[196:199], v[50:53]
	v_mfma_f32_16x16x32_bf16 v[42:45], v[160:163], v[196:199], v[42:45]
	v_mfma_f32_16x16x32_bf16 v[34:37], v[148:151], v[204:207], v[34:37]
	v_mfma_f32_16x16x32_bf16 v[26:29], v[160:163], v[204:207], v[26:29]
	v_mfma_f32_16x16x32_bf16 v[18:21], v[148:151], v[212:215], v[18:21]
	v_mfma_f32_16x16x32_bf16 v[10:13], v[160:163], v[212:215], v[10:13]
	v_mfma_f32_16x16x32_bf16 v[62:65], v[152:155], v[192:195], v[62:65]
	v_mfma_f32_16x16x32_bf16 v[58:61], v[168:171], v[192:195], v[58:61]
	v_mfma_f32_16x16x32_bf16 v[50:53], v[152:155], v[200:203], v[50:53]
	v_mfma_f32_16x16x32_bf16 v[42:45], v[168:171], v[200:203], v[42:45]
	v_mfma_f32_16x16x32_bf16 v[34:37], v[152:155], v[208:211], v[34:37]
	v_mfma_f32_16x16x32_bf16 v[26:29], v[168:171], v[208:211], v[26:29]
	v_mfma_f32_16x16x32_bf16 v[18:21], v[152:155], v[216:219], v[18:21]
	v_mfma_f32_16x16x32_bf16 v[10:13], v[168:171], v[216:219], v[10:13]
	s_setprio 0
	s_setprio 3
	v_mfma_f32_16x16x32_bf16 v[54:57], v[172:175], v[188:191], v[54:57]
	v_mfma_f32_16x16x32_bf16 v[46:49], v[180:183], v[188:191], v[46:49]
	v_mfma_f32_16x16x32_bf16 v[38:41], v[172:175], v[196:199], v[38:41]
	v_mfma_f32_16x16x32_bf16 v[30:33], v[180:183], v[196:199], v[30:33]
	v_mfma_f32_16x16x32_bf16 v[22:25], v[172:175], v[204:207], v[22:25]
	v_mfma_f32_16x16x32_bf16 v[14:17], v[180:183], v[204:207], v[14:17]
	v_mfma_f32_16x16x32_bf16 v[6:9], v[172:175], v[212:215], v[6:9]
	v_mfma_f32_16x16x32_bf16 v[2:5], v[180:183], v[212:215], v[2:5]
	v_mfma_f32_16x16x32_bf16 v[54:57], v[176:179], v[192:195], v[54:57]
	v_mfma_f32_16x16x32_bf16 v[46:49], v[184:187], v[192:195], v[46:49]
	v_mfma_f32_16x16x32_bf16 v[38:41], v[176:179], v[200:203], v[38:41]
	v_mfma_f32_16x16x32_bf16 v[30:33], v[184:187], v[200:203], v[30:33]
	v_mfma_f32_16x16x32_bf16 v[22:25], v[176:179], v[208:211], v[22:25]
	v_mfma_f32_16x16x32_bf16 v[14:17], v[184:187], v[208:211], v[14:17]
	s_barrier
	v_mfma_f32_16x16x32_bf16 v[6:9], v[176:179], v[216:219], v[6:9]
	v_mfma_f32_16x16x32_bf16 v[2:5], v[184:187], v[216:219], v[2:5]
	s_setprio 0
	s_add_i32 s10, 0, 0x18000
	v_add_u32_e32 v167, s10, v141
	s_add_i32 s11, 0, 0x1c000
	ds_read_b128 v[148:151], v167
	ds_read_b128 v[152:155], v167 offset:1024
	ds_read_b128 v[160:163], v167 offset:2048
	ds_read_b128 v[168:171], v167 offset:3072
	v_add_u32_e32 v167, s11, v141
	ds_read_b128 v[172:175], v167
	ds_read_b128 v[176:179], v167 offset:1024
	ds_read_b128 v[180:183], v167 offset:2048
	ds_read_b128 v[184:187], v167 offset:3072
	s_add_u32 s60, s60, 0x80000
	s_addc_u32 s61, s61, 0
	s_mov_b32 m0, s63
	v_lshl_add_u64 v[226:227], s[60:61], 0, v[130:131]
	ds_read_b128 v[188:191], v159 offset:32768
	ds_read_b128 v[192:195], v159 offset:33792
	ds_read_b128 v[196:199], v159 offset:34816
	ds_read_b128 v[200:203], v159 offset:35840
	ds_read_b128 v[204:207], v159 offset:36864
	ds_read_b128 v[208:211], v159 offset:37888
	ds_read_b128 v[212:215], v159 offset:38912
	ds_read_b128 v[216:219], v159 offset:39936
	global_load_lds_dwordx4 v[226:227], off
	v_lshl_add_u64 v[226:227], s[60:61], 0, v[134:135]
	s_mov_b32 m0, s64
	s_nop 0
	global_load_lds_dwordx4 v[226:227], off
	s_waitcnt vmcnt(8)
	s_waitcnt lgkmcnt(0)
	s_barrier
	s_waitcnt lgkmcnt(0)
	v_mfma_f32_16x16x32_bf16 v[126:129], v[148:151], v[188:191], v[126:129]
	v_mfma_f32_16x16x32_bf16 v[122:125], v[160:163], v[188:191], v[122:125]
	s_setprio 3
	v_mfma_f32_16x16x32_bf16 v[114:117], v[148:151], v[196:199], v[114:117]
	v_mfma_f32_16x16x32_bf16 v[106:109], v[160:163], v[196:199], v[106:109]
	v_mfma_f32_16x16x32_bf16 v[98:101], v[148:151], v[204:207], v[98:101]
	v_mfma_f32_16x16x32_bf16 v[90:93], v[160:163], v[204:207], v[90:93]
	v_mfma_f32_16x16x32_bf16 v[82:85], v[148:151], v[212:215], v[82:85]
	v_mfma_f32_16x16x32_bf16 v[74:77], v[160:163], v[212:215], v[74:77]
	v_mfma_f32_16x16x32_bf16 v[126:129], v[152:155], v[192:195], v[126:129]
	v_mfma_f32_16x16x32_bf16 v[122:125], v[168:171], v[192:195], v[122:125]
	v_mfma_f32_16x16x32_bf16 v[114:117], v[152:155], v[200:203], v[114:117]
	v_mfma_f32_16x16x32_bf16 v[106:109], v[168:171], v[200:203], v[106:109]
	v_mfma_f32_16x16x32_bf16 v[98:101], v[152:155], v[208:211], v[98:101]
	v_mfma_f32_16x16x32_bf16 v[90:93], v[168:171], v[208:211], v[90:93]
	v_mfma_f32_16x16x32_bf16 v[82:85], v[152:155], v[216:219], v[82:85]
	v_mfma_f32_16x16x32_bf16 v[74:77], v[168:171], v[216:219], v[74:77]
	s_setprio 0
	s_setprio 3
	v_mfma_f32_16x16x32_bf16 v[118:121], v[172:175], v[188:191], v[118:121]
	v_mfma_f32_16x16x32_bf16 v[110:113], v[180:183], v[188:191], v[110:113]
	v_mfma_f32_16x16x32_bf16 v[102:105], v[172:175], v[196:199], v[102:105]
	v_mfma_f32_16x16x32_bf16 v[94:97], v[180:183], v[196:199], v[94:97]
	v_mfma_f32_16x16x32_bf16 v[86:89], v[172:175], v[204:207], v[86:89]
	v_mfma_f32_16x16x32_bf16 v[78:81], v[180:183], v[204:207], v[78:81]
	v_mfma_f32_16x16x32_bf16 v[70:73], v[172:175], v[212:215], v[70:73]
	v_mfma_f32_16x16x32_bf16 v[66:69], v[180:183], v[212:215], v[66:69]
	v_mfma_f32_16x16x32_bf16 v[118:121], v[176:179], v[192:195], v[118:121]
	v_mfma_f32_16x16x32_bf16 v[110:113], v[184:187], v[192:195], v[110:113]
	v_mfma_f32_16x16x32_bf16 v[102:105], v[176:179], v[200:203], v[102:105]
	v_mfma_f32_16x16x32_bf16 v[94:97], v[184:187], v[200:203], v[94:97]
	v_mfma_f32_16x16x32_bf16 v[86:89], v[176:179], v[208:211], v[86:89]
	v_mfma_f32_16x16x32_bf16 v[78:81], v[184:187], v[208:211], v[78:81]
	s_barrier
; #define PG8_STAGE(bufoff, gbase, voff) do { _Pragma("unroll") for (int _i = 0; _i < 2; ++_i) \
;         __builtin_amdgcn_global_load_lds((const unsigned*)((const char*)(gbase) + (voff)[_i]), (PG8_LAS unsigned*)(lds + (bufoff) + ldsw + _i * 8192), 16, 0, 0); } while (0)
; #define PG8_LDA(dst, b, h) do { _Pragma("unroll") for (int m = 0; m < 4; ++m) _Pragma("unroll") for (int k = 0; k < 2; ++k) dst[m][k] = *(const PG8_LAS bf16x8*)(lds + PG8_SA(b, h) + aoff + m * 2048 + k * 1024); } while (0)
; #define PG8_MMA(ai, bj, At, Bt) do { __builtin_amdgcn_s_setprio(3); _Pragma("unroll") for (int m = 0; m < 4; ++m) _Pragma("unroll") for (int n = 0; n < 2; ++n) _Pragma("unroll") for (int k = 0; k < 2; ++k) \
;         acc[ai][bj][m][n] = __builtin_amdgcn_mfma_f32_16x16x32_bf16(Bt[n][k], At[m][k], acc[ai][bj][m][n], 0, 0, 0); __builtin_amdgcn_s_setprio(0); } while (0)
; #define PG8_WAIT_V(n) asm volatile("s_waitcnt vmcnt(" #n ")" ::: "memory")
; #define PG8_WAIT_L(n) asm volatile("s_waitcnt lgkmcnt(" #n ")" ::: "memory")
; #define PG8_BAR __builtin_amdgcn_s_barrier()
; #define PG8_SCHED __builtin_amdgcn_sched_barrier(0)
; template <class Epi, class Sched, bool ALIGN_EPI = false, bool SP2 = false>
; __device__ __forceinline__ void gemm_phase(PG8_LAS unsigned char* lds, const Gemm g, const Sched& S, const Epi& E) {
;     ...
;             PG8_LDA(At, 1, 1); PG8_STAGE(PG8_SB(1, 0), b3, voffB); PG8_STAGE(PG8_SB(1, 1), b3 + hstep, voffB); PG8_STAGE(PG8_SA(1, 0), a3, voffA);
;             PG8_WAIT_V(8); PG8_WAIT_L(0); PG8_BAR; PG8_MMA(1, 0, At, B0); PG8_MMA(1, 1, At, B1); PG8_BAR; PG8_SCHED;
;     ...
;         }
;         if constexpr (ALIGN_EPI) { if (wr == 0) PG8_BAR; }
	v_mfma_f32_16x16x32_bf16 v[70:73], v[176:179], v[216:219], v[70:73]
	v_mfma_f32_16x16x32_bf16 v[66:69], v[184:187], v[216:219], v[66:69]
	s_setprio 0
	s_add_i32 s10, s10, s42
	v_lshl_add_u64 v[164:165], v[164:165], 0, s[24:25]
	s_mov_b32 m0, s10
	ds_read_b128 v[188:191], v159 offset:49152
	ds_read_b128 v[192:195], v159 offset:50176
	ds_read_b128 v[196:199], v159 offset:51200
	ds_read_b128 v[200:203], v159 offset:52224
	ds_read_b128 v[204:207], v159 offset:53248
	ds_read_b128 v[208:211], v159 offset:54272
	ds_read_b128 v[212:215], v159 offset:55296
	ds_read_b128 v[216:219], v159 offset:56320
	global_load_lds_dwordx4 v[164:165], off
	s_add_i32 m0, s10, 0x2000
	s_add_u32 s58, s58, 0x80080
	v_lshl_add_u64 v[164:165], v[220:221], 0, s[24:25]
	s_addc_u32 s59, s59, 0
	s_add_i32 s10, s11, s42
	global_load_lds_dwordx4 v[164:165], off
	v_lshl_add_u64 v[164:165], s[58:59], 0, v[132:133]
	s_mov_b32 m0, s10
	s_nop 0
	global_load_lds_dwordx4 v[164:165], off
	v_lshl_add_u64 v[164:165], s[58:59], 0, v[136:137]
	s_add_i32 m0, s10, 0x2000
	s_nop 0
	global_load_lds_dwordx4 v[164:165], off
	v_lshl_add_u64 v[164:165], v[222:223], 0, s[24:25]
	s_mov_b32 m0, s69
	s_nop 0
	global_load_lds_dwordx4 v[164:165], off
	v_lshl_add_u64 v[164:165], v[224:225], 0, s[24:25]
	s_mov_b32 m0, s70
	s_nop 0
	global_load_lds_dwordx4 v[164:165], off
	s_waitcnt vmcnt(8)
	s_waitcnt lgkmcnt(0)
	s_barrier
	s_waitcnt lgkmcnt(0)
	v_mfma_f32_16x16x32_bf16 v[62:65], v[148:151], v[188:191], v[62:65]
	v_mfma_f32_16x16x32_bf16 v[58:61], v[160:163], v[188:191], v[58:61]
	s_setprio 3
	v_mfma_f32_16x16x32_bf16 v[50:53], v[148:151], v[196:199], v[50:53]
	v_mfma_f32_16x16x32_bf16 v[42:45], v[160:163], v[196:199], v[42:45]
	v_mfma_f32_16x16x32_bf16 v[34:37], v[148:151], v[204:207], v[34:37]
	v_mfma_f32_16x16x32_bf16 v[26:29], v[160:163], v[204:207], v[26:29]
	v_mfma_f32_16x16x32_bf16 v[18:21], v[148:151], v[212:215], v[18:21]
	v_mfma_f32_16x16x32_bf16 v[10:13], v[160:163], v[212:215], v[10:13]
	v_mfma_f32_16x16x32_bf16 v[62:65], v[152:155], v[192:195], v[62:65]
	v_mfma_f32_16x16x32_bf16 v[58:61], v[168:171], v[192:195], v[58:61]
	v_mfma_f32_16x16x32_bf16 v[50:53], v[152:155], v[200:203], v[50:53]
	v_mfma_f32_16x16x32_bf16 v[42:45], v[168:171], v[200:203], v[42:45]
	v_mfma_f32_16x16x32_bf16 v[34:37], v[152:155], v[208:211], v[34:37]
	v_mfma_f32_16x16x32_bf16 v[26:29], v[168:171], v[208:211], v[26:29]
	v_mfma_f32_16x16x32_bf16 v[18:21], v[152:155], v[216:219], v[18:21]
	v_mfma_f32_16x16x32_bf16 v[10:13], v[168:171], v[216:219], v[10:13]
	s_setprio 0
	s_setprio 3
	v_mfma_f32_16x16x32_bf16 v[54:57], v[172:175], v[188:191], v[54:57]
	v_mfma_f32_16x16x32_bf16 v[46:49], v[180:183], v[188:191], v[46:49]
	v_mfma_f32_16x16x32_bf16 v[38:41], v[172:175], v[196:199], v[38:41]
	v_mfma_f32_16x16x32_bf16 v[30:33], v[180:183], v[196:199], v[30:33]
	v_mfma_f32_16x16x32_bf16 v[22:25], v[172:175], v[204:207], v[22:25]
	v_mfma_f32_16x16x32_bf16 v[14:17], v[180:183], v[204:207], v[14:17]
	v_mfma_f32_16x16x32_bf16 v[6:9], v[172:175], v[212:215], v[6:9]
	v_mfma_f32_16x16x32_bf16 v[2:5], v[180:183], v[212:215], v[2:5]
	v_mfma_f32_16x16x32_bf16 v[54:57], v[176:179], v[192:195], v[54:57]
	v_mfma_f32_16x16x32_bf16 v[46:49], v[184:187], v[192:195], v[46:49]
	v_mfma_f32_16x16x32_bf16 v[38:41], v[176:179], v[200:203], v[38:41]
	v_mfma_f32_16x16x32_bf16 v[30:33], v[184:187], v[200:203], v[30:33]
	v_mfma_f32_16x16x32_bf16 v[22:25], v[176:179], v[208:211], v[22:25]
	v_mfma_f32_16x16x32_bf16 v[14:17], v[184:187], v[208:211], v[14:17]
	s_barrier
	v_mfma_f32_16x16x32_bf16 v[6:9], v[176:179], v[216:219], v[6:9]
	v_mfma_f32_16x16x32_bf16 v[2:5], v[184:187], v[216:219], v[2:5]
	s_setprio 0
	s_add_u32 s56, s56, 0x100
	s_addc_u32 s57, s57, 0
	s_add_u32 s47, s47, 0x100
	s_addc_u32 s51, s51, 0
	s_cmp_ge_u32 s79, s78
	s_mov_b32 s55, s79
	s_cbranch_scc0 .LBB0_1013
	s_and_b64 vcc, exec, s[26:27]
	s_cbranch_vccz .LBB0_1016
	s_barrier

; #define PG8_STAGE(bufoff, gbase, voff) do { _Pragma("unroll") for (int _i = 0; _i < 2; ++_i) \
;         __builtin_amdgcn_global_load_lds((const unsigned*)((const char*)(gbase) + (voff)[_i]), (PG8_LAS unsigned*)(lds + (bufoff) + ldsw + _i * 8192), 16, 0, 0); } while (0)
; #define PG8_LDA(dst, b, h) do { _Pragma("unroll") for (int m = 0; m < 4; ++m) _Pragma("unroll") for (int k = 0; k < 2; ++k) dst[m][k] = *(const PG8_LAS bf16x8*)(lds + PG8_SA(b, h) + aoff + m * 2048 + k * 1024); } while (0)
; #define PG8_LDB(dst, b, h) do { _Pragma("unroll") for (int n = 0; n < 2; ++n) _Pragma("unroll") for (int k = 0; k < 2; ++k) dst[n][k] = *(const PG8_LAS bf16x8*)(lds + PG8_SB(b, h) + boff + n * 2048 + k * 1024); } while (0)
; #define PG8_MMA(ai, bj, At, Bt) do { __builtin_amdgcn_s_setprio(3); _Pragma("unroll") for (int m = 0; m < 4; ++m) _Pragma("unroll") for (int n = 0; n < 2; ++n) _Pragma("unroll") for (int k = 0; k < 2; ++k) \
;         acc[ai][bj][m][n] = __builtin_amdgcn_mfma_f32_16x16x32_bf16(Bt[n][k], At[m][k], acc[ai][bj][m][n], 0, 0, 0); __builtin_amdgcn_s_setprio(0); } while (0)
; #define PG8_WAIT_V(n) asm volatile("s_waitcnt vmcnt(" #n ")" ::: "memory")
; #define PG8_BAR __builtin_amdgcn_s_barrier()
; template <class Epi, class Sched, bool ALIGN_EPI = false, bool SP2 = false>
; __device__ __forceinline__ void gemm_phase(PG8_LAS unsigned char* lds, const Gemm g, const Sched& S, const Epi& E) {
;     ...
;         for (int t = 0; t < nt; t += 2) {
;             const bool last = (t == nt - 2);
;             const char* a1 = cA + (size_t)(t + 1) * kstep;
;             const char* a2 = last ? nA : cA + (size_t)(t + 2) * kstep; const char* b2 = last ? nB : cB + (size_t)(t + 2) * kstep;
;             const char* a3 = a2 + kstep; const char* b3 = b2 + kstep;
;             if (last && has_next) S.a_ready(nxt);
;             if constexpr (SP2) {
;             PG8_LDB(B0, 0, 0); PG8_LDB(B1, 0, 1); PG8_SCHED; PG8_LDA(At, 0, 0); PG8_STAGE(PG8_SA(1, 1), a1 + hstep, voffA);
;             PG8_WAIT_V(8); PG8_WAIT_L(0); PG8_BAR; PG8_MMA(0, 0, At, B0); PG8_MMA(0, 1, At, B1); PG8_BAR; PG8_SCHED;
;             PG8_LDA(At, 0, 1); PG8_STAGE(PG8_SB(0, 0), b2, voffB); PG8_STAGE(PG8_SB(0, 1), b2 + hstep, voffB); PG8_STAGE(PG8_SA(0, 0), a2, voffA);
;             PG8_WAIT_V(8); PG8_WAIT_L(0); PG8_BAR; PG8_MMA(1, 0, At, B0); PG8_MMA(1, 1, At, B1); PG8_BAR; PG8_SCHED;
.LBB0_1218:
	ds_read_b128 v[148:151], v153
	ds_read_b128 v[156:159], v153 offset:1024
	ds_read_b128 v[160:163], v153 offset:2048
	ds_read_b128 v[168:171], v153 offset:3072
	ds_read_b128 v[172:175], v154
	ds_read_b128 v[176:179], v154 offset:1024
	ds_read_b128 v[180:183], v154 offset:2048
	ds_read_b128 v[184:187], v154 offset:3072
	s_add_u32 s10, s46, 0xfff80080
	s_addc_u32 s11, s47, -1
	s_cmp_eq_u32 s66, 28
	s_cselect_b32 s51, s27, s11
	s_cselect_b32 s50, s62, s10
	s_cselect_b32 s49, s25, s65
	s_cselect_b32 s48, s63, s64
	v_lshl_add_u64 v[164:165], s[46:47], 0, v[138:139]
	s_add_i32 m0, s42, 0xc000
	ds_read_b128 v[188:191], v155
	ds_read_b128 v[192:195], v155 offset:1024
	ds_read_b128 v[196:199], v155 offset:2048
	ds_read_b128 v[200:203], v155 offset:3072
	ds_read_b128 v[204:207], v155 offset:4096
	ds_read_b128 v[208:211], v155 offset:5120
	ds_read_b128 v[212:215], v155 offset:6144
	ds_read_b128 v[216:219], v155 offset:7168
	global_load_lds_dwordx4 v[164:165], off
	v_lshl_add_u64 v[164:165], s[46:47], 0, v[142:143]
	s_add_i32 m0, s42, 0xe000
	s_nop 0
	global_load_lds_dwordx4 v[164:165], off
	s_waitcnt vmcnt(8)
	s_waitcnt lgkmcnt(0)
	s_barrier
	s_waitcnt lgkmcnt(0)
	v_mfma_f32_16x16x32_bf16 v[126:129], v[148:151], v[188:191], v[126:129]
	v_mfma_f32_16x16x32_bf16 v[118:121], v[160:163], v[188:191], v[118:121]
	s_setprio 3
	v_mfma_f32_16x16x32_bf16 v[110:113], v[148:151], v[196:199], v[110:113]
	v_mfma_f32_16x16x32_bf16 v[102:105], v[160:163], v[196:199], v[102:105]
	v_mfma_f32_16x16x32_bf16 v[94:97], v[148:151], v[204:207], v[94:97]
	v_mfma_f32_16x16x32_bf16 v[86:89], v[160:163], v[204:207], v[86:89]
	v_mfma_f32_16x16x32_bf16 v[78:81], v[148:151], v[212:215], v[78:81]
	v_mfma_f32_16x16x32_bf16 v[70:73], v[160:163], v[212:215], v[70:73]
	v_mfma_f32_16x16x32_bf16 v[126:129], v[156:159], v[192:195], v[126:129]
	v_mfma_f32_16x16x32_bf16 v[118:121], v[168:171], v[192:195], v[118:121]
	v_mfma_f32_16x16x32_bf16 v[110:113], v[156:159], v[200:203], v[110:113]
	v_mfma_f32_16x16x32_bf16 v[102:105], v[168:171], v[200:203], v[102:105]
	v_mfma_f32_16x16x32_bf16 v[94:97], v[156:159], v[208:211], v[94:97]
	v_mfma_f32_16x16x32_bf16 v[86:89], v[168:171], v[208:211], v[86:89]
	v_mfma_f32_16x16x32_bf16 v[78:81], v[156:159], v[216:219], v[78:81]
	v_mfma_f32_16x16x32_bf16 v[70:73], v[168:171], v[216:219], v[70:73]
	s_setprio 0
	s_setprio 3
	v_mfma_f32_16x16x32_bf16 v[122:125], v[172:175], v[188:191], v[122:125]
	v_mfma_f32_16x16x32_bf16 v[114:117], v[180:183], v[188:191], v[114:117]
	v_mfma_f32_16x16x32_bf16 v[106:109], v[172:175], v[196:199], v[106:109]
	v_mfma_f32_16x16x32_bf16 v[98:101], v[180:183], v[196:199], v[98:101]
	v_mfma_f32_16x16x32_bf16 v[90:93], v[172:175], v[204:207], v[90:93]
	v_mfma_f32_16x16x32_bf16 v[82:85], v[180:183], v[204:207], v[82:85]
	v_mfma_f32_16x16x32_bf16 v[74:77], v[172:175], v[212:215], v[74:77]
	v_mfma_f32_16x16x32_bf16 v[66:69], v[180:183], v[212:215], v[66:69]
	v_mfma_f32_16x16x32_bf16 v[122:125], v[176:179], v[192:195], v[122:125]
	v_mfma_f32_16x16x32_bf16 v[114:117], v[184:187], v[192:195], v[114:117]
	v_mfma_f32_16x16x32_bf16 v[106:109], v[176:179], v[200:203], v[106:109]
	v_mfma_f32_16x16x32_bf16 v[98:101], v[184:187], v[200:203], v[98:101]
	v_mfma_f32_16x16x32_bf16 v[90:93], v[176:179], v[208:211], v[90:93]
	v_mfma_f32_16x16x32_bf16 v[82:85], v[184:187], v[208:211], v[82:85]
	s_barrier
	v_mfma_f32_16x16x32_bf16 v[74:77], v[176:179], v[216:219], v[74:77]
	v_mfma_f32_16x16x32_bf16 v[66:69], v[184:187], v[216:219], v[66:69]
	s_setprio 0
	s_add_i32 s10, s58, s35
	v_lshl_add_u64 v[164:165], s[48:49], 0, v[132:133]
	s_mov_b32 m0, s10
	ds_read_b128 v[188:191], v155 offset:16384
	ds_read_b128 v[192:195], v155 offset:17408
	ds_read_b128 v[196:199], v155 offset:18432
	ds_read_b128 v[200:203], v155 offset:19456
	ds_read_b128 v[204:207], v155 offset:20480
	ds_read_b128 v[208:211], v155 offset:21504
	ds_read_b128 v[212:215], v155 offset:22528
	ds_read_b128 v[216:219], v155 offset:23552
	global_load_lds_dwordx4 v[164:165], off
	s_add_i32 m0, s10, 0x2000
	s_add_u32 s68, s48, 0x80000
	v_lshl_add_u64 v[220:221], s[48:49], 0, v[136:137]
	s_addc_u32 s69, s49, 0
	s_add_i32 s10, s59, s35
	global_load_lds_dwordx4 v[220:221], off
	v_lshl_add_u64 v[222:223], s[68:69], 0, v[132:133]
	s_mov_b32 m0, s10
	v_lshl_add_u64 v[224:225], s[50:51], 0, v[134:135]
	global_load_lds_dwordx4 v[222:223], off
	v_lshl_add_u64 v[222:223], s[68:69], 0, v[136:137]
	s_add_i32 m0, s10, 0x2000
	s_nop 0
	global_load_lds_dwordx4 v[222:223], off
	v_lshl_add_u64 v[222:223], s[50:51], 0, v[130:131]
	s_mov_b32 m0, s42
	s_nop 0
	global_load_lds_dwordx4 v[222:223], off
	s_mov_b32 m0, s43
	s_nop 0
	global_load_lds_dwordx4 v[224:225], off
	s_waitcnt vmcnt(8)
	s_waitcnt lgkmcnt(0)
	s_barrier
; #define PG8_STAGE(bufoff, gbase, voff) do { _Pragma("unroll") for (int _i = 0; _i < 2; ++_i) \
;         __builtin_amdgcn_global_load_lds((const unsigned*)((const char*)(gbase) + (voff)[_i]), (PG8_LAS unsigned*)(lds + (bufoff) + ldsw + _i * 8192), 16, 0, 0); } while (0)
; #define PG8_LDA(dst, b, h) do { _Pragma("unroll") for (int m = 0; m < 4; ++m) _Pragma("unroll") for (int k = 0; k < 2; ++k) dst[m][k] = *(const PG8_LAS bf16x8*)(lds + PG8_SA(b, h) + aoff + m * 2048 + k * 1024); } while (0)
; #define PG8_LDB(dst, b, h) do { _Pragma("unroll") for (int n = 0; n < 2; ++n) _Pragma("unroll") for (int k = 0; k < 2; ++k) dst[n][k] = *(const PG8_LAS bf16x8*)(lds + PG8_SB(b, h) + boff + n * 2048 + k * 1024); } while (0)
; #define PG8_MMA(ai, bj, At, Bt) do { __builtin_amdgcn_s_setprio(3); _Pragma("unroll") for (int m = 0; m < 4; ++m) _Pragma("unroll") for (int n = 0; n < 2; ++n) _Pragma("unroll") for (int k = 0; k < 2; ++k) \
;         acc[ai][bj][m][n] = __builtin_amdgcn_mfma_f32_16x16x32_bf16(Bt[n][k], At[m][k], acc[ai][bj][m][n], 0, 0, 0); __builtin_amdgcn_s_setprio(0); } while (0)
; #define PG8_WAIT_V(n) asm volatile("s_waitcnt vmcnt(" #n ")" ::: "memory")
; #define PG8_WAIT_L(n) asm volatile("s_waitcnt lgkmcnt(" #n ")" ::: "memory")
; #define PG8_BAR __builtin_amdgcn_s_barrier()
; #define PG8_SCHED __builtin_amdgcn_sched_barrier(0)
; template <class Epi, class Sched, bool ALIGN_EPI = false, bool SP2 = false>
; __device__ __forceinline__ void gemm_phase(PG8_LAS unsigned char* lds, const Gemm g, const Sched& S, const Epi& E) {
;     ...
;             PG8_WAIT_V(8); PG8_WAIT_L(0); PG8_BAR; PG8_MMA(1, 0, At, B0); PG8_MMA(1, 1, At, B1); PG8_BAR; PG8_SCHED;
;             PG8_LDB(B0, 1, 0); PG8_LDB(B1, 1, 1); PG8_SCHED; PG8_LDA(At, 1, 0); PG8_STAGE(PG8_SA(0, 1), a2 + hstep, voffA);
;             PG8_WAIT_V(8); PG8_WAIT_L(0); PG8_BAR; PG8_MMA(0, 0, At, B0); PG8_MMA(0, 1, At, B1); PG8_BAR; PG8_SCHED;
	s_waitcnt lgkmcnt(0)
	v_mfma_f32_16x16x32_bf16 v[62:65], v[148:151], v[188:191], v[62:65]
	v_mfma_f32_16x16x32_bf16 v[54:57], v[160:163], v[188:191], v[54:57]
	s_setprio 3
	v_mfma_f32_16x16x32_bf16 v[46:49], v[148:151], v[196:199], v[46:49]
	v_mfma_f32_16x16x32_bf16 v[38:41], v[160:163], v[196:199], v[38:41]
	v_mfma_f32_16x16x32_bf16 v[30:33], v[148:151], v[204:207], v[30:33]
	v_mfma_f32_16x16x32_bf16 v[22:25], v[160:163], v[204:207], v[22:25]
	v_mfma_f32_16x16x32_bf16 v[14:17], v[148:151], v[212:215], v[14:17]
	v_mfma_f32_16x16x32_bf16 v[6:9], v[160:163], v[212:215], v[6:9]
	v_mfma_f32_16x16x32_bf16 v[62:65], v[156:159], v[192:195], v[62:65]
	v_mfma_f32_16x16x32_bf16 v[54:57], v[168:171], v[192:195], v[54:57]
	v_mfma_f32_16x16x32_bf16 v[46:49], v[156:159], v[200:203], v[46:49]
	v_mfma_f32_16x16x32_bf16 v[38:41], v[168:171], v[200:203], v[38:41]
	v_mfma_f32_16x16x32_bf16 v[30:33], v[156:159], v[208:211], v[30:33]
	v_mfma_f32_16x16x32_bf16 v[22:25], v[168:171], v[208:211], v[22:25]
	v_mfma_f32_16x16x32_bf16 v[14:17], v[156:159], v[216:219], v[14:17]
	v_mfma_f32_16x16x32_bf16 v[6:9], v[168:171], v[216:219], v[6:9]
	s_setprio 0
	s_setprio 3
	v_mfma_f32_16x16x32_bf16 v[58:61], v[172:175], v[188:191], v[58:61]
	v_mfma_f32_16x16x32_bf16 v[50:53], v[180:183], v[188:191], v[50:53]
	v_mfma_f32_16x16x32_bf16 v[42:45], v[172:175], v[196:199], v[42:45]
	v_mfma_f32_16x16x32_bf16 v[34:37], v[180:183], v[196:199], v[34:37]
	v_mfma_f32_16x16x32_bf16 v[26:29], v[172:175], v[204:207], v[26:29]
	v_mfma_f32_16x16x32_bf16 v[18:21], v[180:183], v[204:207], v[18:21]
	v_mfma_f32_16x16x32_bf16 v[10:13], v[172:175], v[212:215], v[10:13]
	v_mfma_f32_16x16x32_bf16 v[2:5], v[180:183], v[212:215], v[2:5]
	v_mfma_f32_16x16x32_bf16 v[58:61], v[176:179], v[192:195], v[58:61]
	v_mfma_f32_16x16x32_bf16 v[50:53], v[184:187], v[192:195], v[50:53]
	v_mfma_f32_16x16x32_bf16 v[42:45], v[176:179], v[200:203], v[42:45]
	v_mfma_f32_16x16x32_bf16 v[34:37], v[184:187], v[200:203], v[34:37]
	v_mfma_f32_16x16x32_bf16 v[26:29], v[176:179], v[208:211], v[26:29]
	v_mfma_f32_16x16x32_bf16 v[18:21], v[184:187], v[208:211], v[18:21]
	s_barrier
	v_mfma_f32_16x16x32_bf16 v[10:13], v[176:179], v[216:219], v[10:13]
	v_mfma_f32_16x16x32_bf16 v[2:5], v[184:187], v[216:219], v[2:5]
	s_setprio 0
	s_add_i32 s10, 0, 0x18000
	v_add_u32_e32 v167, s10, v141
	s_add_i32 s11, 0, 0x1c000
	ds_read_b128 v[148:151], v167
	ds_read_b128 v[156:159], v167 offset:1024
	ds_read_b128 v[160:163], v167 offset:2048
	ds_read_b128 v[168:171], v167 offset:3072
	v_add_u32_e32 v167, s11, v141
	ds_read_b128 v[172:175], v167
	ds_read_b128 v[176:179], v167 offset:1024
	ds_read_b128 v[180:183], v167 offset:2048
	ds_read_b128 v[184:187], v167 offset:3072
	s_add_u32 s50, s50, 0x80000
	s_addc_u32 s51, s51, 0
	s_mov_b32 m0, s45
	v_lshl_add_u64 v[226:227], s[50:51], 0, v[130:131]
	ds_read_b128 v[188:191], v155 offset:32768
	ds_read_b128 v[192:195], v155 offset:33792
	ds_read_b128 v[196:199], v155 offset:34816
	ds_read_b128 v[200:203], v155 offset:35840
	ds_read_b128 v[204:207], v155 offset:36864
	ds_read_b128 v[208:211], v155 offset:37888
	ds_read_b128 v[212:215], v155 offset:38912
	ds_read_b128 v[216:219], v155 offset:39936
	global_load_lds_dwordx4 v[226:227], off
	v_lshl_add_u64 v[226:227], s[50:51], 0, v[134:135]
	s_mov_b32 m0, s52
	s_nop 0
	global_load_lds_dwordx4 v[226:227], off
	s_waitcnt vmcnt(8)
	s_waitcnt lgkmcnt(0)
	s_barrier
	s_waitcnt lgkmcnt(0)
	v_mfma_f32_16x16x32_bf16 v[126:129], v[148:151], v[188:191], v[126:129]
	v_mfma_f32_16x16x32_bf16 v[118:121], v[160:163], v[188:191], v[118:121]
	s_setprio 3
	v_mfma_f32_16x16x32_bf16 v[110:113], v[148:151], v[196:199], v[110:113]
	v_mfma_f32_16x16x32_bf16 v[102:105], v[160:163], v[196:199], v[102:105]
	v_mfma_f32_16x16x32_bf16 v[94:97], v[148:151], v[204:207], v[94:97]
	v_mfma_f32_16x16x32_bf16 v[86:89], v[160:163], v[204:207], v[86:89]
	v_mfma_f32_16x16x32_bf16 v[78:81], v[148:151], v[212:215], v[78:81]
	v_mfma_f32_16x16x32_bf16 v[70:73], v[160:163], v[212:215], v[70:73]
	v_mfma_f32_16x16x32_bf16 v[126:129], v[156:159], v[192:195], v[126:129]
	v_mfma_f32_16x16x32_bf16 v[118:121], v[168:171], v[192:195], v[118:121]
	v_mfma_f32_16x16x32_bf16 v[110:113], v[156:159], v[200:203], v[110:113]
	v_mfma_f32_16x16x32_bf16 v[102:105], v[168:171], v[200:203], v[102:105]
	v_mfma_f32_16x16x32_bf16 v[94:97], v[156:159], v[208:211], v[94:97]
	v_mfma_f32_16x16x32_bf16 v[86:89], v[168:171], v[208:211], v[86:89]
	v_mfma_f32_16x16x32_bf16 v[78:81], v[156:159], v[216:219], v[78:81]
	v_mfma_f32_16x16x32_bf16 v[70:73], v[168:171], v[216:219], v[70:73]
	s_setprio 0
	s_setprio 3
	v_mfma_f32_16x16x32_bf16 v[122:125], v[172:175], v[188:191], v[122:125]
	v_mfma_f32_16x16x32_bf16 v[114:117], v[180:183], v[188:191], v[114:117]
	v_mfma_f32_16x16x32_bf16 v[106:109], v[172:175], v[196:199], v[106:109]
	v_mfma_f32_16x16x32_bf16 v[98:101], v[180:183], v[196:199], v[98:101]
	v_mfma_f32_16x16x32_bf16 v[90:93], v[172:175], v[204:207], v[90:93]
	v_mfma_f32_16x16x32_bf16 v[82:85], v[180:183], v[204:207], v[82:85]
	v_mfma_f32_16x16x32_bf16 v[74:77], v[172:175], v[212:215], v[74:77]
	v_mfma_f32_16x16x32_bf16 v[66:69], v[180:183], v[212:215], v[66:69]
	v_mfma_f32_16x16x32_bf16 v[122:125], v[176:179], v[192:195], v[122:125]
	v_mfma_f32_16x16x32_bf16 v[114:117], v[184:187], v[192:195], v[114:117]
	v_mfma_f32_16x16x32_bf16 v[106:109], v[176:179], v[200:203], v[106:109]
	v_mfma_f32_16x16x32_bf16 v[98:101], v[184:187], v[200:203], v[98:101]
	v_mfma_f32_16x16x32_bf16 v[90:93], v[176:179], v[208:211], v[90:93]
	v_mfma_f32_16x16x32_bf16 v[82:85], v[184:187], v[208:211], v[82:85]
	s_barrier
; #define PG8_STAGE(bufoff, gbase, voff) do { _Pragma("unroll") for (int _i = 0; _i < 2; ++_i) \
;         __builtin_amdgcn_global_load_lds((const unsigned*)((const char*)(gbase) + (voff)[_i]), (PG8_LAS unsigned*)(lds + (bufoff) + ldsw + _i * 8192), 16, 0, 0); } while (0)
; #define PG8_LDA(dst, b, h) do { _Pragma("unroll") for (int m = 0; m < 4; ++m) _Pragma("unroll") for (int k = 0; k < 2; ++k) dst[m][k] = *(const PG8_LAS bf16x8*)(lds + PG8_SA(b, h) + aoff + m * 2048 + k * 1024); } while (0)
; #define PG8_MMA(ai, bj, At, Bt) do { __builtin_amdgcn_s_setprio(3); _Pragma("unroll") for (int m = 0; m < 4; ++m) _Pragma("unroll") for (int n = 0; n < 2; ++n) _Pragma("unroll") for (int k = 0; k < 2; ++k) \
;         acc[ai][bj][m][n] = __builtin_amdgcn_mfma_f32_16x16x32_bf16(Bt[n][k], At[m][k], acc[ai][bj][m][n], 0, 0, 0); __builtin_amdgcn_s_setprio(0); } while (0)
; #define PG8_WAIT_V(n) asm volatile("s_waitcnt vmcnt(" #n ")" ::: "memory")
; #define PG8_WAIT_L(n) asm volatile("s_waitcnt lgkmcnt(" #n ")" ::: "memory")
; #define PG8_BAR __builtin_amdgcn_s_barrier()
; #define PG8_SCHED __builtin_amdgcn_sched_barrier(0)
; template <class Epi, class Sched, bool ALIGN_EPI = false, bool SP2 = false>
; __device__ __forceinline__ void gemm_phase(PG8_LAS unsigned char* lds, const Gemm g, const Sched& S, const Epi& E) {
;     ...
;             PG8_LDA(At, 1, 1); PG8_STAGE(PG8_SB(1, 0), b3, voffB); PG8_STAGE(PG8_SB(1, 1), b3 + hstep, voffB); PG8_STAGE(PG8_SA(1, 0), a3, voffA);
;             PG8_WAIT_V(8); PG8_WAIT_L(0); PG8_BAR; PG8_MMA(1, 0, At, B0); PG8_MMA(1, 1, At, B1); PG8_BAR; PG8_SCHED;
;     ...
;         }
;         if constexpr (ALIGN_EPI) { if (wr == 0) PG8_BAR; }
	v_mfma_f32_16x16x32_bf16 v[74:77], v[176:179], v[216:219], v[74:77]
	v_mfma_f32_16x16x32_bf16 v[66:69], v[184:187], v[216:219], v[66:69]
	s_setprio 0
	s_add_i32 s10, s10, s35
	v_lshl_add_u64 v[164:165], v[164:165], 0, s[16:17]
	s_mov_b32 m0, s10
	ds_read_b128 v[188:191], v155 offset:49152
	ds_read_b128 v[192:195], v155 offset:50176
	ds_read_b128 v[196:199], v155 offset:51200
	ds_read_b128 v[200:203], v155 offset:52224
	ds_read_b128 v[204:207], v155 offset:53248
	ds_read_b128 v[208:211], v155 offset:54272
	ds_read_b128 v[212:215], v155 offset:55296
	ds_read_b128 v[216:219], v155 offset:56320
	global_load_lds_dwordx4 v[164:165], off
	s_add_i32 m0, s10, 0x2000
	s_add_u32 s48, s48, 0x80080
	v_lshl_add_u64 v[164:165], v[220:221], 0, s[16:17]
	s_addc_u32 s49, s49, 0
	s_add_i32 s10, s11, s35
	global_load_lds_dwordx4 v[164:165], off
	v_lshl_add_u64 v[164:165], s[48:49], 0, v[132:133]
	s_mov_b32 m0, s10
	s_nop 0
	global_load_lds_dwordx4 v[164:165], off
	v_lshl_add_u64 v[164:165], s[48:49], 0, v[136:137]
	s_add_i32 m0, s10, 0x2000
	s_nop 0
	global_load_lds_dwordx4 v[164:165], off
	v_lshl_add_u64 v[164:165], v[222:223], 0, s[16:17]
	s_mov_b32 m0, s55
	s_nop 0
	global_load_lds_dwordx4 v[164:165], off
	v_lshl_add_u64 v[164:165], v[224:225], 0, s[16:17]
	s_mov_b32 m0, s56
	s_nop 0
	global_load_lds_dwordx4 v[164:165], off
	s_waitcnt vmcnt(8)
	s_waitcnt lgkmcnt(0)
	s_barrier
	s_waitcnt lgkmcnt(0)
	v_mfma_f32_16x16x32_bf16 v[62:65], v[148:151], v[188:191], v[62:65]
	v_mfma_f32_16x16x32_bf16 v[54:57], v[160:163], v[188:191], v[54:57]
	s_setprio 3
	v_mfma_f32_16x16x32_bf16 v[46:49], v[148:151], v[196:199], v[46:49]
	v_mfma_f32_16x16x32_bf16 v[38:41], v[160:163], v[196:199], v[38:41]
	v_mfma_f32_16x16x32_bf16 v[30:33], v[148:151], v[204:207], v[30:33]
	v_mfma_f32_16x16x32_bf16 v[22:25], v[160:163], v[204:207], v[22:25]
	v_mfma_f32_16x16x32_bf16 v[14:17], v[148:151], v[212:215], v[14:17]
	v_mfma_f32_16x16x32_bf16 v[6:9], v[160:163], v[212:215], v[6:9]
	v_mfma_f32_16x16x32_bf16 v[62:65], v[156:159], v[192:195], v[62:65]
	v_mfma_f32_16x16x32_bf16 v[54:57], v[168:171], v[192:195], v[54:57]
	v_mfma_f32_16x16x32_bf16 v[46:49], v[156:159], v[200:203], v[46:49]
	v_mfma_f32_16x16x32_bf16 v[38:41], v[168:171], v[200:203], v[38:41]
	v_mfma_f32_16x16x32_bf16 v[30:33], v[156:159], v[208:211], v[30:33]
	v_mfma_f32_16x16x32_bf16 v[22:25], v[168:171], v[208:211], v[22:25]
	v_mfma_f32_16x16x32_bf16 v[14:17], v[156:159], v[216:219], v[14:17]
	v_mfma_f32_16x16x32_bf16 v[6:9], v[168:171], v[216:219], v[6:9]
	s_setprio 0
	s_setprio 3
	v_mfma_f32_16x16x32_bf16 v[58:61], v[172:175], v[188:191], v[58:61]
	v_mfma_f32_16x16x32_bf16 v[50:53], v[180:183], v[188:191], v[50:53]
	v_mfma_f32_16x16x32_bf16 v[42:45], v[172:175], v[196:199], v[42:45]
	v_mfma_f32_16x16x32_bf16 v[34:37], v[180:183], v[196:199], v[34:37]
	v_mfma_f32_16x16x32_bf16 v[26:29], v[172:175], v[204:207], v[26:29]
	v_mfma_f32_16x16x32_bf16 v[18:21], v[180:183], v[204:207], v[18:21]
	v_mfma_f32_16x16x32_bf16 v[10:13], v[172:175], v[212:215], v[10:13]
	v_mfma_f32_16x16x32_bf16 v[2:5], v[180:183], v[212:215], v[2:5]
	v_mfma_f32_16x16x32_bf16 v[58:61], v[176:179], v[192:195], v[58:61]
	v_mfma_f32_16x16x32_bf16 v[50:53], v[184:187], v[192:195], v[50:53]
	v_mfma_f32_16x16x32_bf16 v[42:45], v[176:179], v[200:203], v[42:45]
	v_mfma_f32_16x16x32_bf16 v[34:37], v[184:187], v[200:203], v[34:37]
	v_mfma_f32_16x16x32_bf16 v[26:29], v[176:179], v[208:211], v[26:29]
	v_mfma_f32_16x16x32_bf16 v[18:21], v[184:187], v[208:211], v[18:21]
	s_barrier
	v_mfma_f32_16x16x32_bf16 v[10:13], v[176:179], v[216:219], v[10:13]
	v_mfma_f32_16x16x32_bf16 v[2:5], v[184:187], v[216:219], v[2:5]
	s_setprio 0
	s_add_i32 s66, s66, 2
	s_add_u32 s46, s46, 0x100
	s_addc_u32 s47, s47, 0
	s_add_u32 s64, s64, 0x100
	s_addc_u32 s65, s65, 0
	s_cmp_gt_u32 s66, 29
	s_cbranch_scc0 .LBB0_1218
	s_and_b64 vcc, exec, s[18:19]
	s_cbranch_vccz .LBB0_1221
	s_barrier

; #define PG8_STAGE(bufoff, gbase, voff) do { _Pragma("unroll") for (int _i = 0; _i < 2; ++_i) \
;         __builtin_amdgcn_global_load_lds((const unsigned*)((const char*)(gbase) + (voff)[_i]), (PG8_LAS unsigned*)(lds + (bufoff) + ldsw + _i * 8192), 16, 0, 0); } while (0)
; #define PG8_LDA(dst, b, h) do { _Pragma("unroll") for (int m = 0; m < 4; ++m) _Pragma("unroll") for (int k = 0; k < 2; ++k) dst[m][k] = *(const PG8_LAS bf16x8*)(lds + PG8_SA(b, h) + aoff + m * 2048 + k * 1024); } while (0)
; #define PG8_LDB(dst, b, h) do { _Pragma("unroll") for (int n = 0; n < 2; ++n) _Pragma("unroll") for (int k = 0; k < 2; ++k) dst[n][k] = *(const PG8_LAS bf16x8*)(lds + PG8_SB(b, h) + boff + n * 2048 + k * 1024); } while (0)
; #define PG8_MMA(ai, bj, At, Bt) do { __builtin_amdgcn_s_setprio(3); _Pragma("unroll") for (int m = 0; m < 4; ++m) _Pragma("unroll") for (int n = 0; n < 2; ++n) _Pragma("unroll") for (int k = 0; k < 2; ++k) \
;         acc[ai][bj][m][n] = __builtin_amdgcn_mfma_f32_16x16x32_bf16(Bt[n][k], At[m][k], acc[ai][bj][m][n], 0, 0, 0); __builtin_amdgcn_s_setprio(0); } while (0)
; #define PG8_WAIT_V(n) asm volatile("s_waitcnt vmcnt(" #n ")" ::: "memory")
; #define PG8_BAR __builtin_amdgcn_s_barrier()
; template <class Epi, class Sched, bool ALIGN_EPI = false, bool SP2 = false>
; __device__ __forceinline__ void gemm_phase(PG8_LAS unsigned char* lds, const Gemm g, const Sched& S, const Epi& E) {
;     ...
;         for (int t = 0; t < nt; t += 2) {
;             const bool last = (t == nt - 2);
;             const char* a1 = cA + (size_t)(t + 1) * kstep;
;             const char* a2 = last ? nA : cA + (size_t)(t + 2) * kstep; const char* b2 = last ? nB : cB + (size_t)(t + 2) * kstep;
;             const char* a3 = a2 + kstep; const char* b3 = b2 + kstep;
;             if (last && has_next) S.a_ready(nxt);
;             if constexpr (SP2) {
;             PG8_LDB(B0, 0, 0); PG8_LDB(B1, 0, 1); PG8_SCHED; PG8_LDA(At, 0, 0); PG8_STAGE(PG8_SA(1, 1), a1 + hstep, voffA);
;             PG8_WAIT_V(8); PG8_WAIT_L(0); PG8_BAR; PG8_MMA(0, 0, At, B0); PG8_MMA(0, 1, At, B1); PG8_BAR; PG8_SCHED;
;             PG8_LDA(At, 0, 1); PG8_STAGE(PG8_SB(0, 0), b2, voffB); PG8_STAGE(PG8_SB(0, 1), b2 + hstep, voffB); PG8_STAGE(PG8_SA(0, 0), a2, voffA);
;             PG8_WAIT_V(8); PG8_WAIT_L(0); PG8_BAR; PG8_MMA(1, 0, At, B0); PG8_MMA(1, 1, At, B1); PG8_BAR; PG8_SCHED;
.LBB0_1309:
	ds_read_b128 v[148:151], v157
	ds_read_b128 v[152:155], v157 offset:1024
	ds_read_b128 v[160:163], v157 offset:2048
	ds_read_b128 v[168:171], v157 offset:3072
	ds_read_b128 v[172:175], v158
	ds_read_b128 v[176:179], v158 offset:1024
	ds_read_b128 v[180:183], v158 offset:2048
	ds_read_b128 v[184:187], v158 offset:3072
	s_add_i32 s79, s50, 2
	s_add_u32 s10, s8, 0xffea8080
	s_addc_u32 s11, s9, -1
	s_cmp_eq_u32 s76, s50
	s_cselect_b32 s50, s48, s77
	s_cselect_b32 s53, s47, s11
	s_cselect_b32 s52, s46, s10
	s_cselect_b32 s51, s49, s78
	v_lshl_add_u64 v[164:165], s[8:9], 0, v[138:139]
	s_add_i32 m0, s43, 0xc000
	ds_read_b128 v[188:191], v159
	ds_read_b128 v[192:195], v159 offset:1024
	ds_read_b128 v[196:199], v159 offset:2048
	ds_read_b128 v[200:203], v159 offset:3072
	ds_read_b128 v[204:207], v159 offset:4096
	ds_read_b128 v[208:211], v159 offset:5120
	ds_read_b128 v[212:215], v159 offset:6144
	ds_read_b128 v[216:219], v159 offset:7168
	global_load_lds_dwordx4 v[164:165], off
	v_lshl_add_u64 v[164:165], s[8:9], 0, v[142:143]
	s_add_i32 m0, s43, 0xe000
	s_nop 0
	global_load_lds_dwordx4 v[164:165], off
	s_waitcnt vmcnt(8)
	s_waitcnt lgkmcnt(0)
	s_barrier
	s_waitcnt lgkmcnt(0)
	v_mfma_f32_16x16x32_bf16 v[126:129], v[148:151], v[188:191], v[126:129]
	v_mfma_f32_16x16x32_bf16 v[122:125], v[160:163], v[188:191], v[122:125]
	s_setprio 3
	v_mfma_f32_16x16x32_bf16 v[114:117], v[148:151], v[196:199], v[114:117]
	v_mfma_f32_16x16x32_bf16 v[106:109], v[160:163], v[196:199], v[106:109]
	v_mfma_f32_16x16x32_bf16 v[98:101], v[148:151], v[204:207], v[98:101]
	v_mfma_f32_16x16x32_bf16 v[90:93], v[160:163], v[204:207], v[90:93]
	v_mfma_f32_16x16x32_bf16 v[82:85], v[148:151], v[212:215], v[82:85]
	v_mfma_f32_16x16x32_bf16 v[74:77], v[160:163], v[212:215], v[74:77]
	v_mfma_f32_16x16x32_bf16 v[126:129], v[152:155], v[192:195], v[126:129]
	v_mfma_f32_16x16x32_bf16 v[122:125], v[168:171], v[192:195], v[122:125]
	v_mfma_f32_16x16x32_bf16 v[114:117], v[152:155], v[200:203], v[114:117]
	v_mfma_f32_16x16x32_bf16 v[106:109], v[168:171], v[200:203], v[106:109]
	v_mfma_f32_16x16x32_bf16 v[98:101], v[152:155], v[208:211], v[98:101]
	v_mfma_f32_16x16x32_bf16 v[90:93], v[168:171], v[208:211], v[90:93]
	v_mfma_f32_16x16x32_bf16 v[82:85], v[152:155], v[216:219], v[82:85]
	v_mfma_f32_16x16x32_bf16 v[74:77], v[168:171], v[216:219], v[74:77]
	s_setprio 0
	s_setprio 3
	v_mfma_f32_16x16x32_bf16 v[118:121], v[172:175], v[188:191], v[118:121]
	v_mfma_f32_16x16x32_bf16 v[110:113], v[180:183], v[188:191], v[110:113]
	v_mfma_f32_16x16x32_bf16 v[102:105], v[172:175], v[196:199], v[102:105]
	v_mfma_f32_16x16x32_bf16 v[94:97], v[180:183], v[196:199], v[94:97]
	v_mfma_f32_16x16x32_bf16 v[86:89], v[172:175], v[204:207], v[86:89]
	v_mfma_f32_16x16x32_bf16 v[78:81], v[180:183], v[204:207], v[78:81]
	v_mfma_f32_16x16x32_bf16 v[70:73], v[172:175], v[212:215], v[70:73]
	v_mfma_f32_16x16x32_bf16 v[66:69], v[180:183], v[212:215], v[66:69]
	v_mfma_f32_16x16x32_bf16 v[118:121], v[176:179], v[192:195], v[118:121]
	v_mfma_f32_16x16x32_bf16 v[110:113], v[184:187], v[192:195], v[110:113]
	v_mfma_f32_16x16x32_bf16 v[102:105], v[176:179], v[200:203], v[102:105]
	v_mfma_f32_16x16x32_bf16 v[94:97], v[184:187], v[200:203], v[94:97]
	v_mfma_f32_16x16x32_bf16 v[86:89], v[176:179], v[208:211], v[86:89]
	v_mfma_f32_16x16x32_bf16 v[78:81], v[184:187], v[208:211], v[78:81]
	s_barrier
	v_mfma_f32_16x16x32_bf16 v[70:73], v[176:179], v[216:219], v[70:73]
	v_mfma_f32_16x16x32_bf16 v[66:69], v[184:187], v[216:219], v[66:69]
	s_setprio 0
	s_add_i32 s10, s66, s42
	v_lshl_add_u64 v[164:165], s[50:51], 0, v[132:133]
	s_mov_b32 m0, s10
	ds_read_b128 v[188:191], v159 offset:16384
	ds_read_b128 v[192:195], v159 offset:17408
	ds_read_b128 v[196:199], v159 offset:18432
	ds_read_b128 v[200:203], v159 offset:19456
	ds_read_b128 v[204:207], v159 offset:20480
	ds_read_b128 v[208:211], v159 offset:21504
	ds_read_b128 v[212:215], v159 offset:22528
	ds_read_b128 v[216:219], v159 offset:23552
	global_load_lds_dwordx4 v[164:165], off
	s_add_i32 m0, s10, 0x2000
	s_add_u32 s82, s50, 0x158000
	v_lshl_add_u64 v[220:221], s[50:51], 0, v[136:137]
	s_addc_u32 s83, s51, 0
	s_add_i32 s10, s67, s42
	global_load_lds_dwordx4 v[220:221], off
	v_lshl_add_u64 v[222:223], s[82:83], 0, v[132:133]
	s_mov_b32 m0, s10
	v_lshl_add_u64 v[224:225], s[52:53], 0, v[134:135]
	global_load_lds_dwordx4 v[222:223], off
	v_lshl_add_u64 v[222:223], s[82:83], 0, v[136:137]
	s_add_i32 m0, s10, 0x2000
	s_nop 0
	global_load_lds_dwordx4 v[222:223], off
	v_lshl_add_u64 v[222:223], s[52:53], 0, v[130:131]
	s_mov_b32 m0, s43
	s_nop 0
	global_load_lds_dwordx4 v[222:223], off
	s_mov_b32 m0, s54
	s_nop 0
	global_load_lds_dwordx4 v[224:225], off
	s_waitcnt vmcnt(8)
	s_waitcnt lgkmcnt(0)
	s_barrier
; #define PG8_STAGE(bufoff, gbase, voff) do { _Pragma("unroll") for (int _i = 0; _i < 2; ++_i) \
;         __builtin_amdgcn_global_load_lds((const unsigned*)((const char*)(gbase) + (voff)[_i]), (PG8_LAS unsigned*)(lds + (bufoff) + ldsw + _i * 8192), 16, 0, 0); } while (0)
; #define PG8_LDA(dst, b, h) do { _Pragma("unroll") for (int m = 0; m < 4; ++m) _Pragma("unroll") for (int k = 0; k < 2; ++k) dst[m][k] = *(const PG8_LAS bf16x8*)(lds + PG8_SA(b, h) + aoff + m * 2048 + k * 1024); } while (0)
; #define PG8_LDB(dst, b, h) do { _Pragma("unroll") for (int n = 0; n < 2; ++n) _Pragma("unroll") for (int k = 0; k < 2; ++k) dst[n][k] = *(const PG8_LAS bf16x8*)(lds + PG8_SB(b, h) + boff + n * 2048 + k * 1024); } while (0)
; #define PG8_MMA(ai, bj, At, Bt) do { __builtin_amdgcn_s_setprio(3); _Pragma("unroll") for (int m = 0; m < 4; ++m) _Pragma("unroll") for (int n = 0; n < 2; ++n) _Pragma("unroll") for (int k = 0; k < 2; ++k) \
;         acc[ai][bj][m][n] = __builtin_amdgcn_mfma_f32_16x16x32_bf16(Bt[n][k], At[m][k], acc[ai][bj][m][n], 0, 0, 0); __builtin_amdgcn_s_setprio(0); } while (0)
; #define PG8_WAIT_V(n) asm volatile("s_waitcnt vmcnt(" #n ")" ::: "memory")
; #define PG8_WAIT_L(n) asm volatile("s_waitcnt lgkmcnt(" #n ")" ::: "memory")
; #define PG8_BAR __builtin_amdgcn_s_barrier()
; #define PG8_SCHED __builtin_amdgcn_sched_barrier(0)
; template <class Epi, class Sched, bool ALIGN_EPI = false, bool SP2 = false>
; __device__ __forceinline__ void gemm_phase(PG8_LAS unsigned char* lds, const Gemm g, const Sched& S, const Epi& E) {
;     ...
;             PG8_WAIT_V(8); PG8_WAIT_L(0); PG8_BAR; PG8_MMA(1, 0, At, B0); PG8_MMA(1, 1, At, B1); PG8_BAR; PG8_SCHED;
;             PG8_LDB(B0, 1, 0); PG8_LDB(B1, 1, 1); PG8_SCHED; PG8_LDA(At, 1, 0); PG8_STAGE(PG8_SA(0, 1), a2 + hstep, voffA);
;             PG8_WAIT_V(8); PG8_WAIT_L(0); PG8_BAR; PG8_MMA(0, 0, At, B0); PG8_MMA(0, 1, At, B1); PG8_BAR; PG8_SCHED;
	s_waitcnt lgkmcnt(0)
	v_mfma_f32_16x16x32_bf16 v[62:65], v[148:151], v[188:191], v[62:65]
	v_mfma_f32_16x16x32_bf16 v[58:61], v[160:163], v[188:191], v[58:61]
	s_setprio 3
	v_mfma_f32_16x16x32_bf16 v[50:53], v[148:151], v[196:199], v[50:53]
	v_mfma_f32_16x16x32_bf16 v[42:45], v[160:163], v[196:199], v[42:45]
	v_mfma_f32_16x16x32_bf16 v[34:37], v[148:151], v[204:207], v[34:37]
	v_mfma_f32_16x16x32_bf16 v[26:29], v[160:163], v[204:207], v[26:29]
	v_mfma_f32_16x16x32_bf16 v[18:21], v[148:151], v[212:215], v[18:21]
	v_mfma_f32_16x16x32_bf16 v[10:13], v[160:163], v[212:215], v[10:13]
	v_mfma_f32_16x16x32_bf16 v[62:65], v[152:155], v[192:195], v[62:65]
	v_mfma_f32_16x16x32_bf16 v[58:61], v[168:171], v[192:195], v[58:61]
	v_mfma_f32_16x16x32_bf16 v[50:53], v[152:155], v[200:203], v[50:53]
	v_mfma_f32_16x16x32_bf16 v[42:45], v[168:171], v[200:203], v[42:45]
	v_mfma_f32_16x16x32_bf16 v[34:37], v[152:155], v[208:211], v[34:37]
	v_mfma_f32_16x16x32_bf16 v[26:29], v[168:171], v[208:211], v[26:29]
	v_mfma_f32_16x16x32_bf16 v[18:21], v[152:155], v[216:219], v[18:21]
	v_mfma_f32_16x16x32_bf16 v[10:13], v[168:171], v[216:219], v[10:13]
	s_setprio 0
	s_setprio 3
	v_mfma_f32_16x16x32_bf16 v[54:57], v[172:175], v[188:191], v[54:57]
	v_mfma_f32_16x16x32_bf16 v[46:49], v[180:183], v[188:191], v[46:49]
	v_mfma_f32_16x16x32_bf16 v[38:41], v[172:175], v[196:199], v[38:41]
	v_mfma_f32_16x16x32_bf16 v[30:33], v[180:183], v[196:199], v[30:33]
	v_mfma_f32_16x16x32_bf16 v[22:25], v[172:175], v[204:207], v[22:25]
	v_mfma_f32_16x16x32_bf16 v[14:17], v[180:183], v[204:207], v[14:17]
	v_mfma_f32_16x16x32_bf16 v[6:9], v[172:175], v[212:215], v[6:9]
	v_mfma_f32_16x16x32_bf16 v[2:5], v[180:183], v[212:215], v[2:5]
	v_mfma_f32_16x16x32_bf16 v[54:57], v[176:179], v[192:195], v[54:57]
	v_mfma_f32_16x16x32_bf16 v[46:49], v[184:187], v[192:195], v[46:49]
	v_mfma_f32_16x16x32_bf16 v[38:41], v[176:179], v[200:203], v[38:41]
	v_mfma_f32_16x16x32_bf16 v[30:33], v[184:187], v[200:203], v[30:33]
	v_mfma_f32_16x16x32_bf16 v[22:25], v[176:179], v[208:211], v[22:25]
	v_mfma_f32_16x16x32_bf16 v[14:17], v[184:187], v[208:211], v[14:17]
	s_barrier
	v_mfma_f32_16x16x32_bf16 v[6:9], v[176:179], v[216:219], v[6:9]
	v_mfma_f32_16x16x32_bf16 v[2:5], v[184:187], v[216:219], v[2:5]
	s_setprio 0
	s_add_i32 s10, 0, 0x18000
	v_add_u32_e32 v167, s10, v141
	s_add_i32 s11, 0, 0x1c000
	ds_read_b128 v[148:151], v167
	ds_read_b128 v[152:155], v167 offset:1024
	ds_read_b128 v[160:163], v167 offset:2048
	ds_read_b128 v[168:171], v167 offset:3072
	v_add_u32_e32 v167, s11, v141
	ds_read_b128 v[172:175], v167
	ds_read_b128 v[176:179], v167 offset:1024
	ds_read_b128 v[180:183], v167 offset:2048
	ds_read_b128 v[184:187], v167 offset:3072
	s_add_u32 s52, s52, 0x158000
	s_addc_u32 s53, s53, 0
	s_mov_b32 m0, s55
	v_lshl_add_u64 v[226:227], s[52:53], 0, v[130:131]
	ds_read_b128 v[188:191], v159 offset:32768
	ds_read_b128 v[192:195], v159 offset:33792
	ds_read_b128 v[196:199], v159 offset:34816
	ds_read_b128 v[200:203], v159 offset:35840
	ds_read_b128 v[204:207], v159 offset:36864
	ds_read_b128 v[208:211], v159 offset:37888
	ds_read_b128 v[212:215], v159 offset:38912
	ds_read_b128 v[216:219], v159 offset:39936
	global_load_lds_dwordx4 v[226:227], off
	v_lshl_add_u64 v[226:227], s[52:53], 0, v[134:135]
	s_mov_b32 m0, s56
	s_nop 0
	global_load_lds_dwordx4 v[226:227], off
	s_waitcnt vmcnt(8)
	s_waitcnt lgkmcnt(0)
	s_barrier
	s_waitcnt lgkmcnt(0)
	v_mfma_f32_16x16x32_bf16 v[126:129], v[148:151], v[188:191], v[126:129]
	v_mfma_f32_16x16x32_bf16 v[122:125], v[160:163], v[188:191], v[122:125]
	s_setprio 3
	v_mfma_f32_16x16x32_bf16 v[114:117], v[148:151], v[196:199], v[114:117]
	v_mfma_f32_16x16x32_bf16 v[106:109], v[160:163], v[196:199], v[106:109]
	v_mfma_f32_16x16x32_bf16 v[98:101], v[148:151], v[204:207], v[98:101]
	v_mfma_f32_16x16x32_bf16 v[90:93], v[160:163], v[204:207], v[90:93]
	v_mfma_f32_16x16x32_bf16 v[82:85], v[148:151], v[212:215], v[82:85]
	v_mfma_f32_16x16x32_bf16 v[74:77], v[160:163], v[212:215], v[74:77]
	v_mfma_f32_16x16x32_bf16 v[126:129], v[152:155], v[192:195], v[126:129]
	v_mfma_f32_16x16x32_bf16 v[122:125], v[168:171], v[192:195], v[122:125]
	v_mfma_f32_16x16x32_bf16 v[114:117], v[152:155], v[200:203], v[114:117]
	v_mfma_f32_16x16x32_bf16 v[106:109], v[168:171], v[200:203], v[106:109]
	v_mfma_f32_16x16x32_bf16 v[98:101], v[152:155], v[208:211], v[98:101]
	v_mfma_f32_16x16x32_bf16 v[90:93], v[168:171], v[208:211], v[90:93]
	v_mfma_f32_16x16x32_bf16 v[82:85], v[152:155], v[216:219], v[82:85]
	v_mfma_f32_16x16x32_bf16 v[74:77], v[168:171], v[216:219], v[74:77]
	s_setprio 0
	s_setprio 3
	v_mfma_f32_16x16x32_bf16 v[118:121], v[172:175], v[188:191], v[118:121]
	v_mfma_f32_16x16x32_bf16 v[110:113], v[180:183], v[188:191], v[110:113]
	v_mfma_f32_16x16x32_bf16 v[102:105], v[172:175], v[196:199], v[102:105]
	v_mfma_f32_16x16x32_bf16 v[94:97], v[180:183], v[196:199], v[94:97]
	v_mfma_f32_16x16x32_bf16 v[86:89], v[172:175], v[204:207], v[86:89]
	v_mfma_f32_16x16x32_bf16 v[78:81], v[180:183], v[204:207], v[78:81]
	v_mfma_f32_16x16x32_bf16 v[70:73], v[172:175], v[212:215], v[70:73]
	v_mfma_f32_16x16x32_bf16 v[66:69], v[180:183], v[212:215], v[66:69]
	v_mfma_f32_16x16x32_bf16 v[118:121], v[176:179], v[192:195], v[118:121]
	v_mfma_f32_16x16x32_bf16 v[110:113], v[184:187], v[192:195], v[110:113]
	v_mfma_f32_16x16x32_bf16 v[102:105], v[176:179], v[200:203], v[102:105]
	v_mfma_f32_16x16x32_bf16 v[94:97], v[184:187], v[200:203], v[94:97]
	v_mfma_f32_16x16x32_bf16 v[86:89], v[176:179], v[208:211], v[86:89]
	v_mfma_f32_16x16x32_bf16 v[78:81], v[184:187], v[208:211], v[78:81]
	s_barrier
; #define PG8_STAGE(bufoff, gbase, voff) do { _Pragma("unroll") for (int _i = 0; _i < 2; ++_i) \
;         __builtin_amdgcn_global_load_lds((const unsigned*)((const char*)(gbase) + (voff)[_i]), (PG8_LAS unsigned*)(lds + (bufoff) + ldsw + _i * 8192), 16, 0, 0); } while (0)
; #define PG8_LDA(dst, b, h) do { _Pragma("unroll") for (int m = 0; m < 4; ++m) _Pragma("unroll") for (int k = 0; k < 2; ++k) dst[m][k] = *(const PG8_LAS bf16x8*)(lds + PG8_SA(b, h) + aoff + m * 2048 + k * 1024); } while (0)
; #define PG8_MMA(ai, bj, At, Bt) do { __builtin_amdgcn_s_setprio(3); _Pragma("unroll") for (int m = 0; m < 4; ++m) _Pragma("unroll") for (int n = 0; n < 2; ++n) _Pragma("unroll") for (int k = 0; k < 2; ++k) \
;         acc[ai][bj][m][n] = __builtin_amdgcn_mfma_f32_16x16x32_bf16(Bt[n][k], At[m][k], acc[ai][bj][m][n], 0, 0, 0); __builtin_amdgcn_s_setprio(0); } while (0)
; #define PG8_WAIT_V(n) asm volatile("s_waitcnt vmcnt(" #n ")" ::: "memory")
; #define PG8_WAIT_L(n) asm volatile("s_waitcnt lgkmcnt(" #n ")" ::: "memory")
; #define PG8_BAR __builtin_amdgcn_s_barrier()
; #define PG8_SCHED __builtin_amdgcn_sched_barrier(0)
; template <class Epi, class Sched, bool ALIGN_EPI = false, bool SP2 = false>
; __device__ __forceinline__ void gemm_phase(PG8_LAS unsigned char* lds, const Gemm g, const Sched& S, const Epi& E) {
;     ...
;             PG8_LDA(At, 1, 1); PG8_STAGE(PG8_SB(1, 0), b3, voffB); PG8_STAGE(PG8_SB(1, 1), b3 + hstep, voffB); PG8_STAGE(PG8_SA(1, 0), a3, voffA);
;             PG8_WAIT_V(8); PG8_WAIT_L(0); PG8_BAR; PG8_MMA(1, 0, At, B0); PG8_MMA(1, 1, At, B1); PG8_BAR; PG8_SCHED;
;     ...
;         }
;         if constexpr (ALIGN_EPI) { if (wr == 0) PG8_BAR; }
	v_mfma_f32_16x16x32_bf16 v[70:73], v[176:179], v[216:219], v[70:73]
	v_mfma_f32_16x16x32_bf16 v[66:69], v[184:187], v[216:219], v[66:69]
	s_setprio 0
	s_add_i32 s10, s10, s42
	v_lshl_add_u64 v[164:165], v[164:165], 0, s[18:19]
	s_mov_b32 m0, s10
	ds_read_b128 v[188:191], v159 offset:49152
	ds_read_b128 v[192:195], v159 offset:50176
	ds_read_b128 v[196:199], v159 offset:51200
	ds_read_b128 v[200:203], v159 offset:52224
	ds_read_b128 v[204:207], v159 offset:53248
	ds_read_b128 v[208:211], v159 offset:54272
	ds_read_b128 v[212:215], v159 offset:55296
	ds_read_b128 v[216:219], v159 offset:56320
	global_load_lds_dwordx4 v[164:165], off
	s_add_i32 m0, s10, 0x2000
	s_add_u32 s50, s50, 0x158080
	v_lshl_add_u64 v[164:165], v[220:221], 0, s[18:19]
	s_addc_u32 s51, s51, 0
	s_add_i32 s10, s11, s42
	global_load_lds_dwordx4 v[164:165], off
	v_lshl_add_u64 v[164:165], s[50:51], 0, v[132:133]
	s_mov_b32 m0, s10
	s_nop 0
	global_load_lds_dwordx4 v[164:165], off
	v_lshl_add_u64 v[164:165], s[50:51], 0, v[136:137]
	s_add_i32 m0, s10, 0x2000
	s_nop 0
	global_load_lds_dwordx4 v[164:165], off
	v_lshl_add_u64 v[164:165], v[222:223], 0, s[18:19]
	s_mov_b32 m0, s61
	s_nop 0
	global_load_lds_dwordx4 v[164:165], off
	v_lshl_add_u64 v[164:165], v[224:225], 0, s[18:19]
	s_mov_b32 m0, s62
	s_nop 0
	global_load_lds_dwordx4 v[164:165], off
	s_waitcnt vmcnt(8)
	s_waitcnt lgkmcnt(0)
	s_barrier
	s_waitcnt lgkmcnt(0)
	v_mfma_f32_16x16x32_bf16 v[62:65], v[148:151], v[188:191], v[62:65]
	v_mfma_f32_16x16x32_bf16 v[58:61], v[160:163], v[188:191], v[58:61]
	s_setprio 3
	v_mfma_f32_16x16x32_bf16 v[50:53], v[148:151], v[196:199], v[50:53]
	v_mfma_f32_16x16x32_bf16 v[42:45], v[160:163], v[196:199], v[42:45]
	v_mfma_f32_16x16x32_bf16 v[34:37], v[148:151], v[204:207], v[34:37]
	v_mfma_f32_16x16x32_bf16 v[26:29], v[160:163], v[204:207], v[26:29]
	v_mfma_f32_16x16x32_bf16 v[18:21], v[148:151], v[212:215], v[18:21]
	v_mfma_f32_16x16x32_bf16 v[10:13], v[160:163], v[212:215], v[10:13]
	v_mfma_f32_16x16x32_bf16 v[62:65], v[152:155], v[192:195], v[62:65]
	v_mfma_f32_16x16x32_bf16 v[58:61], v[168:171], v[192:195], v[58:61]
	v_mfma_f32_16x16x32_bf16 v[50:53], v[152:155], v[200:203], v[50:53]
	v_mfma_f32_16x16x32_bf16 v[42:45], v[168:171], v[200:203], v[42:45]
	v_mfma_f32_16x16x32_bf16 v[34:37], v[152:155], v[208:211], v[34:37]
	v_mfma_f32_16x16x32_bf16 v[26:29], v[168:171], v[208:211], v[26:29]
	v_mfma_f32_16x16x32_bf16 v[18:21], v[152:155], v[216:219], v[18:21]
	v_mfma_f32_16x16x32_bf16 v[10:13], v[168:171], v[216:219], v[10:13]
	s_setprio 0
	s_setprio 3
	v_mfma_f32_16x16x32_bf16 v[54:57], v[172:175], v[188:191], v[54:57]
	v_mfma_f32_16x16x32_bf16 v[46:49], v[180:183], v[188:191], v[46:49]
	v_mfma_f32_16x16x32_bf16 v[38:41], v[172:175], v[196:199], v[38:41]
	v_mfma_f32_16x16x32_bf16 v[30:33], v[180:183], v[196:199], v[30:33]
	v_mfma_f32_16x16x32_bf16 v[22:25], v[172:175], v[204:207], v[22:25]
	v_mfma_f32_16x16x32_bf16 v[14:17], v[180:183], v[204:207], v[14:17]
	v_mfma_f32_16x16x32_bf16 v[6:9], v[172:175], v[212:215], v[6:9]
	v_mfma_f32_16x16x32_bf16 v[2:5], v[180:183], v[212:215], v[2:5]
	v_mfma_f32_16x16x32_bf16 v[54:57], v[176:179], v[192:195], v[54:57]
	v_mfma_f32_16x16x32_bf16 v[46:49], v[184:187], v[192:195], v[46:49]
	v_mfma_f32_16x16x32_bf16 v[38:41], v[176:179], v[200:203], v[38:41]
	v_mfma_f32_16x16x32_bf16 v[30:33], v[184:187], v[200:203], v[30:33]
	v_mfma_f32_16x16x32_bf16 v[22:25], v[176:179], v[208:211], v[22:25]
	v_mfma_f32_16x16x32_bf16 v[14:17], v[184:187], v[208:211], v[14:17]
	s_barrier
	v_mfma_f32_16x16x32_bf16 v[6:9], v[176:179], v[216:219], v[6:9]
	v_mfma_f32_16x16x32_bf16 v[2:5], v[184:187], v[216:219], v[2:5]
	s_setprio 0
	s_add_u32 s8, s8, 0x100
	s_addc_u32 s9, s9, 0
	s_add_u32 s77, s77, 0x100
	s_addc_u32 s78, s78, 0
	s_cmp_ge_u32 s79, s75
	s_mov_b32 s50, s79
	s_cbranch_scc0 .LBB0_1309
	s_and_b64 vcc, exec, s[24:25]
	s_cbranch_vccz .LBB0_1312
	s_barrier
